# speedup vs baseline: 1.0198x; 1.0017x over previous
; #define WAIT_V(n) asm volatile("s_waitcnt vmcnt(%0)" ::"n"(n) : "memory")
; #define WAIT_L(n) asm volatile("s_waitcnt lgkmcnt(%0)" ::"n"(n) : "memory")
; #define SBAR() __builtin_amdgcn_sched_barrier(0)
; #define STAGE(P, base, kt) do { _Pragma("unroll") for (int _i = 0; _i < 2; ++_i)                                        \
;       __builtin_amdgcn_global_load_lds((const unsigned*)((base) + (size_t)(sOff[_i] + (unsigned)(kt) * (BK * 2))),        \
;                                        (unsigned*)((P) + wid * 1024 + _i * 8192), 16, 0, 0); } while (0)
; #define LDA(dst, b, h) _Pragma("unroll") for (int m = 0; m < 4; ++m) _Pragma("unroll") for (int k = 0; k < 2; ++k) \
;       dst[m][k] = *(const bf16x8*)(SA(b, h) + aoff + (m * 2048 + k * 1024))
; #define LDB(dst, b, h) _Pragma("unroll") for (int n = 0; n < 2; ++n) _Pragma("unroll") for (int k = 0; k < 2; ++k) \
;       dst[n][k] = *(const bf16x8*)(SB(b, h) + boff + (n * 256 + k * 1024))
; #define BAR __builtin_amdgcn_s_barrier()
; template <int EPI, int N, int K>
; __device__ __forceinline__ void phase_gemm(const Params& p, const u16* __restrict__ A, const u16* __restrict__ Bt, int nM, char* shm,
;                            u16* __restrict__ outp, float* __restrict__ rowss) {
;     ...
;     for (int t = 0; t < nt - 2; t += 2) {
;       LDB(B0, 0, 0); SBAR(); LDA(At, 0, 0); STAGE(SA(1, 1), A1, t + 1);
;       WAIT_L(8); BAR; WAIT_L(0); MMA(0, 0, At, B0); BAR; SBAR();
;       LDB(B1, 0, 1); STAGE(SB(0, 0), B0p, t + 2);
;       BAR; WAIT_L(0); MMA(0, 1, At, B1); BAR;
;       LDA(At, 0, 1); STAGE(SA(0, 0), A0, t + 2);
;       BAR; WAIT_L(0); MMA(1, 0, At, B0); BAR; SBAR();
;       STAGE(SB(0, 1), B1p, t + 2);
;       WAIT_V(6); BAR; MMA(1, 1, At, B1); BAR;
.LBB0_94:
	v_or_b32_e32 v143, 0x10000, v146
	v_add_u32_e32 v145, 0x10100, v146
	v_add_u32_e32 v144, 0x10400, v146
	ds_read_b128 v[156:159], v143
	ds_read_b128 v[160:163], v144
	v_add_u32_e32 v151, 0x10500, v146
	ds_read_b128 v[164:167], v145
	ds_read_b128 v[168:171], v151
	v_add_u32_e32 v240, v148, v96
	s_mov_b32 m0, s56
	v_add_u32_e32 v152, 0x80, v240
	v_add_u32_e32 v241, v148, v142
	ds_read_b128 v[172:175], v147
	ds_read_b128 v[176:179], v147 offset:1024
	ds_read_b128 v[180:183], v147 offset:2048
	ds_read_b128 v[196:199], v147 offset:3072
	ds_read_b128 v[200:203], v147 offset:4096
	ds_read_b128 v[204:207], v147 offset:5120
	ds_read_b128 v[208:211], v147 offset:6144
	ds_read_b128 v[212:215], v147 offset:7168
	global_load_lds_dwordx4 v152, s[6:7]
	v_add_u32_e32 v152, 0x80, v241
	s_mov_b32 m0, s57
	s_nop 0
	global_load_lds_dwordx4 v152, s[6:7]
	v_or_b32_e32 v152, 0x14000, v146
	v_add_u32_e32 v154, 0x14100, v146
	v_add_u32_e32 v153, 0x14400, v146
	ds_read_b128 v[216:219], v152
	ds_read_b128 v[220:223], v153
	v_add_u32_e32 v155, 0x14500, v146
	ds_read_b128 v[224:227], v154
	ds_read_b128 v[228:231], v155
	s_waitcnt vmcnt(8)
	s_waitcnt lgkmcnt(0)
	s_barrier
	v_mfma_f32_16x16x32_bf16 v[126:129], v[156:159], v[172:175], v[126:129]
	v_mfma_f32_16x16x32_bf16 v[122:125], v[164:167], v[172:175], v[122:125]
	v_mfma_f32_16x16x32_bf16 v[118:121], v[156:159], v[180:183], v[118:121]
	v_mfma_f32_16x16x32_bf16 v[114:117], v[164:167], v[180:183], v[114:117]
	v_mfma_f32_16x16x32_bf16 v[110:113], v[156:159], v[200:203], v[110:113]
	v_mfma_f32_16x16x32_bf16 v[106:109], v[164:167], v[200:203], v[106:109]
	v_mfma_f32_16x16x32_bf16 v[102:105], v[156:159], v[208:211], v[102:105]
	v_mfma_f32_16x16x32_bf16 v[98:101], v[164:167], v[208:211], v[98:101]
	v_mfma_f32_16x16x32_bf16 v[126:129], v[160:163], v[176:179], v[126:129]
	v_mfma_f32_16x16x32_bf16 v[122:125], v[168:171], v[176:179], v[122:125]
	v_mfma_f32_16x16x32_bf16 v[118:121], v[160:163], v[196:199], v[118:121]
	v_mfma_f32_16x16x32_bf16 v[114:117], v[168:171], v[196:199], v[114:117]
	v_mfma_f32_16x16x32_bf16 v[110:113], v[160:163], v[204:207], v[110:113]
	v_mfma_f32_16x16x32_bf16 v[106:109], v[168:171], v[204:207], v[106:109]
	v_mfma_f32_16x16x32_bf16 v[102:105], v[160:163], v[212:215], v[102:105]
	v_mfma_f32_16x16x32_bf16 v[98:101], v[168:171], v[212:215], v[98:101]
	v_mfma_f32_16x16x32_bf16 v[92:95], v[216:219], v[172:175], v[92:95]
	v_mfma_f32_16x16x32_bf16 v[88:91], v[224:227], v[172:175], v[88:91]
	v_mfma_f32_16x16x32_bf16 v[84:87], v[216:219], v[180:183], v[84:87]
	v_mfma_f32_16x16x32_bf16 v[80:83], v[224:227], v[180:183], v[80:83]
	v_mfma_f32_16x16x32_bf16 v[76:79], v[216:219], v[200:203], v[76:79]
	v_mfma_f32_16x16x32_bf16 v[72:75], v[224:227], v[200:203], v[72:75]
	v_mfma_f32_16x16x32_bf16 v[68:71], v[216:219], v[208:211], v[68:71]
	v_mfma_f32_16x16x32_bf16 v[64:67], v[224:227], v[208:211], v[64:67]
	v_mfma_f32_16x16x32_bf16 v[92:95], v[220:223], v[176:179], v[92:95]
	v_mfma_f32_16x16x32_bf16 v[88:91], v[228:231], v[176:179], v[88:91]
	v_mfma_f32_16x16x32_bf16 v[84:87], v[220:223], v[196:199], v[84:87]
	v_mfma_f32_16x16x32_bf16 v[80:83], v[228:231], v[196:199], v[80:83]
	v_mfma_f32_16x16x32_bf16 v[76:79], v[220:223], v[204:207], v[76:79]
	v_mfma_f32_16x16x32_bf16 v[72:75], v[228:231], v[204:207], v[72:75]
	v_mfma_f32_16x16x32_bf16 v[68:71], v[220:223], v[212:215], v[68:71]
	v_mfma_f32_16x16x32_bf16 v[64:67], v[228:231], v[212:215], v[64:67]
	s_barrier
	ds_read_b128 v[172:175], v147 offset:16384
	ds_read_b128 v[176:179], v147 offset:17408
	ds_read_b128 v[180:183], v147 offset:18432
	ds_read_b128 v[196:199], v147 offset:19456
	ds_read_b128 v[200:203], v147 offset:20480
	ds_read_b128 v[204:207], v147 offset:21504
	ds_read_b128 v[208:211], v147 offset:22528
	ds_read_b128 v[212:215], v147 offset:23552
	s_mov_b32 m0, s26
	v_add_u32_e32 v232, 0x100, v240
	global_load_lds_dwordx4 v232, s[12:13]
	v_add_u32_e32 v233, 0x100, v241
	s_mov_b32 m0, s27
	s_nop 0
	global_load_lds_dwordx4 v233, s[12:13]
	s_mov_b32 m0, s5
	s_nop 0
	global_load_lds_dwordx4 v232, s[14:15]
	s_mov_b32 m0, s24
	s_nop 0
	global_load_lds_dwordx4 v233, s[14:15]
	s_mov_b32 m0, s28
	s_nop 0
	global_load_lds_dwordx4 v232, s[22:23]
	s_mov_b32 m0, s29
	s_nop 0
	global_load_lds_dwordx4 v233, s[22:23]
	s_waitcnt vmcnt(8)
	s_waitcnt lgkmcnt(0)
	s_barrier
	v_mfma_f32_16x16x32_bf16 v[60:63], v[156:159], v[172:175], v[60:63]
	v_mfma_f32_16x16x32_bf16 v[56:59], v[164:167], v[172:175], v[56:59]
	v_mfma_f32_16x16x32_bf16 v[52:55], v[156:159], v[180:183], v[52:55]
	v_mfma_f32_16x16x32_bf16 v[48:51], v[164:167], v[180:183], v[48:51]
	v_mfma_f32_16x16x32_bf16 v[44:47], v[156:159], v[200:203], v[44:47]
	v_mfma_f32_16x16x32_bf16 v[40:43], v[164:167], v[200:203], v[40:43]
	v_mfma_f32_16x16x32_bf16 v[36:39], v[156:159], v[208:211], v[36:39]
	v_mfma_f32_16x16x32_bf16 v[32:35], v[164:167], v[208:211], v[32:35]
	v_mfma_f32_16x16x32_bf16 v[60:63], v[160:163], v[176:179], v[60:63]
	v_mfma_f32_16x16x32_bf16 v[56:59], v[168:171], v[176:179], v[56:59]
	v_mfma_f32_16x16x32_bf16 v[52:55], v[160:163], v[196:199], v[52:55]
	v_mfma_f32_16x16x32_bf16 v[48:51], v[168:171], v[196:199], v[48:51]
	v_mfma_f32_16x16x32_bf16 v[44:47], v[160:163], v[204:207], v[44:47]
	v_mfma_f32_16x16x32_bf16 v[40:43], v[168:171], v[204:207], v[40:43]
	v_mfma_f32_16x16x32_bf16 v[36:39], v[160:163], v[212:215], v[36:39]
	v_mfma_f32_16x16x32_bf16 v[32:35], v[168:171], v[212:215], v[32:35]
	v_mfma_f32_16x16x32_bf16 v[28:31], v[216:219], v[172:175], v[28:31]
	v_mfma_f32_16x16x32_bf16 v[24:27], v[224:227], v[172:175], v[24:27]
	v_mfma_f32_16x16x32_bf16 v[20:23], v[216:219], v[180:183], v[20:23]
	v_mfma_f32_16x16x32_bf16 v[16:19], v[224:227], v[180:183], v[16:19]
	v_mfma_f32_16x16x32_bf16 v[12:15], v[216:219], v[200:203], v[12:15]
	v_mfma_f32_16x16x32_bf16 v[8:11], v[224:227], v[200:203], v[8:11]
	v_mfma_f32_16x16x32_bf16 v[4:7], v[216:219], v[208:211], v[4:7]
	v_mfma_f32_16x16x32_bf16 v[0:3], v[224:227], v[208:211], v[0:3]
	v_mfma_f32_16x16x32_bf16 v[28:31], v[220:223], v[176:179], v[28:31]
	v_mfma_f32_16x16x32_bf16 v[24:27], v[228:231], v[176:179], v[24:27]
	v_mfma_f32_16x16x32_bf16 v[20:23], v[220:223], v[196:199], v[20:23]
	v_mfma_f32_16x16x32_bf16 v[16:19], v[228:231], v[196:199], v[16:19]
	v_mfma_f32_16x16x32_bf16 v[12:15], v[220:223], v[204:207], v[12:15]
	v_mfma_f32_16x16x32_bf16 v[8:11], v[228:231], v[204:207], v[8:11]
	v_mfma_f32_16x16x32_bf16 v[4:7], v[220:223], v[212:215], v[4:7]
	v_mfma_f32_16x16x32_bf16 v[0:3], v[228:231], v[212:215], v[0:3]
	v_or_b32_e32 v156, 0x18000, v146
	v_add_u32_e32 v158, 0x18100, v146
	s_barrier
; #define WAIT_V(n) asm volatile("s_waitcnt vmcnt(%0)" ::"n"(n) : "memory")
; #define WAIT_L(n) asm volatile("s_waitcnt lgkmcnt(%0)" ::"n"(n) : "memory")
; #define SBAR() __builtin_amdgcn_sched_barrier(0)
; #define STAGE(P, base, kt) do { _Pragma("unroll") for (int _i = 0; _i < 2; ++_i)                                        \
;       __builtin_amdgcn_global_load_lds((const unsigned*)((base) + (size_t)(sOff[_i] + (unsigned)(kt) * (BK * 2))),        \
;                                        (unsigned*)((P) + wid * 1024 + _i * 8192), 16, 0, 0); } while (0)
; #define LDA(dst, b, h) _Pragma("unroll") for (int m = 0; m < 4; ++m) _Pragma("unroll") for (int k = 0; k < 2; ++k) \
;       dst[m][k] = *(const bf16x8*)(SA(b, h) + aoff + (m * 2048 + k * 1024))
; #define LDB(dst, b, h) _Pragma("unroll") for (int n = 0; n < 2; ++n) _Pragma("unroll") for (int k = 0; k < 2; ++k) \
;       dst[n][k] = *(const bf16x8*)(SB(b, h) + boff + (n * 256 + k * 1024))
; #define BAR __builtin_amdgcn_s_barrier()
; template <int EPI, int N, int K>
; __device__ __forceinline__ void phase_gemm(const Params& p, const u16* __restrict__ A, const u16* __restrict__ Bt, int nM, char* shm,
;                            u16* __restrict__ outp, float* __restrict__ rowss) {
;     ...
;       LDB(B0, 1, 0); SBAR(); LDA(At, 1, 0); STAGE(SA(0, 1), A1, t + 2);
;       WAIT_L(8); BAR; WAIT_L(0); MMA(0, 0, At, B0); BAR; SBAR();
;       LDB(B1, 1, 1); STAGE(SB(1, 0), B0p, t + 3);
;       BAR; WAIT_L(0); MMA(0, 1, At, B1); BAR;
;       LDA(At, 1, 1); STAGE(SA(1, 0), A0, t + 3);
;       BAR; WAIT_L(0); MMA(1, 0, At, B0); BAR; SBAR();
;       STAGE(SB(1, 1), B1p, t + 3);
;       WAIT_V(6); BAR; MMA(1, 1, At, B1); BAR;
;     }
	v_add_u32_e32 v157, 0x18400, v146
	ds_read_b128 v[164:167], v156
	ds_read_b128 v[168:171], v157
	v_add_u32_e32 v159, 0x18500, v146
	ds_read_b128 v[172:175], v158
	ds_read_b128 v[176:179], v159
	s_mov_b32 m0, s30
	ds_read_b128 v[180:183], v147 offset:32768
	ds_read_b128 v[196:199], v147 offset:33792
	ds_read_b128 v[200:203], v147 offset:34816
	ds_read_b128 v[204:207], v147 offset:35840
	ds_read_b128 v[208:211], v147 offset:36864
	ds_read_b128 v[212:215], v147 offset:37888
	ds_read_b128 v[216:219], v147 offset:38912
	ds_read_b128 v[220:223], v147 offset:39936
	global_load_lds_dwordx4 v232, s[6:7]
	s_mov_b32 m0, s31
	s_nop 0
	global_load_lds_dwordx4 v233, s[6:7]
	v_or_b32_e32 v160, 0x1c000, v146
	v_add_u32_e32 v162, 0x1c100, v146
	v_add_u32_e32 v161, 0x1c400, v146
	ds_read_b128 v[224:227], v160
	ds_read_b128 v[228:231], v161
	v_add_u32_e32 v163, 0x1c500, v146
	ds_read_b128 v[232:235], v162
	ds_read_b128 v[236:239], v163
	s_waitcnt vmcnt(8)
	s_waitcnt lgkmcnt(0)
	s_barrier
	v_mfma_f32_16x16x32_bf16 v[126:129], v[164:167], v[180:183], v[126:129]
	v_mfma_f32_16x16x32_bf16 v[122:125], v[172:175], v[180:183], v[122:125]
	v_mfma_f32_16x16x32_bf16 v[118:121], v[164:167], v[200:203], v[118:121]
	v_mfma_f32_16x16x32_bf16 v[114:117], v[172:175], v[200:203], v[114:117]
	v_mfma_f32_16x16x32_bf16 v[110:113], v[164:167], v[208:211], v[110:113]
	v_mfma_f32_16x16x32_bf16 v[106:109], v[172:175], v[208:211], v[106:109]
	v_mfma_f32_16x16x32_bf16 v[102:105], v[164:167], v[216:219], v[102:105]
	v_mfma_f32_16x16x32_bf16 v[98:101], v[172:175], v[216:219], v[98:101]
	v_mfma_f32_16x16x32_bf16 v[126:129], v[168:171], v[196:199], v[126:129]
	v_mfma_f32_16x16x32_bf16 v[122:125], v[176:179], v[196:199], v[122:125]
	v_mfma_f32_16x16x32_bf16 v[118:121], v[168:171], v[204:207], v[118:121]
	v_mfma_f32_16x16x32_bf16 v[114:117], v[176:179], v[204:207], v[114:117]
	v_mfma_f32_16x16x32_bf16 v[110:113], v[168:171], v[212:215], v[110:113]
	v_mfma_f32_16x16x32_bf16 v[106:109], v[176:179], v[212:215], v[106:109]
	v_mfma_f32_16x16x32_bf16 v[102:105], v[168:171], v[220:223], v[102:105]
	v_mfma_f32_16x16x32_bf16 v[98:101], v[176:179], v[220:223], v[98:101]
	v_mfma_f32_16x16x32_bf16 v[92:95], v[224:227], v[180:183], v[92:95]
	v_mfma_f32_16x16x32_bf16 v[88:91], v[232:235], v[180:183], v[88:91]
	v_mfma_f32_16x16x32_bf16 v[84:87], v[224:227], v[200:203], v[84:87]
	v_mfma_f32_16x16x32_bf16 v[80:83], v[232:235], v[200:203], v[80:83]
	v_mfma_f32_16x16x32_bf16 v[76:79], v[224:227], v[208:211], v[76:79]
	v_mfma_f32_16x16x32_bf16 v[72:75], v[232:235], v[208:211], v[72:75]
	v_mfma_f32_16x16x32_bf16 v[68:71], v[224:227], v[216:219], v[68:71]
	v_mfma_f32_16x16x32_bf16 v[64:67], v[232:235], v[216:219], v[64:67]
	v_mfma_f32_16x16x32_bf16 v[92:95], v[228:231], v[196:199], v[92:95]
	v_mfma_f32_16x16x32_bf16 v[88:91], v[236:239], v[196:199], v[88:91]
	v_mfma_f32_16x16x32_bf16 v[84:87], v[228:231], v[204:207], v[84:87]
	v_mfma_f32_16x16x32_bf16 v[80:83], v[236:239], v[204:207], v[80:83]
	v_mfma_f32_16x16x32_bf16 v[76:79], v[228:231], v[212:215], v[76:79]
	v_mfma_f32_16x16x32_bf16 v[72:75], v[236:239], v[212:215], v[72:75]
	v_mfma_f32_16x16x32_bf16 v[68:71], v[228:231], v[220:223], v[68:71]
	v_mfma_f32_16x16x32_bf16 v[64:67], v[236:239], v[220:223], v[64:67]
	s_barrier
	ds_read_b128 v[180:183], v147 offset:49152
	ds_read_b128 v[196:199], v147 offset:50176
	ds_read_b128 v[200:203], v147 offset:51200
	ds_read_b128 v[204:207], v147 offset:52224
	ds_read_b128 v[208:211], v147 offset:53248
	ds_read_b128 v[212:215], v147 offset:54272
	ds_read_b128 v[216:219], v147 offset:55296
	ds_read_b128 v[220:223], v147 offset:56320
	s_mov_b32 m0, s33
	v_add_u32_e32 v240, 0x180, v240
	global_load_lds_dwordx4 v240, s[12:13]
	v_add_u32_e32 v241, 0x180, v241
	s_mov_b32 m0, s35
	s_nop 0
	global_load_lds_dwordx4 v241, s[12:13]
	s_mov_b32 m0, s93
	s_nop 0
	global_load_lds_dwordx4 v240, s[14:15]
	s_mov_b32 m0, s96
	s_nop 0
	global_load_lds_dwordx4 v241, s[14:15]
	s_mov_b32 m0, s52
	s_nop 0
	global_load_lds_dwordx4 v240, s[22:23]
	s_mov_b32 m0, s53
	s_nop 0
	global_load_lds_dwordx4 v241, s[22:23]
	s_waitcnt vmcnt(8)
	s_waitcnt lgkmcnt(0)
	s_barrier
	v_mfma_f32_16x16x32_bf16 v[60:63], v[164:167], v[180:183], v[60:63]
	v_mfma_f32_16x16x32_bf16 v[56:59], v[172:175], v[180:183], v[56:59]
	v_mfma_f32_16x16x32_bf16 v[52:55], v[164:167], v[200:203], v[52:55]
	v_mfma_f32_16x16x32_bf16 v[48:51], v[172:175], v[200:203], v[48:51]
	v_mfma_f32_16x16x32_bf16 v[44:47], v[164:167], v[208:211], v[44:47]
	v_mfma_f32_16x16x32_bf16 v[40:43], v[172:175], v[208:211], v[40:43]
	v_mfma_f32_16x16x32_bf16 v[36:39], v[164:167], v[216:219], v[36:39]
	v_mfma_f32_16x16x32_bf16 v[32:35], v[172:175], v[216:219], v[32:35]
	v_mfma_f32_16x16x32_bf16 v[60:63], v[168:171], v[196:199], v[60:63]
	v_mfma_f32_16x16x32_bf16 v[56:59], v[176:179], v[196:199], v[56:59]
	v_mfma_f32_16x16x32_bf16 v[52:55], v[168:171], v[204:207], v[52:55]
	v_mfma_f32_16x16x32_bf16 v[48:51], v[176:179], v[204:207], v[48:51]
	v_mfma_f32_16x16x32_bf16 v[44:47], v[168:171], v[212:215], v[44:47]
	v_mfma_f32_16x16x32_bf16 v[40:43], v[176:179], v[212:215], v[40:43]
	v_mfma_f32_16x16x32_bf16 v[36:39], v[168:171], v[220:223], v[36:39]
	v_mfma_f32_16x16x32_bf16 v[32:35], v[176:179], v[220:223], v[32:35]
	v_mfma_f32_16x16x32_bf16 v[28:31], v[224:227], v[180:183], v[28:31]
	v_mfma_f32_16x16x32_bf16 v[24:27], v[232:235], v[180:183], v[24:27]
	v_mfma_f32_16x16x32_bf16 v[20:23], v[224:227], v[200:203], v[20:23]
	v_mfma_f32_16x16x32_bf16 v[16:19], v[232:235], v[200:203], v[16:19]
	v_mfma_f32_16x16x32_bf16 v[12:15], v[224:227], v[208:211], v[12:15]
	v_mfma_f32_16x16x32_bf16 v[8:11], v[232:235], v[208:211], v[8:11]
	v_mfma_f32_16x16x32_bf16 v[4:7], v[224:227], v[216:219], v[4:7]
	v_mfma_f32_16x16x32_bf16 v[0:3], v[232:235], v[216:219], v[0:3]
	v_mfma_f32_16x16x32_bf16 v[28:31], v[228:231], v[196:199], v[28:31]
	v_mfma_f32_16x16x32_bf16 v[24:27], v[236:239], v[196:199], v[24:27]
	v_mfma_f32_16x16x32_bf16 v[20:23], v[228:231], v[204:207], v[20:23]
	v_mfma_f32_16x16x32_bf16 v[16:19], v[236:239], v[204:207], v[16:19]
	v_mfma_f32_16x16x32_bf16 v[12:15], v[228:231], v[212:215], v[12:15]
	v_mfma_f32_16x16x32_bf16 v[8:11], v[236:239], v[212:215], v[8:11]
	v_mfma_f32_16x16x32_bf16 v[4:7], v[228:231], v[220:223], v[4:7]
	v_mfma_f32_16x16x32_bf16 v[0:3], v[236:239], v[220:223], v[0:3]
	s_add_i32 s61, s61, 2
	v_add_u32_e32 v142, 0x100, v142
	s_cmp_lt_u32 s61, 40
	v_add_u32_e32 v96, 0x100, v96
	s_barrier
; #define WAIT_V(n) asm volatile("s_waitcnt vmcnt(%0)" ::"n"(n) : "memory")
; #define WAIT_L(n) asm volatile("s_waitcnt lgkmcnt(%0)" ::"n"(n) : "memory")
; #define STAGE(P, base, kt) do { _Pragma("unroll") for (int _i = 0; _i < 2; ++_i)                                        \
;       __builtin_amdgcn_global_load_lds((const unsigned*)((base) + (size_t)(sOff[_i] + (unsigned)(kt) * (BK * 2))),        \
;                                        (unsigned*)((P) + wid * 1024 + _i * 8192), 16, 0, 0); } while (0)
; #define LDA(dst, b, h) _Pragma("unroll") for (int m = 0; m < 4; ++m) _Pragma("unroll") for (int k = 0; k < 2; ++k) \
;       dst[m][k] = *(const bf16x8*)(SA(b, h) + aoff + (m * 2048 + k * 1024))
; #define LDB(dst, b, h) _Pragma("unroll") for (int n = 0; n < 2; ++n) _Pragma("unroll") for (int k = 0; k < 2; ++k) \
;       dst[n][k] = *(const bf16x8*)(SB(b, h) + boff + (n * 256 + k * 1024))
; #define BAR __builtin_amdgcn_s_barrier()
; template <int EPI, int N, int K>
; __device__ __forceinline__ void phase_gemm(const Params& p, const u16* __restrict__ A, const u16* __restrict__ Bt, int nM, char* shm,
;                            u16* __restrict__ outp, float* __restrict__ rowss) {
;     ...
;     { LDB(B0, 0, 0); LDA(At, 0, 0); STAGE(SA(1, 1), A1, nt - 1);
;       BAR; WAIT_L(0); MMA(0, 0, At, B0); BAR;
;       LDB(B1, 0, 1); BAR; WAIT_L(0); MMA(0, 1, At, B1); BAR;
;       LDA(At, 0, 1); WAIT_V(4); BAR; WAIT_L(0); MMA(1, 0, At, B0); MMA(1, 1, At, B1); BAR; }
	s_cbranch_scc1 .LBB0_94
	s_waitcnt vmcnt(6)
	s_mov_b32 m0, s56
	v_lshl_add_u64 v[220:221], s[6:7], 0, v[138:139]
	ds_read_b128 v[164:167], v143
	ds_read_b128 v[168:171], v144
	ds_read_b128 v[142:145], v145
	ds_read_b128 v[172:175], v151
	ds_read_b128 v[176:179], v147
	ds_read_b128 v[180:183], v147 offset:1024
	ds_read_b128 v[196:199], v147 offset:2048
	ds_read_b128 v[200:203], v147 offset:3072
	ds_read_b128 v[204:207], v147 offset:4096
	ds_read_b128 v[208:211], v147 offset:5120
	ds_read_b128 v[212:215], v147 offset:6144
	ds_read_b128 v[216:219], v147 offset:7168
	global_load_lds_dwordx4 v[220:221], off
	v_lshl_add_u64 v[220:221], s[6:7], 0, v[140:141]
	s_mov_b32 m0, s57
	s_nop 0
	global_load_lds_dwordx4 v[220:221], off
	s_barrier
	s_waitcnt lgkmcnt(0)
	s_waitcnt lgkmcnt(0)
	v_mfma_f32_16x16x32_bf16 v[126:129], v[164:167], v[176:179], v[126:129]
	v_mfma_f32_16x16x32_bf16 v[122:125], v[142:145], v[176:179], v[122:125]
	v_mfma_f32_16x16x32_bf16 v[118:121], v[164:167], v[196:199], v[118:121]
	v_mfma_f32_16x16x32_bf16 v[102:105], v[164:167], v[212:215], v[102:105]
	v_mfma_f32_16x16x32_bf16 v[98:101], v[142:145], v[212:215], v[98:101]
	v_mfma_f32_16x16x32_bf16 v[126:129], v[168:171], v[180:183], v[126:129]
	v_mfma_f32_16x16x32_bf16 v[122:125], v[172:175], v[180:183], v[122:125]
	v_mfma_f32_16x16x32_bf16 v[118:121], v[168:171], v[200:203], v[118:121]
	v_mfma_f32_16x16x32_bf16 v[114:117], v[142:145], v[196:199], v[114:117]
	v_mfma_f32_16x16x32_bf16 v[110:113], v[164:167], v[204:207], v[110:113]
	v_mfma_f32_16x16x32_bf16 v[106:109], v[142:145], v[204:207], v[106:109]
	v_mfma_f32_16x16x32_bf16 v[102:105], v[168:171], v[216:219], v[102:105]
	v_mfma_f32_16x16x32_bf16 v[98:101], v[172:175], v[216:219], v[98:101]
	v_mfma_f32_16x16x32_bf16 v[220:223], v[172:175], v[200:203], v[114:117]
	v_mfma_f32_16x16x32_bf16 v[224:227], v[168:171], v[208:211], v[110:113]
	v_mfma_f32_16x16x32_bf16 v[228:231], v[172:175], v[208:211], v[106:109]
	s_barrier
	s_nop 0
	ds_read_b128 v[106:109], v152
	ds_read_b128 v[110:113], v153
	ds_read_b128 v[114:117], v154
	ds_read_b128 v[152:155], v155
	s_barrier
	s_waitcnt lgkmcnt(0)
	s_waitcnt lgkmcnt(0)
	v_mfma_f32_16x16x32_bf16 v[84:87], v[106:109], v[196:199], v[84:87]
	v_mfma_f32_16x16x32_bf16 v[80:83], v[114:117], v[196:199], v[80:83]
	v_mfma_f32_16x16x32_bf16 v[68:71], v[106:109], v[212:215], v[68:71]
	v_mfma_f32_16x16x32_bf16 v[92:95], v[106:109], v[176:179], v[92:95]
	v_mfma_f32_16x16x32_bf16 v[88:91], v[114:117], v[176:179], v[88:91]
	v_mfma_f32_16x16x32_bf16 v[84:87], v[110:113], v[200:203], v[84:87]
	v_mfma_f32_16x16x32_bf16 v[80:83], v[152:155], v[200:203], v[80:83]
	v_mfma_f32_16x16x32_bf16 v[76:79], v[106:109], v[204:207], v[76:79]
	v_mfma_f32_16x16x32_bf16 v[72:75], v[114:117], v[204:207], v[72:75]
	v_mfma_f32_16x16x32_bf16 v[68:71], v[110:113], v[216:219], v[68:71]
	v_mfma_f32_16x16x32_bf16 v[64:67], v[114:117], v[212:215], v[64:67]
	v_mfma_f32_16x16x32_bf16 v[232:235], v[110:113], v[180:183], v[92:95]
	v_mfma_f32_16x16x32_bf16 v[176:179], v[152:155], v[180:183], v[88:91]
	v_mfma_f32_16x16x32_bf16 v[180:183], v[110:113], v[208:211], v[76:79]
	v_mfma_f32_16x16x32_bf16 v[196:199], v[152:155], v[208:211], v[72:75]
	v_mfma_f32_16x16x32_bf16 v[200:203], v[152:155], v[216:219], v[64:67]
	s_barrier
	s_nop 0
	ds_read_b128 v[64:67], v147 offset:16384
	ds_read_b128 v[72:75], v147 offset:17408
	ds_read_b128 v[76:79], v147 offset:18432
	ds_read_b128 v[88:91], v147 offset:19456
	ds_read_b128 v[92:95], v147 offset:20480
	ds_read_b128 v[204:207], v147 offset:21504
	ds_read_b128 v[208:211], v147 offset:22528
	ds_read_b128 v[212:215], v147 offset:23552
	s_waitcnt vmcnt(4)
	s_barrier
	s_waitcnt lgkmcnt(0)
	s_waitcnt lgkmcnt(0)
	v_mfma_f32_16x16x32_bf16 v[60:63], v[164:167], v[64:67], v[60:63]
	v_mfma_f32_16x16x32_bf16 v[52:55], v[164:167], v[76:79], v[52:55]
	v_mfma_f32_16x16x32_bf16 v[48:51], v[142:145], v[76:79], v[48:51]
	v_mfma_f32_16x16x32_bf16 v[36:39], v[164:167], v[208:211], v[36:39]
	v_mfma_f32_16x16x32_bf16 v[32:35], v[142:145], v[208:211], v[32:35]
	v_mfma_f32_16x16x32_bf16 v[60:63], v[168:171], v[72:75], v[60:63]
	v_mfma_f32_16x16x32_bf16 v[56:59], v[142:145], v[64:67], v[56:59]
	v_mfma_f32_16x16x32_bf16 v[52:55], v[168:171], v[88:91], v[52:55]
	v_mfma_f32_16x16x32_bf16 v[48:51], v[172:175], v[88:91], v[48:51]
	v_mfma_f32_16x16x32_bf16 v[44:47], v[164:167], v[92:95], v[44:47]
	v_mfma_f32_16x16x32_bf16 v[40:43], v[142:145], v[92:95], v[40:43]
	v_mfma_f32_16x16x32_bf16 v[36:39], v[168:171], v[212:215], v[36:39]
	v_mfma_f32_16x16x32_bf16 v[32:35], v[172:175], v[212:215], v[32:35]
	v_mfma_f32_16x16x32_bf16 v[216:219], v[172:175], v[72:75], v[56:59]
	v_mfma_f32_16x16x32_bf16 v[236:239], v[168:171], v[204:207], v[44:47]
	v_mfma_f32_16x16x32_bf16 v[240:243], v[172:175], v[204:207], v[40:43]
	v_mfma_f32_16x16x32_bf16 v[20:23], v[106:109], v[76:79], v[20:23]
	v_mfma_f32_16x16x32_bf16 v[16:19], v[114:117], v[76:79], v[16:19]
	v_mfma_f32_16x16x32_bf16 v[4:7], v[106:109], v[208:211], v[4:7]
	v_mfma_f32_16x16x32_bf16 v[28:31], v[106:109], v[64:67], v[28:31]
	v_mfma_f32_16x16x32_bf16 v[24:27], v[114:117], v[64:67], v[24:27]
	v_mfma_f32_16x16x32_bf16 v[20:23], v[110:113], v[88:91], v[20:23]
	v_mfma_f32_16x16x32_bf16 v[16:19], v[152:155], v[88:91], v[16:19]
	v_mfma_f32_16x16x32_bf16 v[12:15], v[106:109], v[92:95], v[12:15]
	v_mfma_f32_16x16x32_bf16 v[8:11], v[114:117], v[92:95], v[8:11]
	v_mfma_f32_16x16x32_bf16 v[4:7], v[110:113], v[212:215], v[4:7]
	v_mfma_f32_16x16x32_bf16 v[0:3], v[114:117], v[208:211], v[0:3]
	v_mfma_f32_16x16x32_bf16 v[142:145], v[110:113], v[72:75], v[28:31]
	v_mfma_f32_16x16x32_bf16 v[164:167], v[152:155], v[72:75], v[24:27]
	v_mfma_f32_16x16x32_bf16 v[168:171], v[110:113], v[204:207], v[12:15]
	v_mfma_f32_16x16x32_bf16 v[172:175], v[152:155], v[204:207], v[8:11]
	v_mfma_f32_16x16x32_bf16 v[152:155], v[152:155], v[212:215], v[0:3]
	s_barrier
; #define WAIT_V(n) asm volatile("s_waitcnt vmcnt(%0)" ::"n"(n) : "memory")
; #define WAIT_L(n) asm volatile("s_waitcnt lgkmcnt(%0)" ::"n"(n) : "memory")
; #define LDA(dst, b, h) _Pragma("unroll") for (int m = 0; m < 4; ++m) _Pragma("unroll") for (int k = 0; k < 2; ++k) \
;       dst[m][k] = *(const bf16x8*)(SA(b, h) + aoff + (m * 2048 + k * 1024))
; #define LDB(dst, b, h) _Pragma("unroll") for (int n = 0; n < 2; ++n) _Pragma("unroll") for (int k = 0; k < 2; ++k) \
;       dst[n][k] = *(const bf16x8*)(SB(b, h) + boff + (n * 256 + k * 1024))
; #define BAR __builtin_amdgcn_s_barrier()
; template <int EPI, int N, int K>
; __device__ __forceinline__ void phase_gemm(const Params& p, const u16* __restrict__ A, const u16* __restrict__ Bt, int nM, char* shm,
;                            u16* __restrict__ outp, float* __restrict__ rowss) {
;     ...
;     { LDB(B0, 1, 0); LDA(At, 1, 0); WAIT_V(2); BAR; WAIT_L(0); MMA(0, 0, At, B0); BAR;
;       LDB(B1, 1, 1); WAIT_V(0); BAR; WAIT_L(0); MMA(0, 1, At, B1); BAR;
;       LDA(At, 1, 1); BAR; WAIT_L(0); MMA(1, 0, At, B0); MMA(1, 1, At, B1); BAR; }
;     if (wr == 0) BAR;
	s_nop 0
	ds_read_b128 v[0:3], v156
	ds_read_b128 v[8:11], v157
	ds_read_b128 v[12:15], v158
	ds_read_b128 v[156:159], v159
	ds_read_b128 v[24:27], v147 offset:32768
	ds_read_b128 v[28:31], v147 offset:33792
	ds_read_b128 v[40:43], v147 offset:34816
	ds_read_b128 v[44:47], v147 offset:35840
	ds_read_b128 v[56:59], v147 offset:36864
	ds_read_b128 v[64:67], v147 offset:37888
	ds_read_b128 v[204:207], v147 offset:38912
	ds_read_b128 v[208:211], v147 offset:39936
	s_waitcnt vmcnt(2)
	s_barrier
	s_waitcnt lgkmcnt(0)
	s_waitcnt lgkmcnt(0)
	v_mfma_f32_16x16x32_bf16 v[72:75], v[0:3], v[24:27], v[126:129]
	v_mfma_f32_16x16x32_bf16 v[126:129], v[8:11], v[28:31], v[72:75]
	v_mfma_f32_16x16x32_bf16 v[72:75], v[12:15], v[24:27], v[122:125]
	v_mfma_f32_16x16x32_bf16 v[114:117], v[156:159], v[28:31], v[72:75]
	v_mfma_f32_16x16x32_bf16 v[72:75], v[0:3], v[40:43], v[118:121]
	v_mfma_f32_16x16x32_bf16 v[106:109], v[8:11], v[44:47], v[72:75]
	v_mfma_f32_16x16x32_bf16 v[72:75], v[12:15], v[40:43], v[220:223]
	v_mfma_f32_16x16x32_bf16 v[110:113], v[156:159], v[44:47], v[72:75]
	v_mfma_f32_16x16x32_bf16 v[72:75], v[0:3], v[56:59], v[224:227]
	v_mfma_f32_16x16x32_bf16 v[88:91], v[8:11], v[64:67], v[72:75]
	v_mfma_f32_16x16x32_bf16 v[72:75], v[12:15], v[56:59], v[228:231]
	v_mfma_f32_16x16x32_bf16 v[92:95], v[156:159], v[64:67], v[72:75]
	v_mfma_f32_16x16x32_bf16 v[72:75], v[0:3], v[204:207], v[102:105]
	v_mfma_f32_16x16x32_bf16 v[76:79], v[12:15], v[204:207], v[98:101]
	v_mfma_f32_16x16x32_bf16 v[72:75], v[8:11], v[208:211], v[72:75]
	v_mfma_f32_16x16x32_bf16 v[76:79], v[156:159], v[208:211], v[76:79]
	s_barrier
	ds_read_b128 v[212:215], v160
	ds_read_b128 v[220:223], v161
	ds_read_b128 v[224:227], v162
	ds_read_b128 v[160:163], v163
	s_waitcnt vmcnt(0)
	s_barrier
	s_waitcnt lgkmcnt(0)
	s_waitcnt lgkmcnt(0)
	v_mfma_f32_16x16x32_bf16 v[98:101], v[212:215], v[24:27], v[232:235]
	v_mfma_f32_16x16x32_bf16 v[24:27], v[224:227], v[24:27], v[176:179]
	v_mfma_f32_16x16x32_bf16 v[122:125], v[160:163], v[28:31], v[24:27]
	v_mfma_f32_16x16x32_bf16 v[24:27], v[212:215], v[40:43], v[84:87]
	v_mfma_f32_16x16x32_bf16 v[118:121], v[220:223], v[28:31], v[98:101]
	v_mfma_f32_16x16x32_bf16 v[98:101], v[220:223], v[44:47], v[24:27]
	v_mfma_f32_16x16x32_bf16 v[24:27], v[224:227], v[40:43], v[80:83]
	v_mfma_f32_16x16x32_bf16 v[102:105], v[160:163], v[44:47], v[24:27]
	v_mfma_f32_16x16x32_bf16 v[24:27], v[212:215], v[56:59], v[180:183]
	v_mfma_f32_16x16x32_bf16 v[80:83], v[220:223], v[64:67], v[24:27]
	v_mfma_f32_16x16x32_bf16 v[24:27], v[224:227], v[56:59], v[196:199]
	v_mfma_f32_16x16x32_bf16 v[84:87], v[160:163], v[64:67], v[24:27]
	v_mfma_f32_16x16x32_bf16 v[24:27], v[212:215], v[204:207], v[68:71]
	v_mfma_f32_16x16x32_bf16 v[64:67], v[220:223], v[208:211], v[24:27]
	v_mfma_f32_16x16x32_bf16 v[24:27], v[224:227], v[204:207], v[200:203]
	v_mfma_f32_16x16x32_bf16 v[68:71], v[160:163], v[208:211], v[24:27]
	s_barrier
	ds_read_b128 v[176:179], v147 offset:49152
	ds_read_b128 v[180:183], v147 offset:50176
	ds_read_b128 v[196:199], v147 offset:51200
	ds_read_b128 v[200:203], v147 offset:52224
	ds_read_b128 v[204:207], v147 offset:53248
	ds_read_b128 v[208:211], v147 offset:54272
	ds_read_b128 v[228:231], v147 offset:55296
	ds_read_b128 v[232:235], v147 offset:56320
	s_barrier
	s_waitcnt lgkmcnt(0)
	s_waitcnt lgkmcnt(0)
	v_mfma_f32_16x16x32_bf16 v[24:27], v[0:3], v[176:179], v[60:63]
	v_mfma_f32_16x16x32_bf16 v[56:59], v[8:11], v[180:183], v[24:27]
	v_mfma_f32_16x16x32_bf16 v[24:27], v[12:15], v[176:179], v[216:219]
	v_mfma_f32_16x16x32_bf16 v[60:63], v[156:159], v[180:183], v[24:27]
	v_mfma_f32_16x16x32_bf16 v[24:27], v[0:3], v[196:199], v[52:55]
	v_mfma_f32_16x16x32_bf16 v[40:43], v[8:11], v[200:203], v[24:27]
	v_mfma_f32_16x16x32_bf16 v[24:27], v[12:15], v[196:199], v[48:51]
	v_mfma_f32_16x16x32_bf16 v[44:47], v[156:159], v[200:203], v[24:27]
	v_mfma_f32_16x16x32_bf16 v[24:27], v[0:3], v[204:207], v[236:239]
	v_mfma_f32_16x16x32_bf16 v[0:3], v[0:3], v[228:231], v[36:39]
	v_mfma_f32_16x16x32_bf16 v[24:27], v[8:11], v[208:211], v[24:27]
	v_mfma_f32_16x16x32_bf16 v[28:31], v[12:15], v[204:207], v[240:243]
	v_mfma_f32_16x16x32_bf16 v[8:11], v[8:11], v[232:235], v[0:3]
	v_mfma_f32_16x16x32_bf16 v[0:3], v[12:15], v[228:231], v[32:35]
	v_mfma_f32_16x16x32_bf16 v[28:31], v[156:159], v[208:211], v[28:31]
	v_mfma_f32_16x16x32_bf16 v[12:15], v[156:159], v[232:235], v[0:3]
	v_mfma_f32_16x16x32_bf16 v[0:3], v[212:215], v[176:179], v[142:145]
	v_mfma_f32_16x16x32_bf16 v[48:51], v[220:223], v[180:183], v[0:3]
	v_mfma_f32_16x16x32_bf16 v[0:3], v[224:227], v[176:179], v[164:167]
	v_mfma_f32_16x16x32_bf16 v[52:55], v[160:163], v[180:183], v[0:3]
	v_mfma_f32_16x16x32_bf16 v[0:3], v[212:215], v[196:199], v[20:23]
	v_mfma_f32_16x16x32_bf16 v[32:35], v[220:223], v[200:203], v[0:3]
	v_mfma_f32_16x16x32_bf16 v[0:3], v[224:227], v[196:199], v[16:19]
	v_mfma_f32_16x16x32_bf16 v[36:39], v[160:163], v[200:203], v[0:3]
	v_mfma_f32_16x16x32_bf16 v[0:3], v[212:215], v[204:207], v[168:171]
	v_mfma_f32_16x16x32_bf16 v[16:19], v[220:223], v[208:211], v[0:3]
	v_mfma_f32_16x16x32_bf16 v[0:3], v[224:227], v[204:207], v[172:175]
	v_mfma_f32_16x16x32_bf16 v[20:23], v[160:163], v[208:211], v[0:3]
	v_mfma_f32_16x16x32_bf16 v[0:3], v[212:215], v[228:231], v[4:7]
	v_mfma_f32_16x16x32_bf16 v[4:7], v[224:227], v[228:231], v[152:155]
	v_mfma_f32_16x16x32_bf16 v[0:3], v[220:223], v[232:235], v[0:3]
	v_mfma_f32_16x16x32_bf16 v[4:7], v[160:163], v[232:235], v[4:7]
	s_andn2_b64 vcc, exec, s[18:19]
	s_barrier
	s_cbranch_vccnz .LBB0_97
	s_barrier

; #define WAIT_V(n) asm volatile("s_waitcnt vmcnt(%0)" ::"n"(n) : "memory")
; #define WAIT_L(n) asm volatile("s_waitcnt lgkmcnt(%0)" ::"n"(n) : "memory")
; #define SBAR() __builtin_amdgcn_sched_barrier(0)
; #define STAGE(P, base, kt) do { _Pragma("unroll") for (int _i = 0; _i < 2; ++_i)                                        \
;       __builtin_amdgcn_global_load_lds((const unsigned*)((base) + (size_t)(sOff[_i] + (unsigned)(kt) * (BK * 2))),        \
;                                        (unsigned*)((P) + wid * 1024 + _i * 8192), 16, 0, 0); } while (0)
; #define LDA(dst, b, h) _Pragma("unroll") for (int m = 0; m < 4; ++m) _Pragma("unroll") for (int k = 0; k < 2; ++k) \
;       dst[m][k] = *(const bf16x8*)(SA(b, h) + aoff + (m * 2048 + k * 1024))
; #define LDB(dst, b, h) _Pragma("unroll") for (int n = 0; n < 2; ++n) _Pragma("unroll") for (int k = 0; k < 2; ++k) \
;       dst[n][k] = *(const bf16x8*)(SB(b, h) + boff + (n * 256 + k * 1024))
; #define BAR __builtin_amdgcn_s_barrier()
; template <int EPI, int N, int K>
; __device__ __forceinline__ void phase_gemm(const Params& p, const u16* __restrict__ A, const u16* __restrict__ Bt, int nM, char* shm,
;                            u16* __restrict__ outp, float* __restrict__ rowss) {
;     ...
;     for (int t = 0; t < nt - 2; t += 2) {
;       LDB(B0, 0, 0); SBAR(); LDA(At, 0, 0); STAGE(SA(1, 1), A1, t + 1);
;       WAIT_L(8); BAR; WAIT_L(0); MMA(0, 0, At, B0); BAR; SBAR();
;       LDB(B1, 0, 1); STAGE(SB(0, 0), B0p, t + 2);
;       BAR; WAIT_L(0); MMA(0, 1, At, B1); BAR;
;       LDA(At, 0, 1); STAGE(SA(0, 0), A0, t + 2);
;       BAR; WAIT_L(0); MMA(1, 0, At, B0); BAR; SBAR();
;       STAGE(SB(0, 1), B1p, t + 2);
;       WAIT_V(6); BAR; MMA(1, 1, At, B1); BAR;
.LBB0_130:
	v_or_b32_e32 v147, 0x10000, v143
	v_add_u32_e32 v149, 0x10100, v143
	v_add_u32_e32 v148, 0x10400, v143
	ds_read_b128 v[156:159], v147
	ds_read_b128 v[160:163], v148
	v_add_u32_e32 v150, 0x10500, v143
	ds_read_b128 v[164:167], v149
	ds_read_b128 v[168:171], v150
	v_add_u32_e32 v240, v142, v140
	s_add_i32 s55, s5, 0xc000
	v_add_u32_e32 v151, 0x80, v240
	s_mov_b32 m0, s55
	v_add_u32_e32 v241, v142, v141
	s_add_i32 s54, s5, 0xe000
	ds_read_b128 v[172:175], v144
	ds_read_b128 v[176:179], v144 offset:1024
	ds_read_b128 v[180:183], v144 offset:2048
	ds_read_b128 v[196:199], v144 offset:3072
	ds_read_b128 v[200:203], v144 offset:4096
	ds_read_b128 v[204:207], v144 offset:5120
	ds_read_b128 v[208:211], v144 offset:6144
	ds_read_b128 v[212:215], v144 offset:7168
	global_load_lds_dwordx4 v151, s[16:17]
	v_add_u32_e32 v151, 0x80, v241
	s_mov_b32 m0, s54
	s_nop 0
	global_load_lds_dwordx4 v151, s[16:17]
	v_or_b32_e32 v151, 0x14000, v143
	v_add_u32_e32 v153, 0x14100, v143
	v_add_u32_e32 v152, 0x14400, v143
	ds_read_b128 v[216:219], v151
	ds_read_b128 v[220:223], v152
	v_add_u32_e32 v154, 0x14500, v143
	ds_read_b128 v[224:227], v153
	ds_read_b128 v[228:231], v154
	s_waitcnt vmcnt(8)
	s_waitcnt lgkmcnt(0)
	s_barrier
	v_mfma_f32_16x16x32_bf16 v[126:129], v[156:159], v[172:175], v[126:129]
	v_mfma_f32_16x16x32_bf16 v[122:125], v[164:167], v[172:175], v[122:125]
	v_mfma_f32_16x16x32_bf16 v[118:121], v[156:159], v[180:183], v[118:121]
	v_mfma_f32_16x16x32_bf16 v[114:117], v[164:167], v[180:183], v[114:117]
	v_mfma_f32_16x16x32_bf16 v[110:113], v[156:159], v[200:203], v[110:113]
	v_mfma_f32_16x16x32_bf16 v[106:109], v[164:167], v[200:203], v[106:109]
	v_mfma_f32_16x16x32_bf16 v[102:105], v[156:159], v[208:211], v[102:105]
	v_mfma_f32_16x16x32_bf16 v[98:101], v[164:167], v[208:211], v[98:101]
	v_mfma_f32_16x16x32_bf16 v[126:129], v[160:163], v[176:179], v[126:129]
	v_mfma_f32_16x16x32_bf16 v[122:125], v[168:171], v[176:179], v[122:125]
	v_mfma_f32_16x16x32_bf16 v[118:121], v[160:163], v[196:199], v[118:121]
	v_mfma_f32_16x16x32_bf16 v[114:117], v[168:171], v[196:199], v[114:117]
	v_mfma_f32_16x16x32_bf16 v[110:113], v[160:163], v[204:207], v[110:113]
	v_mfma_f32_16x16x32_bf16 v[106:109], v[168:171], v[204:207], v[106:109]
	v_mfma_f32_16x16x32_bf16 v[102:105], v[160:163], v[212:215], v[102:105]
	v_mfma_f32_16x16x32_bf16 v[98:101], v[168:171], v[212:215], v[98:101]
	v_mfma_f32_16x16x32_bf16 v[92:95], v[216:219], v[172:175], v[92:95]
	v_mfma_f32_16x16x32_bf16 v[88:91], v[224:227], v[172:175], v[88:91]
	v_mfma_f32_16x16x32_bf16 v[84:87], v[216:219], v[180:183], v[84:87]
	v_mfma_f32_16x16x32_bf16 v[80:83], v[224:227], v[180:183], v[80:83]
	v_mfma_f32_16x16x32_bf16 v[76:79], v[216:219], v[200:203], v[76:79]
	v_mfma_f32_16x16x32_bf16 v[72:75], v[224:227], v[200:203], v[72:75]
	v_mfma_f32_16x16x32_bf16 v[68:71], v[216:219], v[208:211], v[68:71]
	v_mfma_f32_16x16x32_bf16 v[64:67], v[224:227], v[208:211], v[64:67]
	v_mfma_f32_16x16x32_bf16 v[92:95], v[220:223], v[176:179], v[92:95]
	v_mfma_f32_16x16x32_bf16 v[88:91], v[228:231], v[176:179], v[88:91]
	v_mfma_f32_16x16x32_bf16 v[84:87], v[220:223], v[196:199], v[84:87]
	v_mfma_f32_16x16x32_bf16 v[80:83], v[228:231], v[196:199], v[80:83]
	v_mfma_f32_16x16x32_bf16 v[76:79], v[220:223], v[204:207], v[76:79]
	v_mfma_f32_16x16x32_bf16 v[72:75], v[228:231], v[204:207], v[72:75]
	v_mfma_f32_16x16x32_bf16 v[68:71], v[220:223], v[212:215], v[68:71]
	v_mfma_f32_16x16x32_bf16 v[64:67], v[228:231], v[212:215], v[64:67]
	s_barrier
	ds_read_b128 v[172:175], v144 offset:16384
	ds_read_b128 v[176:179], v144 offset:17408
	ds_read_b128 v[180:183], v144 offset:18432
	ds_read_b128 v[196:199], v144 offset:19456
	ds_read_b128 v[200:203], v144 offset:20480
	ds_read_b128 v[204:207], v144 offset:21504
	ds_read_b128 v[208:211], v144 offset:22528
	ds_read_b128 v[212:215], v144 offset:23552
	s_mov_b32 m0, s23
	v_add_u32_e32 v232, 0x100, v240
	global_load_lds_dwordx4 v232, s[8:9]
	v_add_u32_e32 v233, 0x100, v241
	s_mov_b32 m0, s94
	s_nop 0
	global_load_lds_dwordx4 v233, s[8:9]
	s_mov_b32 m0, s5
	s_nop 0
	global_load_lds_dwordx4 v232, s[10:11]
	s_mov_b32 m0, s22
	s_nop 0
	global_load_lds_dwordx4 v233, s[10:11]
	s_mov_b32 m0, s95
	s_nop 0
	global_load_lds_dwordx4 v232, s[18:19]
	s_mov_b32 m0, s96
	s_nop 0
	global_load_lds_dwordx4 v233, s[18:19]
	s_waitcnt vmcnt(8)
	s_waitcnt lgkmcnt(0)
	s_barrier
	v_mfma_f32_16x16x32_bf16 v[60:63], v[156:159], v[172:175], v[60:63]
	v_mfma_f32_16x16x32_bf16 v[56:59], v[164:167], v[172:175], v[56:59]
	v_mfma_f32_16x16x32_bf16 v[52:55], v[156:159], v[180:183], v[52:55]
	v_mfma_f32_16x16x32_bf16 v[48:51], v[164:167], v[180:183], v[48:51]
	v_mfma_f32_16x16x32_bf16 v[44:47], v[156:159], v[200:203], v[44:47]
	v_mfma_f32_16x16x32_bf16 v[40:43], v[164:167], v[200:203], v[40:43]
	v_mfma_f32_16x16x32_bf16 v[36:39], v[156:159], v[208:211], v[36:39]
	v_mfma_f32_16x16x32_bf16 v[32:35], v[164:167], v[208:211], v[32:35]
	v_mfma_f32_16x16x32_bf16 v[60:63], v[160:163], v[176:179], v[60:63]
	v_mfma_f32_16x16x32_bf16 v[56:59], v[168:171], v[176:179], v[56:59]
	v_mfma_f32_16x16x32_bf16 v[52:55], v[160:163], v[196:199], v[52:55]
	v_mfma_f32_16x16x32_bf16 v[48:51], v[168:171], v[196:199], v[48:51]
	v_mfma_f32_16x16x32_bf16 v[44:47], v[160:163], v[204:207], v[44:47]
	v_mfma_f32_16x16x32_bf16 v[40:43], v[168:171], v[204:207], v[40:43]
	v_mfma_f32_16x16x32_bf16 v[36:39], v[160:163], v[212:215], v[36:39]
	v_mfma_f32_16x16x32_bf16 v[32:35], v[168:171], v[212:215], v[32:35]
	v_mfma_f32_16x16x32_bf16 v[28:31], v[216:219], v[172:175], v[28:31]
	v_mfma_f32_16x16x32_bf16 v[24:27], v[224:227], v[172:175], v[24:27]
	v_mfma_f32_16x16x32_bf16 v[20:23], v[216:219], v[180:183], v[20:23]
	v_mfma_f32_16x16x32_bf16 v[16:19], v[224:227], v[180:183], v[16:19]
	v_mfma_f32_16x16x32_bf16 v[12:15], v[216:219], v[200:203], v[12:15]
	v_mfma_f32_16x16x32_bf16 v[8:11], v[224:227], v[200:203], v[8:11]
	v_mfma_f32_16x16x32_bf16 v[4:7], v[216:219], v[208:211], v[4:7]
	v_mfma_f32_16x16x32_bf16 v[0:3], v[224:227], v[208:211], v[0:3]
	v_mfma_f32_16x16x32_bf16 v[28:31], v[220:223], v[176:179], v[28:31]
	v_mfma_f32_16x16x32_bf16 v[24:27], v[228:231], v[176:179], v[24:27]
	v_mfma_f32_16x16x32_bf16 v[20:23], v[220:223], v[196:199], v[20:23]
	v_mfma_f32_16x16x32_bf16 v[16:19], v[228:231], v[196:199], v[16:19]
	v_mfma_f32_16x16x32_bf16 v[12:15], v[220:223], v[204:207], v[12:15]
	v_mfma_f32_16x16x32_bf16 v[8:11], v[228:231], v[204:207], v[8:11]
	v_mfma_f32_16x16x32_bf16 v[4:7], v[220:223], v[212:215], v[4:7]
	v_mfma_f32_16x16x32_bf16 v[0:3], v[228:231], v[212:215], v[0:3]
	v_or_b32_e32 v155, 0x18000, v143
	v_add_u32_e32 v157, 0x18100, v143
	s_barrier
; #define WAIT_V(n) asm volatile("s_waitcnt vmcnt(%0)" ::"n"(n) : "memory")
; #define WAIT_L(n) asm volatile("s_waitcnt lgkmcnt(%0)" ::"n"(n) : "memory")
; #define SBAR() __builtin_amdgcn_sched_barrier(0)
; #define STAGE(P, base, kt) do { _Pragma("unroll") for (int _i = 0; _i < 2; ++_i)                                        \
;       __builtin_amdgcn_global_load_lds((const unsigned*)((base) + (size_t)(sOff[_i] + (unsigned)(kt) * (BK * 2))),        \
;                                        (unsigned*)((P) + wid * 1024 + _i * 8192), 16, 0, 0); } while (0)
; #define LDA(dst, b, h) _Pragma("unroll") for (int m = 0; m < 4; ++m) _Pragma("unroll") for (int k = 0; k < 2; ++k) \
;       dst[m][k] = *(const bf16x8*)(SA(b, h) + aoff + (m * 2048 + k * 1024))
; #define LDB(dst, b, h) _Pragma("unroll") for (int n = 0; n < 2; ++n) _Pragma("unroll") for (int k = 0; k < 2; ++k) \
;       dst[n][k] = *(const bf16x8*)(SB(b, h) + boff + (n * 256 + k * 1024))
; #define BAR __builtin_amdgcn_s_barrier()
; template <int EPI, int N, int K>
; __device__ __forceinline__ void phase_gemm(const Params& p, const u16* __restrict__ A, const u16* __restrict__ Bt, int nM, char* shm,
;                            u16* __restrict__ outp, float* __restrict__ rowss) {
;     ...
;       LDB(B0, 1, 0); SBAR(); LDA(At, 1, 0); STAGE(SA(0, 1), A1, t + 2);
;       WAIT_L(8); BAR; WAIT_L(0); MMA(0, 0, At, B0); BAR; SBAR();
;       LDB(B1, 1, 1); STAGE(SB(1, 0), B0p, t + 3);
;       BAR; WAIT_L(0); MMA(0, 1, At, B1); BAR;
;       LDA(At, 1, 1); STAGE(SA(1, 0), A0, t + 3);
;       BAR; WAIT_L(0); MMA(1, 0, At, B0); BAR; SBAR();
;       STAGE(SB(1, 1), B1p, t + 3);
;       WAIT_V(6); BAR; MMA(1, 1, At, B1); BAR;
;     }
	v_add_u32_e32 v156, 0x18400, v143
	ds_read_b128 v[164:167], v155
	ds_read_b128 v[168:171], v156
	v_add_u32_e32 v158, 0x18500, v143
	ds_read_b128 v[172:175], v157
	ds_read_b128 v[176:179], v158
	s_mov_b32 m0, s97
	ds_read_b128 v[180:183], v144 offset:32768
	ds_read_b128 v[196:199], v144 offset:33792
	ds_read_b128 v[200:203], v144 offset:34816
	ds_read_b128 v[204:207], v144 offset:35840
	ds_read_b128 v[208:211], v144 offset:36864
	ds_read_b128 v[212:215], v144 offset:37888
	ds_read_b128 v[216:219], v144 offset:38912
	ds_read_b128 v[220:223], v144 offset:39936
	global_load_lds_dwordx4 v232, s[16:17]
	s_mov_b32 m0, s33
	s_nop 0
	global_load_lds_dwordx4 v233, s[16:17]
	v_or_b32_e32 v159, 0x1c000, v143
	v_add_u32_e32 v161, 0x1c100, v143
	v_add_u32_e32 v160, 0x1c400, v143
	ds_read_b128 v[224:227], v159
	ds_read_b128 v[228:231], v160
	v_add_u32_e32 v162, 0x1c500, v143
	ds_read_b128 v[232:235], v161
	ds_read_b128 v[236:239], v162
	s_waitcnt vmcnt(8)
	s_waitcnt lgkmcnt(0)
	s_barrier
	v_mfma_f32_16x16x32_bf16 v[126:129], v[164:167], v[180:183], v[126:129]
	v_mfma_f32_16x16x32_bf16 v[122:125], v[172:175], v[180:183], v[122:125]
	v_mfma_f32_16x16x32_bf16 v[118:121], v[164:167], v[200:203], v[118:121]
	v_mfma_f32_16x16x32_bf16 v[114:117], v[172:175], v[200:203], v[114:117]
	v_mfma_f32_16x16x32_bf16 v[110:113], v[164:167], v[208:211], v[110:113]
	v_mfma_f32_16x16x32_bf16 v[106:109], v[172:175], v[208:211], v[106:109]
	v_mfma_f32_16x16x32_bf16 v[102:105], v[164:167], v[216:219], v[102:105]
	v_mfma_f32_16x16x32_bf16 v[98:101], v[172:175], v[216:219], v[98:101]
	v_mfma_f32_16x16x32_bf16 v[126:129], v[168:171], v[196:199], v[126:129]
	v_mfma_f32_16x16x32_bf16 v[122:125], v[176:179], v[196:199], v[122:125]
	v_mfma_f32_16x16x32_bf16 v[118:121], v[168:171], v[204:207], v[118:121]
	v_mfma_f32_16x16x32_bf16 v[114:117], v[176:179], v[204:207], v[114:117]
	v_mfma_f32_16x16x32_bf16 v[110:113], v[168:171], v[212:215], v[110:113]
	v_mfma_f32_16x16x32_bf16 v[106:109], v[176:179], v[212:215], v[106:109]
	v_mfma_f32_16x16x32_bf16 v[102:105], v[168:171], v[220:223], v[102:105]
	v_mfma_f32_16x16x32_bf16 v[98:101], v[176:179], v[220:223], v[98:101]
	v_mfma_f32_16x16x32_bf16 v[92:95], v[224:227], v[180:183], v[92:95]
	v_mfma_f32_16x16x32_bf16 v[88:91], v[232:235], v[180:183], v[88:91]
	v_mfma_f32_16x16x32_bf16 v[84:87], v[224:227], v[200:203], v[84:87]
	v_mfma_f32_16x16x32_bf16 v[80:83], v[232:235], v[200:203], v[80:83]
	v_mfma_f32_16x16x32_bf16 v[76:79], v[224:227], v[208:211], v[76:79]
	v_mfma_f32_16x16x32_bf16 v[72:75], v[232:235], v[208:211], v[72:75]
	v_mfma_f32_16x16x32_bf16 v[68:71], v[224:227], v[216:219], v[68:71]
	v_mfma_f32_16x16x32_bf16 v[64:67], v[232:235], v[216:219], v[64:67]
	v_mfma_f32_16x16x32_bf16 v[92:95], v[228:231], v[196:199], v[92:95]
	v_mfma_f32_16x16x32_bf16 v[88:91], v[236:239], v[196:199], v[88:91]
	v_mfma_f32_16x16x32_bf16 v[84:87], v[228:231], v[204:207], v[84:87]
	v_mfma_f32_16x16x32_bf16 v[80:83], v[236:239], v[204:207], v[80:83]
	v_mfma_f32_16x16x32_bf16 v[76:79], v[228:231], v[212:215], v[76:79]
	v_mfma_f32_16x16x32_bf16 v[72:75], v[236:239], v[212:215], v[72:75]
	v_mfma_f32_16x16x32_bf16 v[68:71], v[228:231], v[220:223], v[68:71]
	v_mfma_f32_16x16x32_bf16 v[64:67], v[236:239], v[220:223], v[64:67]
	s_barrier
	ds_read_b128 v[180:183], v144 offset:49152
	ds_read_b128 v[196:199], v144 offset:50176
	ds_read_b128 v[200:203], v144 offset:51200
	ds_read_b128 v[204:207], v144 offset:52224
	ds_read_b128 v[208:211], v144 offset:53248
	ds_read_b128 v[212:215], v144 offset:54272
	ds_read_b128 v[216:219], v144 offset:55296
	ds_read_b128 v[220:223], v144 offset:56320
	s_mov_b32 m0, s35
	v_add_u32_e32 v163, 0x180, v240
	global_load_lds_dwordx4 v163, s[8:9]
	v_add_u32_e32 v240, 0x180, v241
	s_mov_b32 m0, s93
	s_nop 0
	global_load_lds_dwordx4 v240, s[8:9]
	s_mov_b32 m0, s24
	s_nop 0
	global_load_lds_dwordx4 v163, s[10:11]
	s_mov_b32 m0, s25
	s_nop 0
	global_load_lds_dwordx4 v240, s[10:11]
	s_mov_b32 m0, s26
	s_nop 0
	global_load_lds_dwordx4 v163, s[18:19]
	s_mov_b32 m0, s27
	s_nop 0
	global_load_lds_dwordx4 v240, s[18:19]
	s_waitcnt vmcnt(8)
	s_waitcnt lgkmcnt(0)
	s_barrier
	v_mfma_f32_16x16x32_bf16 v[60:63], v[164:167], v[180:183], v[60:63]
	v_mfma_f32_16x16x32_bf16 v[56:59], v[172:175], v[180:183], v[56:59]
	v_mfma_f32_16x16x32_bf16 v[52:55], v[164:167], v[200:203], v[52:55]
	v_mfma_f32_16x16x32_bf16 v[48:51], v[172:175], v[200:203], v[48:51]
	v_mfma_f32_16x16x32_bf16 v[44:47], v[164:167], v[208:211], v[44:47]
	v_mfma_f32_16x16x32_bf16 v[40:43], v[172:175], v[208:211], v[40:43]
	v_mfma_f32_16x16x32_bf16 v[36:39], v[164:167], v[216:219], v[36:39]
	v_mfma_f32_16x16x32_bf16 v[32:35], v[172:175], v[216:219], v[32:35]
	v_mfma_f32_16x16x32_bf16 v[60:63], v[168:171], v[196:199], v[60:63]
	v_mfma_f32_16x16x32_bf16 v[56:59], v[176:179], v[196:199], v[56:59]
	v_mfma_f32_16x16x32_bf16 v[52:55], v[168:171], v[204:207], v[52:55]
	v_mfma_f32_16x16x32_bf16 v[48:51], v[176:179], v[204:207], v[48:51]
	v_mfma_f32_16x16x32_bf16 v[44:47], v[168:171], v[212:215], v[44:47]
	v_mfma_f32_16x16x32_bf16 v[40:43], v[176:179], v[212:215], v[40:43]
	v_mfma_f32_16x16x32_bf16 v[36:39], v[168:171], v[220:223], v[36:39]
	v_mfma_f32_16x16x32_bf16 v[32:35], v[176:179], v[220:223], v[32:35]
	v_mfma_f32_16x16x32_bf16 v[28:31], v[224:227], v[180:183], v[28:31]
	v_mfma_f32_16x16x32_bf16 v[24:27], v[232:235], v[180:183], v[24:27]
	v_mfma_f32_16x16x32_bf16 v[20:23], v[224:227], v[200:203], v[20:23]
	v_mfma_f32_16x16x32_bf16 v[16:19], v[232:235], v[200:203], v[16:19]
	v_mfma_f32_16x16x32_bf16 v[12:15], v[224:227], v[208:211], v[12:15]
	v_mfma_f32_16x16x32_bf16 v[8:11], v[232:235], v[208:211], v[8:11]
	v_mfma_f32_16x16x32_bf16 v[4:7], v[224:227], v[216:219], v[4:7]
	v_mfma_f32_16x16x32_bf16 v[0:3], v[232:235], v[216:219], v[0:3]
	v_mfma_f32_16x16x32_bf16 v[28:31], v[228:231], v[196:199], v[28:31]
	v_mfma_f32_16x16x32_bf16 v[24:27], v[236:239], v[196:199], v[24:27]
	v_mfma_f32_16x16x32_bf16 v[20:23], v[228:231], v[204:207], v[20:23]
	v_mfma_f32_16x16x32_bf16 v[16:19], v[236:239], v[204:207], v[16:19]
	v_mfma_f32_16x16x32_bf16 v[12:15], v[228:231], v[212:215], v[12:15]
	v_mfma_f32_16x16x32_bf16 v[8:11], v[236:239], v[212:215], v[8:11]
	v_mfma_f32_16x16x32_bf16 v[4:7], v[228:231], v[220:223], v[4:7]
	v_mfma_f32_16x16x32_bf16 v[0:3], v[236:239], v[220:223], v[0:3]
	s_add_i32 s53, s53, 2
	v_add_u32_e32 v141, 0x100, v141
	s_cmp_lt_u32 s53, 12
	v_add_u32_e32 v140, 0x100, v140
	s_barrier
; #define WAIT_V(n) asm volatile("s_waitcnt vmcnt(%0)" ::"n"(n) : "memory")
; #define WAIT_L(n) asm volatile("s_waitcnt lgkmcnt(%0)" ::"n"(n) : "memory")
; #define STAGE(P, base, kt) do { _Pragma("unroll") for (int _i = 0; _i < 2; ++_i)                                        \
;       __builtin_amdgcn_global_load_lds((const unsigned*)((base) + (size_t)(sOff[_i] + (unsigned)(kt) * (BK * 2))),        \
;                                        (unsigned*)((P) + wid * 1024 + _i * 8192), 16, 0, 0); } while (0)
; #define LDA(dst, b, h) _Pragma("unroll") for (int m = 0; m < 4; ++m) _Pragma("unroll") for (int k = 0; k < 2; ++k) \
;       dst[m][k] = *(const bf16x8*)(SA(b, h) + aoff + (m * 2048 + k * 1024))
; #define LDB(dst, b, h) _Pragma("unroll") for (int n = 0; n < 2; ++n) _Pragma("unroll") for (int k = 0; k < 2; ++k) \
;       dst[n][k] = *(const bf16x8*)(SB(b, h) + boff + (n * 256 + k * 1024))
; #define BAR __builtin_amdgcn_s_barrier()
; template <int EPI, int N, int K>
; __device__ __forceinline__ void phase_gemm(const Params& p, const u16* __restrict__ A, const u16* __restrict__ Bt, int nM, char* shm,
;                            u16* __restrict__ outp, float* __restrict__ rowss) {
;     ...
;     { LDB(B0, 0, 0); LDA(At, 0, 0); STAGE(SA(1, 1), A1, nt - 1);
;       BAR; WAIT_L(0); MMA(0, 0, At, B0); BAR;
;       LDB(B1, 0, 1); BAR; WAIT_L(0); MMA(0, 1, At, B1); BAR;
;       LDA(At, 0, 1); WAIT_V(4); BAR; WAIT_L(0); MMA(1, 0, At, B0); MMA(1, 1, At, B1); BAR; }
	s_cbranch_scc1 .LBB0_130
	s_waitcnt vmcnt(6)
	s_mov_b32 m0, s55
	v_lshl_add_u64 v[140:141], s[16:17], 0, v[136:137]
	ds_read_b128 v[164:167], v147
	ds_read_b128 v[168:171], v148
	ds_read_b128 v[172:175], v149
	ds_read_b128 v[176:179], v150
	ds_read_b128 v[180:183], v144
	ds_read_b128 v[196:199], v144 offset:1024
	ds_read_b128 v[200:203], v144 offset:2048
	ds_read_b128 v[204:207], v144 offset:3072
	ds_read_b128 v[208:211], v144 offset:4096
	ds_read_b128 v[212:215], v144 offset:5120
	ds_read_b128 v[216:219], v144 offset:6144
	ds_read_b128 v[220:223], v144 offset:7168
	global_load_lds_dwordx4 v[140:141], off
	v_lshl_add_u64 v[140:141], s[16:17], 0, v[138:139]
	s_mov_b32 m0, s54
	s_nop 0
	global_load_lds_dwordx4 v[140:141], off
	s_barrier
	s_waitcnt lgkmcnt(0)
	s_waitcnt lgkmcnt(0)
	v_mfma_f32_16x16x32_bf16 v[126:129], v[164:167], v[180:183], v[126:129]
	v_mfma_f32_16x16x32_bf16 v[118:121], v[164:167], v[200:203], v[118:121]
	v_mfma_f32_16x16x32_bf16 v[110:113], v[164:167], v[208:211], v[110:113]
	v_mfma_f32_16x16x32_bf16 v[102:105], v[164:167], v[216:219], v[102:105]
	v_mfma_f32_16x16x32_bf16 v[126:129], v[168:171], v[196:199], v[126:129]
	v_mfma_f32_16x16x32_bf16 v[122:125], v[172:175], v[180:183], v[122:125]
	v_mfma_f32_16x16x32_bf16 v[118:121], v[168:171], v[204:207], v[118:121]
	v_mfma_f32_16x16x32_bf16 v[114:117], v[172:175], v[200:203], v[114:117]
	v_mfma_f32_16x16x32_bf16 v[110:113], v[168:171], v[212:215], v[110:113]
	v_mfma_f32_16x16x32_bf16 v[106:109], v[172:175], v[208:211], v[106:109]
	v_mfma_f32_16x16x32_bf16 v[102:105], v[168:171], v[220:223], v[102:105]
	v_mfma_f32_16x16x32_bf16 v[98:101], v[172:175], v[216:219], v[98:101]
	v_mfma_f32_16x16x32_bf16 v[224:227], v[176:179], v[196:199], v[122:125]
	v_mfma_f32_16x16x32_bf16 v[228:231], v[176:179], v[204:207], v[114:117]
	v_mfma_f32_16x16x32_bf16 v[232:235], v[176:179], v[212:215], v[106:109]
	v_mfma_f32_16x16x32_bf16 v[236:239], v[176:179], v[220:223], v[98:101]
	s_barrier
	s_nop 1
	ds_read_b128 v[98:101], v151
	ds_read_b128 v[106:109], v152
	ds_read_b128 v[114:117], v153
	ds_read_b128 v[122:125], v154
	s_barrier
	s_waitcnt lgkmcnt(0)
	s_waitcnt lgkmcnt(0)
	v_mfma_f32_16x16x32_bf16 v[92:95], v[98:101], v[180:183], v[92:95]
	v_mfma_f32_16x16x32_bf16 v[84:87], v[98:101], v[200:203], v[84:87]
	v_mfma_f32_16x16x32_bf16 v[76:79], v[98:101], v[208:211], v[76:79]
	v_mfma_f32_16x16x32_bf16 v[68:71], v[98:101], v[216:219], v[68:71]
	v_mfma_f32_16x16x32_bf16 v[92:95], v[106:109], v[196:199], v[92:95]
	v_mfma_f32_16x16x32_bf16 v[88:91], v[114:117], v[180:183], v[88:91]
	v_mfma_f32_16x16x32_bf16 v[84:87], v[106:109], v[204:207], v[84:87]
	v_mfma_f32_16x16x32_bf16 v[80:83], v[114:117], v[200:203], v[80:83]
	v_mfma_f32_16x16x32_bf16 v[76:79], v[106:109], v[212:215], v[76:79]
	v_mfma_f32_16x16x32_bf16 v[72:75], v[114:117], v[208:211], v[72:75]
	v_mfma_f32_16x16x32_bf16 v[68:71], v[106:109], v[220:223], v[68:71]
	v_mfma_f32_16x16x32_bf16 v[64:67], v[114:117], v[216:219], v[64:67]
	v_mfma_f32_16x16x32_bf16 v[148:151], v[122:125], v[196:199], v[88:91]
	v_mfma_f32_16x16x32_bf16 v[180:183], v[122:125], v[204:207], v[80:83]
	v_mfma_f32_16x16x32_bf16 v[196:199], v[122:125], v[212:215], v[72:75]
	v_mfma_f32_16x16x32_bf16 v[200:203], v[122:125], v[220:223], v[64:67]
	s_barrier
	s_nop 1
	ds_read_b128 v[64:67], v144 offset:16384
	ds_read_b128 v[72:75], v144 offset:17408
	ds_read_b128 v[80:83], v144 offset:18432
	ds_read_b128 v[88:91], v144 offset:19456
	ds_read_b128 v[204:207], v144 offset:20480
	ds_read_b128 v[208:211], v144 offset:21504
	ds_read_b128 v[212:215], v144 offset:22528
	ds_read_b128 v[216:219], v144 offset:23552
	s_waitcnt vmcnt(4)
	s_barrier
	s_waitcnt lgkmcnt(0)
	s_waitcnt lgkmcnt(0)
	v_mfma_f32_16x16x32_bf16 v[60:63], v[164:167], v[64:67], v[60:63]
	v_mfma_f32_16x16x32_bf16 v[52:55], v[164:167], v[80:83], v[52:55]
	v_mfma_f32_16x16x32_bf16 v[44:47], v[164:167], v[204:207], v[44:47]
	v_mfma_f32_16x16x32_bf16 v[36:39], v[164:167], v[212:215], v[36:39]
	v_mfma_f32_16x16x32_bf16 v[60:63], v[168:171], v[72:75], v[60:63]
	v_mfma_f32_16x16x32_bf16 v[56:59], v[172:175], v[64:67], v[56:59]
	v_mfma_f32_16x16x32_bf16 v[52:55], v[168:171], v[88:91], v[52:55]
	v_mfma_f32_16x16x32_bf16 v[48:51], v[172:175], v[80:83], v[48:51]
	v_mfma_f32_16x16x32_bf16 v[44:47], v[168:171], v[208:211], v[44:47]
	v_mfma_f32_16x16x32_bf16 v[40:43], v[172:175], v[204:207], v[40:43]
	v_mfma_f32_16x16x32_bf16 v[36:39], v[168:171], v[216:219], v[36:39]
	v_mfma_f32_16x16x32_bf16 v[32:35], v[172:175], v[212:215], v[32:35]
	v_mfma_f32_16x16x32_bf16 v[220:223], v[176:179], v[72:75], v[56:59]
	v_mfma_f32_16x16x32_bf16 v[240:243], v[176:179], v[88:91], v[48:51]
	v_mfma_f32_16x16x32_bf16 v[244:247], v[176:179], v[208:211], v[40:43]
	v_mfma_f32_16x16x32_bf16 v[164:167], v[176:179], v[216:219], v[32:35]
	v_mfma_f32_16x16x32_bf16 v[28:31], v[98:101], v[64:67], v[28:31]
	v_mfma_f32_16x16x32_bf16 v[20:23], v[98:101], v[80:83], v[20:23]
	v_mfma_f32_16x16x32_bf16 v[12:15], v[98:101], v[204:207], v[12:15]
	v_mfma_f32_16x16x32_bf16 v[4:7], v[98:101], v[212:215], v[4:7]
	v_mfma_f32_16x16x32_bf16 v[28:31], v[106:109], v[72:75], v[28:31]
	v_mfma_f32_16x16x32_bf16 v[24:27], v[114:117], v[64:67], v[24:27]
	v_mfma_f32_16x16x32_bf16 v[20:23], v[106:109], v[88:91], v[20:23]
	v_mfma_f32_16x16x32_bf16 v[16:19], v[114:117], v[80:83], v[16:19]
	v_mfma_f32_16x16x32_bf16 v[12:15], v[106:109], v[208:211], v[12:15]
	v_mfma_f32_16x16x32_bf16 v[8:11], v[114:117], v[204:207], v[8:11]
	v_mfma_f32_16x16x32_bf16 v[4:7], v[106:109], v[216:219], v[4:7]
	v_mfma_f32_16x16x32_bf16 v[0:3], v[114:117], v[212:215], v[0:3]
	v_mfma_f32_16x16x32_bf16 v[168:171], v[122:125], v[72:75], v[24:27]
	v_mfma_f32_16x16x32_bf16 v[172:175], v[122:125], v[88:91], v[16:19]
	v_mfma_f32_16x16x32_bf16 v[176:179], v[122:125], v[208:211], v[8:11]
	v_mfma_f32_16x16x32_bf16 v[204:207], v[122:125], v[216:219], v[0:3]
	s_barrier
; #define WAIT_V(n) asm volatile("s_waitcnt vmcnt(%0)" ::"n"(n) : "memory")
; #define WAIT_L(n) asm volatile("s_waitcnt lgkmcnt(%0)" ::"n"(n) : "memory")
; #define LDA(dst, b, h) _Pragma("unroll") for (int m = 0; m < 4; ++m) _Pragma("unroll") for (int k = 0; k < 2; ++k) \
;       dst[m][k] = *(const bf16x8*)(SA(b, h) + aoff + (m * 2048 + k * 1024))
; #define LDB(dst, b, h) _Pragma("unroll") for (int n = 0; n < 2; ++n) _Pragma("unroll") for (int k = 0; k < 2; ++k) \
;       dst[n][k] = *(const bf16x8*)(SB(b, h) + boff + (n * 256 + k * 1024))
; #define BAR __builtin_amdgcn_s_barrier()
; template <int EPI, int N, int K>
; __device__ __forceinline__ void phase_gemm(const Params& p, const u16* __restrict__ A, const u16* __restrict__ Bt, int nM, char* shm,
;                            u16* __restrict__ outp, float* __restrict__ rowss) {
;     ...
;     { LDB(B0, 1, 0); LDA(At, 1, 0); WAIT_V(2); BAR; WAIT_L(0); MMA(0, 0, At, B0); BAR;
;       LDB(B1, 1, 1); WAIT_V(0); BAR; WAIT_L(0); MMA(0, 1, At, B1); BAR;
;       LDA(At, 1, 1); BAR; WAIT_L(0); MMA(1, 0, At, B0); MMA(1, 1, At, B1); BAR; }
;     if (wr == 0) BAR;
	s_nop 1
	ds_read_b128 v[0:3], v155
	ds_read_b128 v[8:11], v156
	ds_read_b128 v[152:155], v157
	ds_read_b128 v[208:211], v158
	ds_read_b128 v[16:19], v144 offset:32768
	ds_read_b128 v[24:27], v144 offset:33792
	ds_read_b128 v[32:35], v144 offset:34816
	ds_read_b128 v[40:43], v144 offset:35840
	ds_read_b128 v[48:51], v144 offset:36864
	ds_read_b128 v[56:59], v144 offset:37888
	ds_read_b128 v[212:215], v144 offset:38912
	ds_read_b128 v[216:219], v144 offset:39936
	s_waitcnt vmcnt(2)
	s_barrier
	s_waitcnt lgkmcnt(0)
	s_waitcnt lgkmcnt(0)
	v_mfma_f32_16x16x32_bf16 v[64:67], v[0:3], v[16:19], v[126:129]
	v_mfma_f32_16x16x32_bf16 v[122:125], v[8:11], v[24:27], v[64:67]
	v_mfma_f32_16x16x32_bf16 v[64:67], v[152:155], v[16:19], v[224:227]
	v_mfma_f32_16x16x32_bf16 v[114:117], v[208:211], v[24:27], v[64:67]
	v_mfma_f32_16x16x32_bf16 v[64:67], v[0:3], v[32:35], v[118:121]
	v_mfma_f32_16x16x32_bf16 v[106:109], v[8:11], v[40:43], v[64:67]
	v_mfma_f32_16x16x32_bf16 v[64:67], v[152:155], v[32:35], v[228:231]
	v_mfma_f32_16x16x32_bf16 v[98:101], v[208:211], v[40:43], v[64:67]
	v_mfma_f32_16x16x32_bf16 v[64:67], v[0:3], v[48:51], v[110:113]
	v_mfma_f32_16x16x32_bf16 v[88:91], v[8:11], v[56:59], v[64:67]
	v_mfma_f32_16x16x32_bf16 v[64:67], v[152:155], v[48:51], v[232:235]
	v_mfma_f32_16x16x32_bf16 v[80:83], v[208:211], v[56:59], v[64:67]
	v_mfma_f32_16x16x32_bf16 v[64:67], v[0:3], v[212:215], v[102:105]
	v_mfma_f32_16x16x32_bf16 v[72:75], v[8:11], v[216:219], v[64:67]
	v_mfma_f32_16x16x32_bf16 v[64:67], v[152:155], v[212:215], v[236:239]
	v_mfma_f32_16x16x32_bf16 v[64:67], v[208:211], v[216:219], v[64:67]
	s_barrier
	ds_read_b128 v[156:159], v159
	ds_read_b128 v[224:227], v160
	ds_read_b128 v[228:231], v161
	ds_read_b128 v[160:163], v162
	s_waitcnt vmcnt(0)
	s_barrier
	s_waitcnt lgkmcnt(0)
	s_waitcnt lgkmcnt(0)
	v_mfma_f32_16x16x32_bf16 v[92:95], v[156:159], v[16:19], v[92:95]
	v_mfma_f32_16x16x32_bf16 v[16:19], v[228:231], v[16:19], v[148:151]
	v_mfma_f32_16x16x32_bf16 v[118:121], v[160:163], v[24:27], v[16:19]
	v_mfma_f32_16x16x32_bf16 v[16:19], v[156:159], v[32:35], v[84:87]
	v_mfma_f32_16x16x32_bf16 v[110:113], v[224:227], v[40:43], v[16:19]
	v_mfma_f32_16x16x32_bf16 v[16:19], v[228:231], v[32:35], v[180:183]
	v_mfma_f32_16x16x32_bf16 v[102:105], v[160:163], v[40:43], v[16:19]
	v_mfma_f32_16x16x32_bf16 v[16:19], v[156:159], v[48:51], v[76:79]
	v_mfma_f32_16x16x32_bf16 v[126:129], v[224:227], v[24:27], v[92:95]
	v_mfma_f32_16x16x32_bf16 v[92:95], v[224:227], v[56:59], v[16:19]
	v_mfma_f32_16x16x32_bf16 v[16:19], v[228:231], v[48:51], v[196:199]
	v_mfma_f32_16x16x32_bf16 v[84:87], v[160:163], v[56:59], v[16:19]
	v_mfma_f32_16x16x32_bf16 v[16:19], v[156:159], v[212:215], v[68:71]
	v_mfma_f32_16x16x32_bf16 v[76:79], v[224:227], v[216:219], v[16:19]
	v_mfma_f32_16x16x32_bf16 v[16:19], v[228:231], v[212:215], v[200:203]
	v_mfma_f32_16x16x32_bf16 v[68:71], v[160:163], v[216:219], v[16:19]
	s_barrier
	ds_read_b128 v[148:151], v144 offset:49152
	ds_read_b128 v[180:183], v144 offset:50176
	ds_read_b128 v[196:199], v144 offset:51200
	ds_read_b128 v[200:203], v144 offset:52224
	ds_read_b128 v[212:215], v144 offset:53248
	ds_read_b128 v[216:219], v144 offset:54272
	ds_read_b128 v[232:235], v144 offset:55296
	ds_read_b128 v[236:239], v144 offset:56320
	s_barrier
	s_waitcnt lgkmcnt(0)
	s_waitcnt lgkmcnt(0)
	v_mfma_f32_16x16x32_bf16 v[16:19], v[0:3], v[148:151], v[60:63]
	v_mfma_f32_16x16x32_bf16 v[56:59], v[8:11], v[180:183], v[16:19]
	v_mfma_f32_16x16x32_bf16 v[16:19], v[152:155], v[148:151], v[220:223]
	v_mfma_f32_16x16x32_bf16 v[48:51], v[208:211], v[180:183], v[16:19]
	v_mfma_f32_16x16x32_bf16 v[16:19], v[0:3], v[196:199], v[52:55]
	v_mfma_f32_16x16x32_bf16 v[40:43], v[8:11], v[200:203], v[16:19]
	v_mfma_f32_16x16x32_bf16 v[16:19], v[152:155], v[196:199], v[240:243]
	v_mfma_f32_16x16x32_bf16 v[32:35], v[208:211], v[200:203], v[16:19]
	v_mfma_f32_16x16x32_bf16 v[16:19], v[0:3], v[212:215], v[44:47]
	v_mfma_f32_16x16x32_bf16 v[0:3], v[0:3], v[232:235], v[36:39]
	v_mfma_f32_16x16x32_bf16 v[24:27], v[8:11], v[216:219], v[16:19]
	v_mfma_f32_16x16x32_bf16 v[16:19], v[152:155], v[212:215], v[244:247]
	v_mfma_f32_16x16x32_bf16 v[8:11], v[8:11], v[236:239], v[0:3]
	v_mfma_f32_16x16x32_bf16 v[0:3], v[152:155], v[232:235], v[164:167]
	v_mfma_f32_16x16x32_bf16 v[16:19], v[208:211], v[216:219], v[16:19]
	v_mfma_f32_16x16x32_bf16 v[0:3], v[208:211], v[236:239], v[0:3]
	v_mfma_f32_16x16x32_bf16 v[28:31], v[156:159], v[148:151], v[28:31]
	v_mfma_f32_16x16x32_bf16 v[60:63], v[224:227], v[180:183], v[28:31]
	v_mfma_f32_16x16x32_bf16 v[28:31], v[228:231], v[148:151], v[168:171]
	v_mfma_f32_16x16x32_bf16 v[20:23], v[156:159], v[196:199], v[20:23]
	v_mfma_f32_16x16x32_bf16 v[12:15], v[156:159], v[212:215], v[12:15]
	v_mfma_f32_16x16x32_bf16 v[52:55], v[160:163], v[180:183], v[28:31]
	v_mfma_f32_16x16x32_bf16 v[44:47], v[224:227], v[200:203], v[20:23]
	v_mfma_f32_16x16x32_bf16 v[20:23], v[228:231], v[196:199], v[172:175]
	v_mfma_f32_16x16x32_bf16 v[28:31], v[224:227], v[216:219], v[12:15]
	v_mfma_f32_16x16x32_bf16 v[12:15], v[228:231], v[212:215], v[176:179]
	v_mfma_f32_16x16x32_bf16 v[4:7], v[156:159], v[232:235], v[4:7]
	v_mfma_f32_16x16x32_bf16 v[36:39], v[160:163], v[200:203], v[20:23]
	v_mfma_f32_16x16x32_bf16 v[20:23], v[160:163], v[216:219], v[12:15]
	v_mfma_f32_16x16x32_bf16 v[12:15], v[224:227], v[236:239], v[4:7]
	v_mfma_f32_16x16x32_bf16 v[4:7], v[228:231], v[232:235], v[204:207]
	v_mfma_f32_16x16x32_bf16 v[4:7], v[160:163], v[236:239], v[4:7]
	s_andn2_b64 vcc, exec, s[14:15]
	s_barrier
	s_cbranch_vccnz .LBB0_133
	s_barrier

; #define WAIT_V(n) asm volatile("s_waitcnt vmcnt(%0)" ::"n"(n) : "memory")
; #define WAIT_L(n) asm volatile("s_waitcnt lgkmcnt(%0)" ::"n"(n) : "memory")
; #define SBAR() __builtin_amdgcn_sched_barrier(0)
; #define STAGE(P, base, kt) do { _Pragma("unroll") for (int _i = 0; _i < 2; ++_i)                                        \
;       __builtin_amdgcn_global_load_lds((const unsigned*)((base) + (size_t)(sOff[_i] + (unsigned)(kt) * (BK * 2))),        \
;                                        (unsigned*)((P) + wid * 1024 + _i * 8192), 16, 0, 0); } while (0)
; #define LDA(dst, b, h) _Pragma("unroll") for (int m = 0; m < 4; ++m) _Pragma("unroll") for (int k = 0; k < 2; ++k) \
;       dst[m][k] = *(const bf16x8*)(SA(b, h) + aoff + (m * 2048 + k * 1024))
; #define LDB(dst, b, h) _Pragma("unroll") for (int n = 0; n < 2; ++n) _Pragma("unroll") for (int k = 0; k < 2; ++k) \
;       dst[n][k] = *(const bf16x8*)(SB(b, h) + boff + (n * 256 + k * 1024))
; #define BAR __builtin_amdgcn_s_barrier()
; template <int EPI, int N, int K>
; __device__ __forceinline__ void phase_gemm(const Params& p, const u16* __restrict__ A, const u16* __restrict__ Bt, int nM, char* shm,
;                            u16* __restrict__ outp, float* __restrict__ rowss) {
;     ...
;     for (int t = 0; t < nt - 2; t += 2) {
;       LDB(B0, 0, 0); SBAR(); LDA(At, 0, 0); STAGE(SA(1, 1), A1, t + 1);
;       WAIT_L(8); BAR; WAIT_L(0); MMA(0, 0, At, B0); BAR; SBAR();
;       LDB(B1, 0, 1); STAGE(SB(0, 0), B0p, t + 2);
;       BAR; WAIT_L(0); MMA(0, 1, At, B1); BAR;
;       LDA(At, 0, 1); STAGE(SA(0, 0), A0, t + 2);
;       BAR; WAIT_L(0); MMA(1, 0, At, B0); BAR; SBAR();
;       STAGE(SB(0, 1), B1p, t + 2);
;       WAIT_V(6); BAR; MMA(1, 1, At, B1); BAR;
.LBB0_198:
	v_or_b32_e32 v143, 0x10000, v147
	v_add_u32_e32 v145, 0x10100, v147
	v_add_u32_e32 v144, 0x10400, v147
	ds_read_b128 v[156:159], v143
	ds_read_b128 v[160:163], v144
	v_add_u32_e32 v151, 0x10500, v147
	ds_read_b128 v[164:167], v145
	ds_read_b128 v[168:171], v151
	v_add_u32_e32 v240, v146, v96
	s_add_i32 s61, s5, 0xc000
	v_add_u32_e32 v152, 0x80, v240
	s_mov_b32 m0, s61
	v_add_u32_e32 v241, v146, v142
	s_add_i32 s60, s5, 0xe000
	ds_read_b128 v[172:175], v148
	ds_read_b128 v[176:179], v148 offset:1024
	ds_read_b128 v[180:183], v148 offset:2048
	ds_read_b128 v[196:199], v148 offset:3072
	ds_read_b128 v[200:203], v148 offset:4096
	ds_read_b128 v[204:207], v148 offset:5120
	ds_read_b128 v[208:211], v148 offset:6144
	ds_read_b128 v[212:215], v148 offset:7168
	global_load_lds_dwordx4 v152, s[6:7]
	v_add_u32_e32 v152, 0x80, v241
	s_mov_b32 m0, s60
	s_nop 0
	global_load_lds_dwordx4 v152, s[6:7]
	v_or_b32_e32 v152, 0x14000, v147
	v_add_u32_e32 v154, 0x14100, v147
	v_add_u32_e32 v153, 0x14400, v147
	ds_read_b128 v[216:219], v152
	ds_read_b128 v[220:223], v153
	v_add_u32_e32 v155, 0x14500, v147
	ds_read_b128 v[224:227], v154
	ds_read_b128 v[228:231], v155
	s_waitcnt vmcnt(8)
	s_waitcnt lgkmcnt(0)
	s_barrier
	v_mfma_f32_16x16x32_bf16 v[126:129], v[156:159], v[172:175], v[126:129]
	v_mfma_f32_16x16x32_bf16 v[122:125], v[164:167], v[172:175], v[122:125]
	v_mfma_f32_16x16x32_bf16 v[118:121], v[156:159], v[180:183], v[118:121]
	v_mfma_f32_16x16x32_bf16 v[114:117], v[164:167], v[180:183], v[114:117]
	v_mfma_f32_16x16x32_bf16 v[110:113], v[156:159], v[200:203], v[110:113]
	v_mfma_f32_16x16x32_bf16 v[106:109], v[164:167], v[200:203], v[106:109]
	v_mfma_f32_16x16x32_bf16 v[102:105], v[156:159], v[208:211], v[102:105]
	v_mfma_f32_16x16x32_bf16 v[98:101], v[164:167], v[208:211], v[98:101]
	v_mfma_f32_16x16x32_bf16 v[126:129], v[160:163], v[176:179], v[126:129]
	v_mfma_f32_16x16x32_bf16 v[122:125], v[168:171], v[176:179], v[122:125]
	v_mfma_f32_16x16x32_bf16 v[118:121], v[160:163], v[196:199], v[118:121]
	v_mfma_f32_16x16x32_bf16 v[114:117], v[168:171], v[196:199], v[114:117]
	v_mfma_f32_16x16x32_bf16 v[110:113], v[160:163], v[204:207], v[110:113]
	v_mfma_f32_16x16x32_bf16 v[106:109], v[168:171], v[204:207], v[106:109]
	v_mfma_f32_16x16x32_bf16 v[102:105], v[160:163], v[212:215], v[102:105]
	v_mfma_f32_16x16x32_bf16 v[98:101], v[168:171], v[212:215], v[98:101]
	v_mfma_f32_16x16x32_bf16 v[92:95], v[216:219], v[172:175], v[92:95]
	v_mfma_f32_16x16x32_bf16 v[88:91], v[224:227], v[172:175], v[88:91]
	v_mfma_f32_16x16x32_bf16 v[84:87], v[216:219], v[180:183], v[84:87]
	v_mfma_f32_16x16x32_bf16 v[80:83], v[224:227], v[180:183], v[80:83]
	v_mfma_f32_16x16x32_bf16 v[76:79], v[216:219], v[200:203], v[76:79]
	v_mfma_f32_16x16x32_bf16 v[72:75], v[224:227], v[200:203], v[72:75]
	v_mfma_f32_16x16x32_bf16 v[68:71], v[216:219], v[208:211], v[68:71]
	v_mfma_f32_16x16x32_bf16 v[64:67], v[224:227], v[208:211], v[64:67]
	v_mfma_f32_16x16x32_bf16 v[92:95], v[220:223], v[176:179], v[92:95]
	v_mfma_f32_16x16x32_bf16 v[88:91], v[228:231], v[176:179], v[88:91]
	v_mfma_f32_16x16x32_bf16 v[84:87], v[220:223], v[196:199], v[84:87]
	v_mfma_f32_16x16x32_bf16 v[80:83], v[228:231], v[196:199], v[80:83]
	v_mfma_f32_16x16x32_bf16 v[76:79], v[220:223], v[204:207], v[76:79]
	v_mfma_f32_16x16x32_bf16 v[72:75], v[228:231], v[204:207], v[72:75]
	v_mfma_f32_16x16x32_bf16 v[68:71], v[220:223], v[212:215], v[68:71]
	v_mfma_f32_16x16x32_bf16 v[64:67], v[228:231], v[212:215], v[64:67]
	s_barrier
	ds_read_b128 v[172:175], v148 offset:16384
	ds_read_b128 v[176:179], v148 offset:17408
	ds_read_b128 v[180:183], v148 offset:18432
	ds_read_b128 v[196:199], v148 offset:19456
	ds_read_b128 v[200:203], v148 offset:20480
	ds_read_b128 v[204:207], v148 offset:21504
	ds_read_b128 v[208:211], v148 offset:22528
	ds_read_b128 v[212:215], v148 offset:23552
	s_mov_b32 m0, s26
	v_add_u32_e32 v232, 0x100, v240
	global_load_lds_dwordx4 v232, s[12:13]
	v_add_u32_e32 v233, 0x100, v241
	s_mov_b32 m0, s27
	s_nop 0
	global_load_lds_dwordx4 v233, s[12:13]
	s_mov_b32 m0, s5
	s_nop 0
	global_load_lds_dwordx4 v232, s[14:15]
	s_mov_b32 m0, s24
	s_nop 0
	global_load_lds_dwordx4 v233, s[14:15]
	s_mov_b32 m0, s28
	s_nop 0
	global_load_lds_dwordx4 v232, s[22:23]
	s_mov_b32 m0, s29
	s_nop 0
	global_load_lds_dwordx4 v233, s[22:23]
	s_waitcnt vmcnt(8)
	s_waitcnt lgkmcnt(0)
	s_barrier
	v_mfma_f32_16x16x32_bf16 v[60:63], v[156:159], v[172:175], v[60:63]
	v_mfma_f32_16x16x32_bf16 v[56:59], v[164:167], v[172:175], v[56:59]
	v_mfma_f32_16x16x32_bf16 v[52:55], v[156:159], v[180:183], v[52:55]
	v_mfma_f32_16x16x32_bf16 v[48:51], v[164:167], v[180:183], v[48:51]
	v_mfma_f32_16x16x32_bf16 v[44:47], v[156:159], v[200:203], v[44:47]
	v_mfma_f32_16x16x32_bf16 v[40:43], v[164:167], v[200:203], v[40:43]
	v_mfma_f32_16x16x32_bf16 v[36:39], v[156:159], v[208:211], v[36:39]
	v_mfma_f32_16x16x32_bf16 v[32:35], v[164:167], v[208:211], v[32:35]
	v_mfma_f32_16x16x32_bf16 v[60:63], v[160:163], v[176:179], v[60:63]
	v_mfma_f32_16x16x32_bf16 v[56:59], v[168:171], v[176:179], v[56:59]
	v_mfma_f32_16x16x32_bf16 v[52:55], v[160:163], v[196:199], v[52:55]
	v_mfma_f32_16x16x32_bf16 v[48:51], v[168:171], v[196:199], v[48:51]
	v_mfma_f32_16x16x32_bf16 v[44:47], v[160:163], v[204:207], v[44:47]
	v_mfma_f32_16x16x32_bf16 v[40:43], v[168:171], v[204:207], v[40:43]
	v_mfma_f32_16x16x32_bf16 v[36:39], v[160:163], v[212:215], v[36:39]
	v_mfma_f32_16x16x32_bf16 v[32:35], v[168:171], v[212:215], v[32:35]
	v_mfma_f32_16x16x32_bf16 v[28:31], v[216:219], v[172:175], v[28:31]
	v_mfma_f32_16x16x32_bf16 v[24:27], v[224:227], v[172:175], v[24:27]
	v_mfma_f32_16x16x32_bf16 v[20:23], v[216:219], v[180:183], v[20:23]
	v_mfma_f32_16x16x32_bf16 v[16:19], v[224:227], v[180:183], v[16:19]
	v_mfma_f32_16x16x32_bf16 v[12:15], v[216:219], v[200:203], v[12:15]
	v_mfma_f32_16x16x32_bf16 v[8:11], v[224:227], v[200:203], v[8:11]
	v_mfma_f32_16x16x32_bf16 v[4:7], v[216:219], v[208:211], v[4:7]
	v_mfma_f32_16x16x32_bf16 v[0:3], v[224:227], v[208:211], v[0:3]
	v_mfma_f32_16x16x32_bf16 v[28:31], v[220:223], v[176:179], v[28:31]
	v_mfma_f32_16x16x32_bf16 v[24:27], v[228:231], v[176:179], v[24:27]
	v_mfma_f32_16x16x32_bf16 v[20:23], v[220:223], v[196:199], v[20:23]
	v_mfma_f32_16x16x32_bf16 v[16:19], v[228:231], v[196:199], v[16:19]
	v_mfma_f32_16x16x32_bf16 v[12:15], v[220:223], v[204:207], v[12:15]
	v_mfma_f32_16x16x32_bf16 v[8:11], v[228:231], v[204:207], v[8:11]
	v_mfma_f32_16x16x32_bf16 v[4:7], v[220:223], v[212:215], v[4:7]
	v_mfma_f32_16x16x32_bf16 v[0:3], v[228:231], v[212:215], v[0:3]
	v_or_b32_e32 v156, 0x18000, v147
	v_add_u32_e32 v158, 0x18100, v147
	s_barrier
; #define WAIT_V(n) asm volatile("s_waitcnt vmcnt(%0)" ::"n"(n) : "memory")
; #define WAIT_L(n) asm volatile("s_waitcnt lgkmcnt(%0)" ::"n"(n) : "memory")
; #define SBAR() __builtin_amdgcn_sched_barrier(0)
; #define STAGE(P, base, kt) do { _Pragma("unroll") for (int _i = 0; _i < 2; ++_i)                                        \
;       __builtin_amdgcn_global_load_lds((const unsigned*)((base) + (size_t)(sOff[_i] + (unsigned)(kt) * (BK * 2))),        \
;                                        (unsigned*)((P) + wid * 1024 + _i * 8192), 16, 0, 0); } while (0)
; #define LDA(dst, b, h) _Pragma("unroll") for (int m = 0; m < 4; ++m) _Pragma("unroll") for (int k = 0; k < 2; ++k) \
;       dst[m][k] = *(const bf16x8*)(SA(b, h) + aoff + (m * 2048 + k * 1024))
; #define LDB(dst, b, h) _Pragma("unroll") for (int n = 0; n < 2; ++n) _Pragma("unroll") for (int k = 0; k < 2; ++k) \
;       dst[n][k] = *(const bf16x8*)(SB(b, h) + boff + (n * 256 + k * 1024))
; #define BAR __builtin_amdgcn_s_barrier()
; template <int EPI, int N, int K>
; __device__ __forceinline__ void phase_gemm(const Params& p, const u16* __restrict__ A, const u16* __restrict__ Bt, int nM, char* shm,
;                            u16* __restrict__ outp, float* __restrict__ rowss) {
;     ...
;       LDB(B0, 1, 0); SBAR(); LDA(At, 1, 0); STAGE(SA(0, 1), A1, t + 2);
;       WAIT_L(8); BAR; WAIT_L(0); MMA(0, 0, At, B0); BAR; SBAR();
;       LDB(B1, 1, 1); STAGE(SB(1, 0), B0p, t + 3);
;       BAR; WAIT_L(0); MMA(0, 1, At, B1); BAR;
;       LDA(At, 1, 1); STAGE(SA(1, 0), A0, t + 3);
;       BAR; WAIT_L(0); MMA(1, 0, At, B0); BAR; SBAR();
;       STAGE(SB(1, 1), B1p, t + 3);
;       WAIT_V(6); BAR; MMA(1, 1, At, B1); BAR;
;     }
	v_add_u32_e32 v157, 0x18400, v147
	ds_read_b128 v[164:167], v156
	ds_read_b128 v[168:171], v157
	v_add_u32_e32 v159, 0x18500, v147
	ds_read_b128 v[172:175], v158
	ds_read_b128 v[176:179], v159
	s_mov_b32 m0, s30
	ds_read_b128 v[180:183], v148 offset:32768
	ds_read_b128 v[196:199], v148 offset:33792
	ds_read_b128 v[200:203], v148 offset:34816
	ds_read_b128 v[204:207], v148 offset:35840
	ds_read_b128 v[208:211], v148 offset:36864
	ds_read_b128 v[212:215], v148 offset:37888
	ds_read_b128 v[216:219], v148 offset:38912
	ds_read_b128 v[220:223], v148 offset:39936
	global_load_lds_dwordx4 v232, s[6:7]
	s_mov_b32 m0, s31
	s_nop 0
	global_load_lds_dwordx4 v233, s[6:7]
	v_or_b32_e32 v160, 0x1c000, v147
	v_add_u32_e32 v162, 0x1c100, v147
	v_add_u32_e32 v161, 0x1c400, v147
	ds_read_b128 v[224:227], v160
	ds_read_b128 v[228:231], v161
	v_add_u32_e32 v163, 0x1c500, v147
	ds_read_b128 v[232:235], v162
	ds_read_b128 v[236:239], v163
	s_waitcnt vmcnt(8)
	s_waitcnt lgkmcnt(0)
	s_barrier
	v_mfma_f32_16x16x32_bf16 v[126:129], v[164:167], v[180:183], v[126:129]
	v_mfma_f32_16x16x32_bf16 v[122:125], v[172:175], v[180:183], v[122:125]
	v_mfma_f32_16x16x32_bf16 v[118:121], v[164:167], v[200:203], v[118:121]
	v_mfma_f32_16x16x32_bf16 v[114:117], v[172:175], v[200:203], v[114:117]
	v_mfma_f32_16x16x32_bf16 v[110:113], v[164:167], v[208:211], v[110:113]
	v_mfma_f32_16x16x32_bf16 v[106:109], v[172:175], v[208:211], v[106:109]
	v_mfma_f32_16x16x32_bf16 v[102:105], v[164:167], v[216:219], v[102:105]
	v_mfma_f32_16x16x32_bf16 v[98:101], v[172:175], v[216:219], v[98:101]
	v_mfma_f32_16x16x32_bf16 v[126:129], v[168:171], v[196:199], v[126:129]
	v_mfma_f32_16x16x32_bf16 v[122:125], v[176:179], v[196:199], v[122:125]
	v_mfma_f32_16x16x32_bf16 v[118:121], v[168:171], v[204:207], v[118:121]
	v_mfma_f32_16x16x32_bf16 v[114:117], v[176:179], v[204:207], v[114:117]
	v_mfma_f32_16x16x32_bf16 v[110:113], v[168:171], v[212:215], v[110:113]
	v_mfma_f32_16x16x32_bf16 v[106:109], v[176:179], v[212:215], v[106:109]
	v_mfma_f32_16x16x32_bf16 v[102:105], v[168:171], v[220:223], v[102:105]
	v_mfma_f32_16x16x32_bf16 v[98:101], v[176:179], v[220:223], v[98:101]
	v_mfma_f32_16x16x32_bf16 v[92:95], v[224:227], v[180:183], v[92:95]
	v_mfma_f32_16x16x32_bf16 v[88:91], v[232:235], v[180:183], v[88:91]
	v_mfma_f32_16x16x32_bf16 v[84:87], v[224:227], v[200:203], v[84:87]
	v_mfma_f32_16x16x32_bf16 v[80:83], v[232:235], v[200:203], v[80:83]
	v_mfma_f32_16x16x32_bf16 v[76:79], v[224:227], v[208:211], v[76:79]
	v_mfma_f32_16x16x32_bf16 v[72:75], v[232:235], v[208:211], v[72:75]
	v_mfma_f32_16x16x32_bf16 v[68:71], v[224:227], v[216:219], v[68:71]
	v_mfma_f32_16x16x32_bf16 v[64:67], v[232:235], v[216:219], v[64:67]
	v_mfma_f32_16x16x32_bf16 v[92:95], v[228:231], v[196:199], v[92:95]
	v_mfma_f32_16x16x32_bf16 v[88:91], v[236:239], v[196:199], v[88:91]
	v_mfma_f32_16x16x32_bf16 v[84:87], v[228:231], v[204:207], v[84:87]
	v_mfma_f32_16x16x32_bf16 v[80:83], v[236:239], v[204:207], v[80:83]
	v_mfma_f32_16x16x32_bf16 v[76:79], v[228:231], v[212:215], v[76:79]
	v_mfma_f32_16x16x32_bf16 v[72:75], v[236:239], v[212:215], v[72:75]
	v_mfma_f32_16x16x32_bf16 v[68:71], v[228:231], v[220:223], v[68:71]
	v_mfma_f32_16x16x32_bf16 v[64:67], v[236:239], v[220:223], v[64:67]
	s_barrier
	ds_read_b128 v[180:183], v148 offset:49152
	ds_read_b128 v[196:199], v148 offset:50176
	ds_read_b128 v[200:203], v148 offset:51200
	ds_read_b128 v[204:207], v148 offset:52224
	ds_read_b128 v[208:211], v148 offset:53248
	ds_read_b128 v[212:215], v148 offset:54272
	ds_read_b128 v[216:219], v148 offset:55296
	ds_read_b128 v[220:223], v148 offset:56320
	s_mov_b32 m0, s33
	v_add_u32_e32 v240, 0x180, v240
	global_load_lds_dwordx4 v240, s[12:13]
	v_add_u32_e32 v241, 0x180, v241
	s_mov_b32 m0, s35
	s_nop 0
	global_load_lds_dwordx4 v241, s[12:13]
	s_mov_b32 m0, s92
	s_nop 0
	global_load_lds_dwordx4 v240, s[14:15]
	s_mov_b32 m0, s93
	s_nop 0
	global_load_lds_dwordx4 v241, s[14:15]
	s_mov_b32 m0, s52
	s_nop 0
	global_load_lds_dwordx4 v240, s[22:23]
	s_mov_b32 m0, s53
	s_nop 0
	global_load_lds_dwordx4 v241, s[22:23]
	s_waitcnt vmcnt(8)
	s_waitcnt lgkmcnt(0)
	s_barrier
	v_mfma_f32_16x16x32_bf16 v[60:63], v[164:167], v[180:183], v[60:63]
	v_mfma_f32_16x16x32_bf16 v[56:59], v[172:175], v[180:183], v[56:59]
	v_mfma_f32_16x16x32_bf16 v[52:55], v[164:167], v[200:203], v[52:55]
	v_mfma_f32_16x16x32_bf16 v[48:51], v[172:175], v[200:203], v[48:51]
	v_mfma_f32_16x16x32_bf16 v[44:47], v[164:167], v[208:211], v[44:47]
	v_mfma_f32_16x16x32_bf16 v[40:43], v[172:175], v[208:211], v[40:43]
	v_mfma_f32_16x16x32_bf16 v[36:39], v[164:167], v[216:219], v[36:39]
	v_mfma_f32_16x16x32_bf16 v[32:35], v[172:175], v[216:219], v[32:35]
	v_mfma_f32_16x16x32_bf16 v[60:63], v[168:171], v[196:199], v[60:63]
	v_mfma_f32_16x16x32_bf16 v[56:59], v[176:179], v[196:199], v[56:59]
	v_mfma_f32_16x16x32_bf16 v[52:55], v[168:171], v[204:207], v[52:55]
	v_mfma_f32_16x16x32_bf16 v[48:51], v[176:179], v[204:207], v[48:51]
	v_mfma_f32_16x16x32_bf16 v[44:47], v[168:171], v[212:215], v[44:47]
	v_mfma_f32_16x16x32_bf16 v[40:43], v[176:179], v[212:215], v[40:43]
	v_mfma_f32_16x16x32_bf16 v[36:39], v[168:171], v[220:223], v[36:39]
	v_mfma_f32_16x16x32_bf16 v[32:35], v[176:179], v[220:223], v[32:35]
	v_mfma_f32_16x16x32_bf16 v[28:31], v[224:227], v[180:183], v[28:31]
	v_mfma_f32_16x16x32_bf16 v[24:27], v[232:235], v[180:183], v[24:27]
	v_mfma_f32_16x16x32_bf16 v[20:23], v[224:227], v[200:203], v[20:23]
	v_mfma_f32_16x16x32_bf16 v[16:19], v[232:235], v[200:203], v[16:19]
	v_mfma_f32_16x16x32_bf16 v[12:15], v[224:227], v[208:211], v[12:15]
	v_mfma_f32_16x16x32_bf16 v[8:11], v[232:235], v[208:211], v[8:11]
	v_mfma_f32_16x16x32_bf16 v[4:7], v[224:227], v[216:219], v[4:7]
	v_mfma_f32_16x16x32_bf16 v[0:3], v[232:235], v[216:219], v[0:3]
	v_mfma_f32_16x16x32_bf16 v[28:31], v[228:231], v[196:199], v[28:31]
	v_mfma_f32_16x16x32_bf16 v[24:27], v[236:239], v[196:199], v[24:27]
	v_mfma_f32_16x16x32_bf16 v[20:23], v[228:231], v[204:207], v[20:23]
	v_mfma_f32_16x16x32_bf16 v[16:19], v[236:239], v[204:207], v[16:19]
	v_mfma_f32_16x16x32_bf16 v[12:15], v[228:231], v[212:215], v[12:15]
	v_mfma_f32_16x16x32_bf16 v[8:11], v[236:239], v[212:215], v[8:11]
	v_mfma_f32_16x16x32_bf16 v[4:7], v[228:231], v[220:223], v[4:7]
	v_mfma_f32_16x16x32_bf16 v[0:3], v[236:239], v[220:223], v[0:3]
	s_add_i32 s59, s59, 2
	v_add_u32_e32 v142, 0x100, v142
	s_cmp_lt_u32 s59, 12
	v_add_u32_e32 v96, 0x100, v96
	s_barrier
; #define WAIT_V(n) asm volatile("s_waitcnt vmcnt(%0)" ::"n"(n) : "memory")
; #define WAIT_L(n) asm volatile("s_waitcnt lgkmcnt(%0)" ::"n"(n) : "memory")
; #define STAGE(P, base, kt) do { _Pragma("unroll") for (int _i = 0; _i < 2; ++_i)                                        \
;       __builtin_amdgcn_global_load_lds((const unsigned*)((base) + (size_t)(sOff[_i] + (unsigned)(kt) * (BK * 2))),        \
;                                        (unsigned*)((P) + wid * 1024 + _i * 8192), 16, 0, 0); } while (0)
; #define LDA(dst, b, h) _Pragma("unroll") for (int m = 0; m < 4; ++m) _Pragma("unroll") for (int k = 0; k < 2; ++k) \
;       dst[m][k] = *(const bf16x8*)(SA(b, h) + aoff + (m * 2048 + k * 1024))
; #define LDB(dst, b, h) _Pragma("unroll") for (int n = 0; n < 2; ++n) _Pragma("unroll") for (int k = 0; k < 2; ++k) \
;       dst[n][k] = *(const bf16x8*)(SB(b, h) + boff + (n * 256 + k * 1024))
; #define BAR __builtin_amdgcn_s_barrier()
; template <int EPI, int N, int K>
; __device__ __forceinline__ void phase_gemm(const Params& p, const u16* __restrict__ A, const u16* __restrict__ Bt, int nM, char* shm,
;                            u16* __restrict__ outp, float* __restrict__ rowss) {
;     ...
;     { LDB(B0, 0, 0); LDA(At, 0, 0); STAGE(SA(1, 1), A1, nt - 1);
;       BAR; WAIT_L(0); MMA(0, 0, At, B0); BAR;
;       LDB(B1, 0, 1); BAR; WAIT_L(0); MMA(0, 1, At, B1); BAR;
;       LDA(At, 0, 1); WAIT_V(4); BAR; WAIT_L(0); MMA(1, 0, At, B0); MMA(1, 1, At, B1); BAR; }
	s_cbranch_scc1 .LBB0_198
	s_waitcnt vmcnt(6)
	s_mov_b32 m0, s61
	v_lshl_add_u64 v[220:221], s[6:7], 0, v[138:139]
	ds_read_b128 v[164:167], v143
	ds_read_b128 v[168:171], v144
	ds_read_b128 v[142:145], v145
	ds_read_b128 v[172:175], v151
	ds_read_b128 v[176:179], v148
	ds_read_b128 v[180:183], v148 offset:1024
	ds_read_b128 v[196:199], v148 offset:2048
	ds_read_b128 v[200:203], v148 offset:3072
	ds_read_b128 v[204:207], v148 offset:4096
	ds_read_b128 v[208:211], v148 offset:5120
	ds_read_b128 v[212:215], v148 offset:6144
	ds_read_b128 v[216:219], v148 offset:7168
	global_load_lds_dwordx4 v[220:221], off
	v_lshl_add_u64 v[220:221], s[6:7], 0, v[140:141]
	s_mov_b32 m0, s60
	s_nop 0
	global_load_lds_dwordx4 v[220:221], off
	s_barrier
	s_waitcnt lgkmcnt(0)
	s_waitcnt lgkmcnt(0)
	v_mfma_f32_16x16x32_bf16 v[126:129], v[164:167], v[176:179], v[126:129]
	v_mfma_f32_16x16x32_bf16 v[122:125], v[142:145], v[176:179], v[122:125]
	v_mfma_f32_16x16x32_bf16 v[118:121], v[164:167], v[196:199], v[118:121]
	v_mfma_f32_16x16x32_bf16 v[102:105], v[164:167], v[212:215], v[102:105]
	v_mfma_f32_16x16x32_bf16 v[98:101], v[142:145], v[212:215], v[98:101]
	v_mfma_f32_16x16x32_bf16 v[126:129], v[168:171], v[180:183], v[126:129]
	v_mfma_f32_16x16x32_bf16 v[122:125], v[172:175], v[180:183], v[122:125]
	v_mfma_f32_16x16x32_bf16 v[118:121], v[168:171], v[200:203], v[118:121]
	v_mfma_f32_16x16x32_bf16 v[114:117], v[142:145], v[196:199], v[114:117]
	v_mfma_f32_16x16x32_bf16 v[110:113], v[164:167], v[204:207], v[110:113]
	v_mfma_f32_16x16x32_bf16 v[106:109], v[142:145], v[204:207], v[106:109]
	v_mfma_f32_16x16x32_bf16 v[102:105], v[168:171], v[216:219], v[102:105]
	v_mfma_f32_16x16x32_bf16 v[98:101], v[172:175], v[216:219], v[98:101]
	v_mfma_f32_16x16x32_bf16 v[220:223], v[172:175], v[200:203], v[114:117]
	v_mfma_f32_16x16x32_bf16 v[224:227], v[168:171], v[208:211], v[110:113]
	v_mfma_f32_16x16x32_bf16 v[228:231], v[172:175], v[208:211], v[106:109]
	s_barrier
	s_nop 0
	ds_read_b128 v[106:109], v152
	ds_read_b128 v[110:113], v153
	ds_read_b128 v[114:117], v154
	ds_read_b128 v[152:155], v155
	s_barrier
	s_waitcnt lgkmcnt(0)
	s_waitcnt lgkmcnt(0)
	v_mfma_f32_16x16x32_bf16 v[84:87], v[106:109], v[196:199], v[84:87]
	v_mfma_f32_16x16x32_bf16 v[80:83], v[114:117], v[196:199], v[80:83]
	v_mfma_f32_16x16x32_bf16 v[68:71], v[106:109], v[212:215], v[68:71]
	v_mfma_f32_16x16x32_bf16 v[92:95], v[106:109], v[176:179], v[92:95]
	v_mfma_f32_16x16x32_bf16 v[88:91], v[114:117], v[176:179], v[88:91]
	v_mfma_f32_16x16x32_bf16 v[84:87], v[110:113], v[200:203], v[84:87]
	v_mfma_f32_16x16x32_bf16 v[80:83], v[152:155], v[200:203], v[80:83]
	v_mfma_f32_16x16x32_bf16 v[76:79], v[106:109], v[204:207], v[76:79]
	v_mfma_f32_16x16x32_bf16 v[72:75], v[114:117], v[204:207], v[72:75]
	v_mfma_f32_16x16x32_bf16 v[68:71], v[110:113], v[216:219], v[68:71]
	v_mfma_f32_16x16x32_bf16 v[64:67], v[114:117], v[212:215], v[64:67]
	v_mfma_f32_16x16x32_bf16 v[232:235], v[110:113], v[180:183], v[92:95]
	v_mfma_f32_16x16x32_bf16 v[176:179], v[152:155], v[180:183], v[88:91]
	v_mfma_f32_16x16x32_bf16 v[180:183], v[110:113], v[208:211], v[76:79]
	v_mfma_f32_16x16x32_bf16 v[196:199], v[152:155], v[208:211], v[72:75]
	v_mfma_f32_16x16x32_bf16 v[200:203], v[152:155], v[216:219], v[64:67]
	s_barrier
	s_nop 0
	ds_read_b128 v[64:67], v148 offset:16384
	ds_read_b128 v[72:75], v148 offset:17408
	ds_read_b128 v[76:79], v148 offset:18432
	ds_read_b128 v[88:91], v148 offset:19456
	ds_read_b128 v[92:95], v148 offset:20480
	ds_read_b128 v[204:207], v148 offset:21504
	ds_read_b128 v[208:211], v148 offset:22528
	ds_read_b128 v[212:215], v148 offset:23552
	s_waitcnt vmcnt(4)
	s_barrier
	s_waitcnt lgkmcnt(0)
	s_waitcnt lgkmcnt(0)
	v_mfma_f32_16x16x32_bf16 v[60:63], v[164:167], v[64:67], v[60:63]
	v_mfma_f32_16x16x32_bf16 v[52:55], v[164:167], v[76:79], v[52:55]
	v_mfma_f32_16x16x32_bf16 v[48:51], v[142:145], v[76:79], v[48:51]
	v_mfma_f32_16x16x32_bf16 v[36:39], v[164:167], v[208:211], v[36:39]
	v_mfma_f32_16x16x32_bf16 v[32:35], v[142:145], v[208:211], v[32:35]
	v_mfma_f32_16x16x32_bf16 v[60:63], v[168:171], v[72:75], v[60:63]
	v_mfma_f32_16x16x32_bf16 v[56:59], v[142:145], v[64:67], v[56:59]
	v_mfma_f32_16x16x32_bf16 v[52:55], v[168:171], v[88:91], v[52:55]
	v_mfma_f32_16x16x32_bf16 v[48:51], v[172:175], v[88:91], v[48:51]
	v_mfma_f32_16x16x32_bf16 v[44:47], v[164:167], v[92:95], v[44:47]
	v_mfma_f32_16x16x32_bf16 v[40:43], v[142:145], v[92:95], v[40:43]
	v_mfma_f32_16x16x32_bf16 v[36:39], v[168:171], v[212:215], v[36:39]
	v_mfma_f32_16x16x32_bf16 v[32:35], v[172:175], v[212:215], v[32:35]
	v_mfma_f32_16x16x32_bf16 v[216:219], v[172:175], v[72:75], v[56:59]
	v_mfma_f32_16x16x32_bf16 v[236:239], v[168:171], v[204:207], v[44:47]
	v_mfma_f32_16x16x32_bf16 v[240:243], v[172:175], v[204:207], v[40:43]
	v_mfma_f32_16x16x32_bf16 v[20:23], v[106:109], v[76:79], v[20:23]
	v_mfma_f32_16x16x32_bf16 v[16:19], v[114:117], v[76:79], v[16:19]
	v_mfma_f32_16x16x32_bf16 v[4:7], v[106:109], v[208:211], v[4:7]
	v_mfma_f32_16x16x32_bf16 v[28:31], v[106:109], v[64:67], v[28:31]
	v_mfma_f32_16x16x32_bf16 v[24:27], v[114:117], v[64:67], v[24:27]
	v_mfma_f32_16x16x32_bf16 v[20:23], v[110:113], v[88:91], v[20:23]
	v_mfma_f32_16x16x32_bf16 v[16:19], v[152:155], v[88:91], v[16:19]
	v_mfma_f32_16x16x32_bf16 v[12:15], v[106:109], v[92:95], v[12:15]
	v_mfma_f32_16x16x32_bf16 v[8:11], v[114:117], v[92:95], v[8:11]
	v_mfma_f32_16x16x32_bf16 v[4:7], v[110:113], v[212:215], v[4:7]
	v_mfma_f32_16x16x32_bf16 v[0:3], v[114:117], v[208:211], v[0:3]
	v_mfma_f32_16x16x32_bf16 v[142:145], v[110:113], v[72:75], v[28:31]
	v_mfma_f32_16x16x32_bf16 v[164:167], v[152:155], v[72:75], v[24:27]
	v_mfma_f32_16x16x32_bf16 v[168:171], v[110:113], v[204:207], v[12:15]
	v_mfma_f32_16x16x32_bf16 v[172:175], v[152:155], v[204:207], v[8:11]
	v_mfma_f32_16x16x32_bf16 v[152:155], v[152:155], v[212:215], v[0:3]
	s_barrier
; #define WAIT_V(n) asm volatile("s_waitcnt vmcnt(%0)" ::"n"(n) : "memory")
; #define WAIT_L(n) asm volatile("s_waitcnt lgkmcnt(%0)" ::"n"(n) : "memory")
; #define LDA(dst, b, h) _Pragma("unroll") for (int m = 0; m < 4; ++m) _Pragma("unroll") for (int k = 0; k < 2; ++k) \
;       dst[m][k] = *(const bf16x8*)(SA(b, h) + aoff + (m * 2048 + k * 1024))
; #define LDB(dst, b, h) _Pragma("unroll") for (int n = 0; n < 2; ++n) _Pragma("unroll") for (int k = 0; k < 2; ++k) \
;       dst[n][k] = *(const bf16x8*)(SB(b, h) + boff + (n * 256 + k * 1024))
; #define BAR __builtin_amdgcn_s_barrier()
; template <int EPI, int N, int K>
; __device__ __forceinline__ void phase_gemm(const Params& p, const u16* __restrict__ A, const u16* __restrict__ Bt, int nM, char* shm,
;                            u16* __restrict__ outp, float* __restrict__ rowss) {
;     ...
;     { LDB(B0, 1, 0); LDA(At, 1, 0); WAIT_V(2); BAR; WAIT_L(0); MMA(0, 0, At, B0); BAR;
;       LDB(B1, 1, 1); WAIT_V(0); BAR; WAIT_L(0); MMA(0, 1, At, B1); BAR;
;       LDA(At, 1, 1); BAR; WAIT_L(0); MMA(1, 0, At, B0); MMA(1, 1, At, B1); BAR; }
;     if (wr == 0) BAR;
	s_nop 0
	ds_read_b128 v[0:3], v156
	ds_read_b128 v[8:11], v157
	ds_read_b128 v[12:15], v158
	ds_read_b128 v[156:159], v159
	ds_read_b128 v[24:27], v148 offset:32768
	ds_read_b128 v[28:31], v148 offset:33792
	ds_read_b128 v[40:43], v148 offset:34816
	ds_read_b128 v[44:47], v148 offset:35840
	ds_read_b128 v[56:59], v148 offset:36864
	ds_read_b128 v[64:67], v148 offset:37888
	ds_read_b128 v[204:207], v148 offset:38912
	ds_read_b128 v[208:211], v148 offset:39936
	s_waitcnt vmcnt(2)
	s_barrier
	s_waitcnt lgkmcnt(0)
	s_waitcnt lgkmcnt(0)
	v_mfma_f32_16x16x32_bf16 v[72:75], v[0:3], v[24:27], v[126:129]
	v_mfma_f32_16x16x32_bf16 v[126:129], v[8:11], v[28:31], v[72:75]
	v_mfma_f32_16x16x32_bf16 v[72:75], v[12:15], v[24:27], v[122:125]
	v_mfma_f32_16x16x32_bf16 v[114:117], v[156:159], v[28:31], v[72:75]
	v_mfma_f32_16x16x32_bf16 v[72:75], v[0:3], v[40:43], v[118:121]
	v_mfma_f32_16x16x32_bf16 v[106:109], v[8:11], v[44:47], v[72:75]
	v_mfma_f32_16x16x32_bf16 v[72:75], v[12:15], v[40:43], v[220:223]
	v_mfma_f32_16x16x32_bf16 v[110:113], v[156:159], v[44:47], v[72:75]
	v_mfma_f32_16x16x32_bf16 v[72:75], v[0:3], v[56:59], v[224:227]
	v_mfma_f32_16x16x32_bf16 v[88:91], v[8:11], v[64:67], v[72:75]
	v_mfma_f32_16x16x32_bf16 v[72:75], v[12:15], v[56:59], v[228:231]
	v_mfma_f32_16x16x32_bf16 v[92:95], v[156:159], v[64:67], v[72:75]
	v_mfma_f32_16x16x32_bf16 v[72:75], v[0:3], v[204:207], v[102:105]
	v_mfma_f32_16x16x32_bf16 v[76:79], v[12:15], v[204:207], v[98:101]
	v_mfma_f32_16x16x32_bf16 v[72:75], v[8:11], v[208:211], v[72:75]
	v_mfma_f32_16x16x32_bf16 v[76:79], v[156:159], v[208:211], v[76:79]
	s_barrier
	ds_read_b128 v[212:215], v160
	ds_read_b128 v[220:223], v161
	ds_read_b128 v[224:227], v162
	ds_read_b128 v[160:163], v163
	s_waitcnt vmcnt(0)
	s_barrier
	s_waitcnt lgkmcnt(0)
	s_waitcnt lgkmcnt(0)
	v_mfma_f32_16x16x32_bf16 v[98:101], v[212:215], v[24:27], v[232:235]
	v_mfma_f32_16x16x32_bf16 v[24:27], v[224:227], v[24:27], v[176:179]
	v_mfma_f32_16x16x32_bf16 v[122:125], v[160:163], v[28:31], v[24:27]
	v_mfma_f32_16x16x32_bf16 v[24:27], v[212:215], v[40:43], v[84:87]
	v_mfma_f32_16x16x32_bf16 v[118:121], v[220:223], v[28:31], v[98:101]
	v_mfma_f32_16x16x32_bf16 v[98:101], v[220:223], v[44:47], v[24:27]
	v_mfma_f32_16x16x32_bf16 v[24:27], v[224:227], v[40:43], v[80:83]
	v_mfma_f32_16x16x32_bf16 v[102:105], v[160:163], v[44:47], v[24:27]
	v_mfma_f32_16x16x32_bf16 v[24:27], v[212:215], v[56:59], v[180:183]
	v_mfma_f32_16x16x32_bf16 v[80:83], v[220:223], v[64:67], v[24:27]
	v_mfma_f32_16x16x32_bf16 v[24:27], v[224:227], v[56:59], v[196:199]
	v_mfma_f32_16x16x32_bf16 v[84:87], v[160:163], v[64:67], v[24:27]
	v_mfma_f32_16x16x32_bf16 v[24:27], v[212:215], v[204:207], v[68:71]
	v_mfma_f32_16x16x32_bf16 v[64:67], v[220:223], v[208:211], v[24:27]
	v_mfma_f32_16x16x32_bf16 v[24:27], v[224:227], v[204:207], v[200:203]
	v_mfma_f32_16x16x32_bf16 v[68:71], v[160:163], v[208:211], v[24:27]
	s_barrier
	ds_read_b128 v[176:179], v148 offset:49152
	ds_read_b128 v[180:183], v148 offset:50176
	ds_read_b128 v[196:199], v148 offset:51200
	ds_read_b128 v[200:203], v148 offset:52224
	ds_read_b128 v[204:207], v148 offset:53248
	ds_read_b128 v[208:211], v148 offset:54272
	ds_read_b128 v[228:231], v148 offset:55296
	ds_read_b128 v[232:235], v148 offset:56320
	s_barrier
	s_waitcnt lgkmcnt(0)
	s_waitcnt lgkmcnt(0)
	v_mfma_f32_16x16x32_bf16 v[24:27], v[0:3], v[176:179], v[60:63]
	v_mfma_f32_16x16x32_bf16 v[56:59], v[8:11], v[180:183], v[24:27]
	v_mfma_f32_16x16x32_bf16 v[24:27], v[12:15], v[176:179], v[216:219]
	v_mfma_f32_16x16x32_bf16 v[60:63], v[156:159], v[180:183], v[24:27]
	v_mfma_f32_16x16x32_bf16 v[24:27], v[0:3], v[196:199], v[52:55]
	v_mfma_f32_16x16x32_bf16 v[40:43], v[8:11], v[200:203], v[24:27]
	v_mfma_f32_16x16x32_bf16 v[24:27], v[12:15], v[196:199], v[48:51]
	v_mfma_f32_16x16x32_bf16 v[44:47], v[156:159], v[200:203], v[24:27]
	v_mfma_f32_16x16x32_bf16 v[24:27], v[0:3], v[204:207], v[236:239]
	v_mfma_f32_16x16x32_bf16 v[0:3], v[0:3], v[228:231], v[36:39]
	v_mfma_f32_16x16x32_bf16 v[24:27], v[8:11], v[208:211], v[24:27]
	v_mfma_f32_16x16x32_bf16 v[28:31], v[12:15], v[204:207], v[240:243]
	v_mfma_f32_16x16x32_bf16 v[8:11], v[8:11], v[232:235], v[0:3]
	v_mfma_f32_16x16x32_bf16 v[0:3], v[12:15], v[228:231], v[32:35]
	v_mfma_f32_16x16x32_bf16 v[28:31], v[156:159], v[208:211], v[28:31]
	v_mfma_f32_16x16x32_bf16 v[12:15], v[156:159], v[232:235], v[0:3]
	v_mfma_f32_16x16x32_bf16 v[0:3], v[212:215], v[176:179], v[142:145]
	v_mfma_f32_16x16x32_bf16 v[48:51], v[220:223], v[180:183], v[0:3]
	v_mfma_f32_16x16x32_bf16 v[0:3], v[224:227], v[176:179], v[164:167]
	v_mfma_f32_16x16x32_bf16 v[52:55], v[160:163], v[180:183], v[0:3]
	v_mfma_f32_16x16x32_bf16 v[0:3], v[212:215], v[196:199], v[20:23]
	v_mfma_f32_16x16x32_bf16 v[32:35], v[220:223], v[200:203], v[0:3]
	v_mfma_f32_16x16x32_bf16 v[0:3], v[224:227], v[196:199], v[16:19]
	v_mfma_f32_16x16x32_bf16 v[36:39], v[160:163], v[200:203], v[0:3]
	v_mfma_f32_16x16x32_bf16 v[0:3], v[212:215], v[204:207], v[168:171]
	v_mfma_f32_16x16x32_bf16 v[16:19], v[220:223], v[208:211], v[0:3]
	v_mfma_f32_16x16x32_bf16 v[0:3], v[224:227], v[204:207], v[172:175]
	v_mfma_f32_16x16x32_bf16 v[20:23], v[160:163], v[208:211], v[0:3]
	v_mfma_f32_16x16x32_bf16 v[0:3], v[212:215], v[228:231], v[4:7]
	v_mfma_f32_16x16x32_bf16 v[4:7], v[224:227], v[228:231], v[152:155]
	v_mfma_f32_16x16x32_bf16 v[0:3], v[220:223], v[232:235], v[0:3]
	v_mfma_f32_16x16x32_bf16 v[4:7], v[160:163], v[232:235], v[4:7]
	s_andn2_b64 vcc, exec, s[18:19]
	s_barrier
	s_cbranch_vccnz .LBB0_201
	s_barrier

; #define WAIT_V(n) asm volatile("s_waitcnt vmcnt(%0)" ::"n"(n) : "memory")
; #define WAIT_L(n) asm volatile("s_waitcnt lgkmcnt(%0)" ::"n"(n) : "memory")
; #define SBAR() __builtin_amdgcn_sched_barrier(0)
; #define STAGE(P, base, kt) do { _Pragma("unroll") for (int _i = 0; _i < 2; ++_i)                                        \
;       __builtin_amdgcn_global_load_lds((const unsigned*)((base) + (size_t)(sOff[_i] + (unsigned)(kt) * (BK * 2))),        \
;                                        (unsigned*)((P) + wid * 1024 + _i * 8192), 16, 0, 0); } while (0)
; #define LDA(dst, b, h) _Pragma("unroll") for (int m = 0; m < 4; ++m) _Pragma("unroll") for (int k = 0; k < 2; ++k) \
;       dst[m][k] = *(const bf16x8*)(SA(b, h) + aoff + (m * 2048 + k * 1024))
; #define LDB(dst, b, h) _Pragma("unroll") for (int n = 0; n < 2; ++n) _Pragma("unroll") for (int k = 0; k < 2; ++k) \
;       dst[n][k] = *(const bf16x8*)(SB(b, h) + boff + (n * 256 + k * 1024))
; #define BAR __builtin_amdgcn_s_barrier()
; template <int EPI, int N, int K>
; __device__ __forceinline__ void phase_gemm(const Params& p, const u16* __restrict__ A, const u16* __restrict__ Bt, int nM, char* shm,
;                            u16* __restrict__ outp, float* __restrict__ rowss) {
;     ...
;     for (int t = 0; t < nt - 2; t += 2) {
;       LDB(B0, 0, 0); SBAR(); LDA(At, 0, 0); STAGE(SA(1, 1), A1, t + 1);
;       WAIT_L(8); BAR; WAIT_L(0); MMA(0, 0, At, B0); BAR; SBAR();
;       LDB(B1, 0, 1); STAGE(SB(0, 0), B0p, t + 2);
;       BAR; WAIT_L(0); MMA(0, 1, At, B1); BAR;
;       LDA(At, 0, 1); STAGE(SA(0, 0), A0, t + 2);
;       BAR; WAIT_L(0); MMA(1, 0, At, B0); BAR; SBAR();
;       STAGE(SB(0, 1), B1p, t + 2);
;       WAIT_V(6); BAR; MMA(1, 1, At, B1); BAR;
.LBB0_379:
	v_or_b32_e32 v131, 0x10000, v150
	v_add_u32_e32 v133, 0x10100, v150
	v_add_u32_e32 v132, 0x10400, v150
	ds_read_b128 v[156:159], v131
	ds_read_b128 v[160:163], v132
	v_add_u32_e32 v146, 0x10500, v150
	ds_read_b128 v[164:167], v133
	ds_read_b128 v[168:171], v146
	v_add_u32_e32 v240, v147, v96
	s_add_i32 s26, s94, 0xc000
	v_add_u32_e32 v148, 0x80, v240
	s_mov_b32 m0, s26
	v_add_u32_e32 v241, v147, v130
	s_add_i32 s25, s94, 0xe000
	ds_read_b128 v[172:175], v151
	ds_read_b128 v[176:179], v151 offset:1024
	ds_read_b128 v[180:183], v151 offset:2048
	ds_read_b128 v[196:199], v151 offset:3072
	ds_read_b128 v[200:203], v151 offset:4096
	ds_read_b128 v[204:207], v151 offset:5120
	ds_read_b128 v[208:211], v151 offset:6144
	ds_read_b128 v[212:215], v151 offset:7168
	global_load_lds_dwordx4 v148, s[6:7]
	v_add_u32_e32 v148, 0x80, v241
	s_mov_b32 m0, s25
	s_nop 0
	global_load_lds_dwordx4 v148, s[6:7]
	v_or_b32_e32 v148, 0x14000, v150
	v_add_u32_e32 v154, 0x14100, v150
	v_add_u32_e32 v149, 0x14400, v150
	ds_read_b128 v[216:219], v148
	ds_read_b128 v[220:223], v149
	v_add_u32_e32 v155, 0x14500, v150
	ds_read_b128 v[224:227], v154
	ds_read_b128 v[228:231], v155
	s_waitcnt vmcnt(8)
	s_waitcnt lgkmcnt(0)
	s_barrier
	v_mfma_f32_16x16x32_bf16 v[126:129], v[156:159], v[172:175], v[126:129]
	v_mfma_f32_16x16x32_bf16 v[122:125], v[164:167], v[172:175], v[122:125]
	v_mfma_f32_16x16x32_bf16 v[118:121], v[156:159], v[180:183], v[118:121]
	v_mfma_f32_16x16x32_bf16 v[114:117], v[164:167], v[180:183], v[114:117]
	v_mfma_f32_16x16x32_bf16 v[110:113], v[156:159], v[200:203], v[110:113]
	v_mfma_f32_16x16x32_bf16 v[106:109], v[164:167], v[200:203], v[106:109]
	v_mfma_f32_16x16x32_bf16 v[102:105], v[156:159], v[208:211], v[102:105]
	v_mfma_f32_16x16x32_bf16 v[98:101], v[164:167], v[208:211], v[98:101]
	v_mfma_f32_16x16x32_bf16 v[126:129], v[160:163], v[176:179], v[126:129]
	v_mfma_f32_16x16x32_bf16 v[122:125], v[168:171], v[176:179], v[122:125]
	v_mfma_f32_16x16x32_bf16 v[118:121], v[160:163], v[196:199], v[118:121]
	v_mfma_f32_16x16x32_bf16 v[114:117], v[168:171], v[196:199], v[114:117]
	v_mfma_f32_16x16x32_bf16 v[110:113], v[160:163], v[204:207], v[110:113]
	v_mfma_f32_16x16x32_bf16 v[106:109], v[168:171], v[204:207], v[106:109]
	v_mfma_f32_16x16x32_bf16 v[102:105], v[160:163], v[212:215], v[102:105]
	v_mfma_f32_16x16x32_bf16 v[98:101], v[168:171], v[212:215], v[98:101]
	v_mfma_f32_16x16x32_bf16 v[92:95], v[216:219], v[172:175], v[92:95]
	v_mfma_f32_16x16x32_bf16 v[88:91], v[224:227], v[172:175], v[88:91]
	v_mfma_f32_16x16x32_bf16 v[84:87], v[216:219], v[180:183], v[84:87]
	v_mfma_f32_16x16x32_bf16 v[80:83], v[224:227], v[180:183], v[80:83]
	v_mfma_f32_16x16x32_bf16 v[76:79], v[216:219], v[200:203], v[76:79]
	v_mfma_f32_16x16x32_bf16 v[72:75], v[224:227], v[200:203], v[72:75]
	v_mfma_f32_16x16x32_bf16 v[68:71], v[216:219], v[208:211], v[68:71]
	v_mfma_f32_16x16x32_bf16 v[64:67], v[224:227], v[208:211], v[64:67]
	v_mfma_f32_16x16x32_bf16 v[92:95], v[220:223], v[176:179], v[92:95]
	v_mfma_f32_16x16x32_bf16 v[88:91], v[228:231], v[176:179], v[88:91]
	v_mfma_f32_16x16x32_bf16 v[84:87], v[220:223], v[196:199], v[84:87]
	v_mfma_f32_16x16x32_bf16 v[80:83], v[228:231], v[196:199], v[80:83]
	v_mfma_f32_16x16x32_bf16 v[76:79], v[220:223], v[204:207], v[76:79]
	v_mfma_f32_16x16x32_bf16 v[72:75], v[228:231], v[204:207], v[72:75]
	v_mfma_f32_16x16x32_bf16 v[68:71], v[220:223], v[212:215], v[68:71]
	v_mfma_f32_16x16x32_bf16 v[64:67], v[228:231], v[212:215], v[64:67]
	s_barrier
	ds_read_b128 v[172:175], v151 offset:16384
	ds_read_b128 v[176:179], v151 offset:17408
	ds_read_b128 v[180:183], v151 offset:18432
	ds_read_b128 v[196:199], v151 offset:19456
	ds_read_b128 v[200:203], v151 offset:20480
	ds_read_b128 v[204:207], v151 offset:21504
	ds_read_b128 v[208:211], v151 offset:22528
	ds_read_b128 v[212:215], v151 offset:23552
	s_mov_b32 m0, s22
	v_add_u32_e32 v232, 0x100, v240
	global_load_lds_dwordx4 v232, s[16:17]
	v_add_u32_e32 v233, 0x100, v241
	s_mov_b32 m0, s23
	s_nop 0
	global_load_lds_dwordx4 v233, s[16:17]
	s_mov_b32 m0, s94
	s_nop 0
	global_load_lds_dwordx4 v232, s[18:19]
	s_mov_b32 m0, s95
	s_nop 0
	global_load_lds_dwordx4 v233, s[18:19]
	s_mov_b32 m0, s2
	s_nop 0
	global_load_lds_dwordx4 v232, s[8:9]
	s_mov_b32 m0, s3
	s_nop 0
	global_load_lds_dwordx4 v233, s[8:9]
	s_waitcnt vmcnt(8)
	s_waitcnt lgkmcnt(0)
	s_barrier
	v_mfma_f32_16x16x32_bf16 v[60:63], v[156:159], v[172:175], v[60:63]
	v_mfma_f32_16x16x32_bf16 v[56:59], v[164:167], v[172:175], v[56:59]
	v_mfma_f32_16x16x32_bf16 v[52:55], v[156:159], v[180:183], v[52:55]
	v_mfma_f32_16x16x32_bf16 v[48:51], v[164:167], v[180:183], v[48:51]
	v_mfma_f32_16x16x32_bf16 v[44:47], v[156:159], v[200:203], v[44:47]
	v_mfma_f32_16x16x32_bf16 v[40:43], v[164:167], v[200:203], v[40:43]
	v_mfma_f32_16x16x32_bf16 v[36:39], v[156:159], v[208:211], v[36:39]
	v_mfma_f32_16x16x32_bf16 v[32:35], v[164:167], v[208:211], v[32:35]
	v_mfma_f32_16x16x32_bf16 v[60:63], v[160:163], v[176:179], v[60:63]
	v_mfma_f32_16x16x32_bf16 v[56:59], v[168:171], v[176:179], v[56:59]
	v_mfma_f32_16x16x32_bf16 v[52:55], v[160:163], v[196:199], v[52:55]
	v_mfma_f32_16x16x32_bf16 v[48:51], v[168:171], v[196:199], v[48:51]
	v_mfma_f32_16x16x32_bf16 v[44:47], v[160:163], v[204:207], v[44:47]
	v_mfma_f32_16x16x32_bf16 v[40:43], v[168:171], v[204:207], v[40:43]
	v_mfma_f32_16x16x32_bf16 v[36:39], v[160:163], v[212:215], v[36:39]
	v_mfma_f32_16x16x32_bf16 v[32:35], v[168:171], v[212:215], v[32:35]
	v_mfma_f32_16x16x32_bf16 v[28:31], v[216:219], v[172:175], v[28:31]
	v_mfma_f32_16x16x32_bf16 v[24:27], v[224:227], v[172:175], v[24:27]
	v_mfma_f32_16x16x32_bf16 v[20:23], v[216:219], v[180:183], v[20:23]
	v_mfma_f32_16x16x32_bf16 v[16:19], v[224:227], v[180:183], v[16:19]
	v_mfma_f32_16x16x32_bf16 v[12:15], v[216:219], v[200:203], v[12:15]
	v_mfma_f32_16x16x32_bf16 v[8:11], v[224:227], v[200:203], v[8:11]
	v_mfma_f32_16x16x32_bf16 v[4:7], v[216:219], v[208:211], v[4:7]
	v_mfma_f32_16x16x32_bf16 v[0:3], v[224:227], v[208:211], v[0:3]
	v_mfma_f32_16x16x32_bf16 v[28:31], v[220:223], v[176:179], v[28:31]
	v_mfma_f32_16x16x32_bf16 v[24:27], v[228:231], v[176:179], v[24:27]
	v_mfma_f32_16x16x32_bf16 v[20:23], v[220:223], v[196:199], v[20:23]
	v_mfma_f32_16x16x32_bf16 v[16:19], v[228:231], v[196:199], v[16:19]
	v_mfma_f32_16x16x32_bf16 v[12:15], v[220:223], v[204:207], v[12:15]
	v_mfma_f32_16x16x32_bf16 v[8:11], v[228:231], v[204:207], v[8:11]
	v_mfma_f32_16x16x32_bf16 v[4:7], v[220:223], v[212:215], v[4:7]
	v_mfma_f32_16x16x32_bf16 v[0:3], v[228:231], v[212:215], v[0:3]
	v_or_b32_e32 v156, 0x18000, v150
	v_add_u32_e32 v158, 0x18100, v150
	s_barrier
; #define WAIT_V(n) asm volatile("s_waitcnt vmcnt(%0)" ::"n"(n) : "memory")
; #define WAIT_L(n) asm volatile("s_waitcnt lgkmcnt(%0)" ::"n"(n) : "memory")
; #define SBAR() __builtin_amdgcn_sched_barrier(0)
; #define STAGE(P, base, kt) do { _Pragma("unroll") for (int _i = 0; _i < 2; ++_i)                                        \
;       __builtin_amdgcn_global_load_lds((const unsigned*)((base) + (size_t)(sOff[_i] + (unsigned)(kt) * (BK * 2))),        \
;                                        (unsigned*)((P) + wid * 1024 + _i * 8192), 16, 0, 0); } while (0)
; #define LDA(dst, b, h) _Pragma("unroll") for (int m = 0; m < 4; ++m) _Pragma("unroll") for (int k = 0; k < 2; ++k) \
;       dst[m][k] = *(const bf16x8*)(SA(b, h) + aoff + (m * 2048 + k * 1024))
; #define LDB(dst, b, h) _Pragma("unroll") for (int n = 0; n < 2; ++n) _Pragma("unroll") for (int k = 0; k < 2; ++k) \
;       dst[n][k] = *(const bf16x8*)(SB(b, h) + boff + (n * 256 + k * 1024))
; #define BAR __builtin_amdgcn_s_barrier()
; template <int EPI, int N, int K>
; __device__ __forceinline__ void phase_gemm(const Params& p, const u16* __restrict__ A, const u16* __restrict__ Bt, int nM, char* shm,
;                            u16* __restrict__ outp, float* __restrict__ rowss) {
;     ...
;       LDB(B0, 1, 0); SBAR(); LDA(At, 1, 0); STAGE(SA(0, 1), A1, t + 2);
;       WAIT_L(8); BAR; WAIT_L(0); MMA(0, 0, At, B0); BAR; SBAR();
;       LDB(B1, 1, 1); STAGE(SB(1, 0), B0p, t + 3);
;       BAR; WAIT_L(0); MMA(0, 1, At, B1); BAR;
;       LDA(At, 1, 1); STAGE(SA(1, 0), A0, t + 3);
;       BAR; WAIT_L(0); MMA(1, 0, At, B0); BAR; SBAR();
;       STAGE(SB(1, 1), B1p, t + 3);
;       WAIT_V(6); BAR; MMA(1, 1, At, B1); BAR;
;     }
	v_add_u32_e32 v157, 0x18400, v150
	ds_read_b128 v[164:167], v156
	ds_read_b128 v[168:171], v157
	v_add_u32_e32 v159, 0x18500, v150
	ds_read_b128 v[172:175], v158
	ds_read_b128 v[176:179], v159
	s_mov_b32 m0, s92
	ds_read_b128 v[180:183], v151 offset:32768
	ds_read_b128 v[196:199], v151 offset:33792
	ds_read_b128 v[200:203], v151 offset:34816
	ds_read_b128 v[204:207], v151 offset:35840
	ds_read_b128 v[208:211], v151 offset:36864
	ds_read_b128 v[212:215], v151 offset:37888
	ds_read_b128 v[216:219], v151 offset:38912
	ds_read_b128 v[220:223], v151 offset:39936
	global_load_lds_dwordx4 v232, s[6:7]
	s_mov_b32 m0, s0
	s_nop 0
	global_load_lds_dwordx4 v233, s[6:7]
	v_or_b32_e32 v160, 0x1c000, v150
	v_add_u32_e32 v162, 0x1c100, v150
	v_add_u32_e32 v161, 0x1c400, v150
	ds_read_b128 v[224:227], v160
	ds_read_b128 v[228:231], v161
	v_add_u32_e32 v163, 0x1c500, v150
	ds_read_b128 v[232:235], v162
	ds_read_b128 v[236:239], v163
	s_waitcnt vmcnt(8)
	s_waitcnt lgkmcnt(0)
	s_barrier
	v_mfma_f32_16x16x32_bf16 v[126:129], v[164:167], v[180:183], v[126:129]
	v_mfma_f32_16x16x32_bf16 v[122:125], v[172:175], v[180:183], v[122:125]
	v_mfma_f32_16x16x32_bf16 v[118:121], v[164:167], v[200:203], v[118:121]
	v_mfma_f32_16x16x32_bf16 v[114:117], v[172:175], v[200:203], v[114:117]
	v_mfma_f32_16x16x32_bf16 v[110:113], v[164:167], v[208:211], v[110:113]
	v_mfma_f32_16x16x32_bf16 v[106:109], v[172:175], v[208:211], v[106:109]
	v_mfma_f32_16x16x32_bf16 v[102:105], v[164:167], v[216:219], v[102:105]
	v_mfma_f32_16x16x32_bf16 v[98:101], v[172:175], v[216:219], v[98:101]
	v_mfma_f32_16x16x32_bf16 v[126:129], v[168:171], v[196:199], v[126:129]
	v_mfma_f32_16x16x32_bf16 v[122:125], v[176:179], v[196:199], v[122:125]
	v_mfma_f32_16x16x32_bf16 v[118:121], v[168:171], v[204:207], v[118:121]
	v_mfma_f32_16x16x32_bf16 v[114:117], v[176:179], v[204:207], v[114:117]
	v_mfma_f32_16x16x32_bf16 v[110:113], v[168:171], v[212:215], v[110:113]
	v_mfma_f32_16x16x32_bf16 v[106:109], v[176:179], v[212:215], v[106:109]
	v_mfma_f32_16x16x32_bf16 v[102:105], v[168:171], v[220:223], v[102:105]
	v_mfma_f32_16x16x32_bf16 v[98:101], v[176:179], v[220:223], v[98:101]
	v_mfma_f32_16x16x32_bf16 v[92:95], v[224:227], v[180:183], v[92:95]
	v_mfma_f32_16x16x32_bf16 v[88:91], v[232:235], v[180:183], v[88:91]
	v_mfma_f32_16x16x32_bf16 v[84:87], v[224:227], v[200:203], v[84:87]
	v_mfma_f32_16x16x32_bf16 v[80:83], v[232:235], v[200:203], v[80:83]
	v_mfma_f32_16x16x32_bf16 v[76:79], v[224:227], v[208:211], v[76:79]
	v_mfma_f32_16x16x32_bf16 v[72:75], v[232:235], v[208:211], v[72:75]
	v_mfma_f32_16x16x32_bf16 v[68:71], v[224:227], v[216:219], v[68:71]
	v_mfma_f32_16x16x32_bf16 v[64:67], v[232:235], v[216:219], v[64:67]
	v_mfma_f32_16x16x32_bf16 v[92:95], v[228:231], v[196:199], v[92:95]
	v_mfma_f32_16x16x32_bf16 v[88:91], v[236:239], v[196:199], v[88:91]
	v_mfma_f32_16x16x32_bf16 v[84:87], v[228:231], v[204:207], v[84:87]
	v_mfma_f32_16x16x32_bf16 v[80:83], v[236:239], v[204:207], v[80:83]
	v_mfma_f32_16x16x32_bf16 v[76:79], v[228:231], v[212:215], v[76:79]
	v_mfma_f32_16x16x32_bf16 v[72:75], v[236:239], v[212:215], v[72:75]
	v_mfma_f32_16x16x32_bf16 v[68:71], v[228:231], v[220:223], v[68:71]
	v_mfma_f32_16x16x32_bf16 v[64:67], v[236:239], v[220:223], v[64:67]
	s_barrier
	ds_read_b128 v[180:183], v151 offset:49152
	ds_read_b128 v[196:199], v151 offset:50176
	ds_read_b128 v[200:203], v151 offset:51200
	ds_read_b128 v[204:207], v151 offset:52224
	ds_read_b128 v[208:211], v151 offset:53248
	ds_read_b128 v[212:215], v151 offset:54272
	ds_read_b128 v[216:219], v151 offset:55296
	ds_read_b128 v[220:223], v151 offset:56320
	s_mov_b32 m0, s1
	v_add_u32_e32 v240, 0x180, v240
	global_load_lds_dwordx4 v240, s[16:17]
	v_add_u32_e32 v241, 0x180, v241
	s_mov_b32 m0, s12
	s_nop 0
	global_load_lds_dwordx4 v241, s[16:17]
	s_mov_b32 m0, s13
	s_nop 0
	global_load_lds_dwordx4 v240, s[18:19]
	s_mov_b32 m0, s14
	s_nop 0
	global_load_lds_dwordx4 v241, s[18:19]
	s_mov_b32 m0, s15
	s_nop 0
	global_load_lds_dwordx4 v240, s[8:9]
	s_mov_b32 m0, s4
	s_nop 0
	global_load_lds_dwordx4 v241, s[8:9]
	s_waitcnt vmcnt(8)
	s_waitcnt lgkmcnt(0)
	s_barrier
	v_mfma_f32_16x16x32_bf16 v[60:63], v[164:167], v[180:183], v[60:63]
	v_mfma_f32_16x16x32_bf16 v[56:59], v[172:175], v[180:183], v[56:59]
	v_mfma_f32_16x16x32_bf16 v[52:55], v[164:167], v[200:203], v[52:55]
	v_mfma_f32_16x16x32_bf16 v[48:51], v[172:175], v[200:203], v[48:51]
	v_mfma_f32_16x16x32_bf16 v[44:47], v[164:167], v[208:211], v[44:47]
	v_mfma_f32_16x16x32_bf16 v[40:43], v[172:175], v[208:211], v[40:43]
	v_mfma_f32_16x16x32_bf16 v[36:39], v[164:167], v[216:219], v[36:39]
	v_mfma_f32_16x16x32_bf16 v[32:35], v[172:175], v[216:219], v[32:35]
	v_mfma_f32_16x16x32_bf16 v[60:63], v[168:171], v[196:199], v[60:63]
	v_mfma_f32_16x16x32_bf16 v[56:59], v[176:179], v[196:199], v[56:59]
	v_mfma_f32_16x16x32_bf16 v[52:55], v[168:171], v[204:207], v[52:55]
	v_mfma_f32_16x16x32_bf16 v[48:51], v[176:179], v[204:207], v[48:51]
	v_mfma_f32_16x16x32_bf16 v[44:47], v[168:171], v[212:215], v[44:47]
	v_mfma_f32_16x16x32_bf16 v[40:43], v[176:179], v[212:215], v[40:43]
	v_mfma_f32_16x16x32_bf16 v[36:39], v[168:171], v[220:223], v[36:39]
	v_mfma_f32_16x16x32_bf16 v[32:35], v[176:179], v[220:223], v[32:35]
	v_mfma_f32_16x16x32_bf16 v[28:31], v[224:227], v[180:183], v[28:31]
	v_mfma_f32_16x16x32_bf16 v[24:27], v[232:235], v[180:183], v[24:27]
	v_mfma_f32_16x16x32_bf16 v[20:23], v[224:227], v[200:203], v[20:23]
	v_mfma_f32_16x16x32_bf16 v[16:19], v[232:235], v[200:203], v[16:19]
	v_mfma_f32_16x16x32_bf16 v[12:15], v[224:227], v[208:211], v[12:15]
	v_mfma_f32_16x16x32_bf16 v[8:11], v[232:235], v[208:211], v[8:11]
	v_mfma_f32_16x16x32_bf16 v[4:7], v[224:227], v[216:219], v[4:7]
	v_mfma_f32_16x16x32_bf16 v[0:3], v[232:235], v[216:219], v[0:3]
	v_mfma_f32_16x16x32_bf16 v[28:31], v[228:231], v[196:199], v[28:31]
	v_mfma_f32_16x16x32_bf16 v[24:27], v[236:239], v[196:199], v[24:27]
	v_mfma_f32_16x16x32_bf16 v[20:23], v[228:231], v[204:207], v[20:23]
	v_mfma_f32_16x16x32_bf16 v[16:19], v[236:239], v[204:207], v[16:19]
	v_mfma_f32_16x16x32_bf16 v[12:15], v[228:231], v[212:215], v[12:15]
	v_mfma_f32_16x16x32_bf16 v[8:11], v[236:239], v[212:215], v[8:11]
	v_mfma_f32_16x16x32_bf16 v[4:7], v[228:231], v[220:223], v[4:7]
	v_mfma_f32_16x16x32_bf16 v[0:3], v[236:239], v[220:223], v[0:3]
	s_add_i32 s11, s11, 2
	v_add_u32_e32 v130, 0x100, v130
	s_cmp_lt_u32 s11, 12
	v_add_u32_e32 v96, 0x100, v96
	s_barrier
; #define WAIT_V(n) asm volatile("s_waitcnt vmcnt(%0)" ::"n"(n) : "memory")
; #define WAIT_L(n) asm volatile("s_waitcnt lgkmcnt(%0)" ::"n"(n) : "memory")
; #define STAGE(P, base, kt) do { _Pragma("unroll") for (int _i = 0; _i < 2; ++_i)                                        \
;       __builtin_amdgcn_global_load_lds((const unsigned*)((base) + (size_t)(sOff[_i] + (unsigned)(kt) * (BK * 2))),        \
;                                        (unsigned*)((P) + wid * 1024 + _i * 8192), 16, 0, 0); } while (0)
; #define LDA(dst, b, h) _Pragma("unroll") for (int m = 0; m < 4; ++m) _Pragma("unroll") for (int k = 0; k < 2; ++k) \
;       dst[m][k] = *(const bf16x8*)(SA(b, h) + aoff + (m * 2048 + k * 1024))
; #define LDB(dst, b, h) _Pragma("unroll") for (int n = 0; n < 2; ++n) _Pragma("unroll") for (int k = 0; k < 2; ++k) \
;       dst[n][k] = *(const bf16x8*)(SB(b, h) + boff + (n * 256 + k * 1024))
; #define BAR __builtin_amdgcn_s_barrier()
; template <int EPI, int N, int K>
; __device__ __forceinline__ void phase_gemm(const Params& p, const u16* __restrict__ A, const u16* __restrict__ Bt, int nM, char* shm,
;                            u16* __restrict__ outp, float* __restrict__ rowss) {
;     ...
;     { LDB(B0, 0, 0); LDA(At, 0, 0); STAGE(SA(1, 1), A1, nt - 1);
;       BAR; WAIT_L(0); MMA(0, 0, At, B0); BAR;
;       LDB(B1, 0, 1); BAR; WAIT_L(0); MMA(0, 1, At, B1); BAR;
;       LDA(At, 0, 1); WAIT_V(4); BAR; WAIT_L(0); MMA(1, 0, At, B0); MMA(1, 1, At, B1); BAR; }
	s_cbranch_scc1 .LBB0_379
	s_waitcnt vmcnt(6)
	s_mov_b32 m0, s26
	v_lshl_add_u64 v[220:221], s[6:7], 0, v[142:143]
	ds_read_b128 v[164:167], v131
	ds_read_b128 v[168:171], v132
	ds_read_b128 v[130:133], v133
	ds_read_b128 v[172:175], v146
	ds_read_b128 v[176:179], v151
	ds_read_b128 v[180:183], v151 offset:1024
	ds_read_b128 v[196:199], v151 offset:2048
	ds_read_b128 v[200:203], v151 offset:3072
	ds_read_b128 v[204:207], v151 offset:4096
	ds_read_b128 v[208:211], v151 offset:5120
	ds_read_b128 v[212:215], v151 offset:6144
	ds_read_b128 v[216:219], v151 offset:7168
	global_load_lds_dwordx4 v[220:221], off
	v_lshl_add_u64 v[220:221], s[6:7], 0, v[144:145]
	s_mov_b32 m0, s25
	s_nop 0
	global_load_lds_dwordx4 v[220:221], off
	s_barrier
	s_waitcnt lgkmcnt(0)
	s_waitcnt lgkmcnt(0)
	v_mfma_f32_16x16x32_bf16 v[126:129], v[164:167], v[176:179], v[126:129]
	v_mfma_f32_16x16x32_bf16 v[122:125], v[130:133], v[176:179], v[122:125]
	v_mfma_f32_16x16x32_bf16 v[118:121], v[164:167], v[196:199], v[118:121]
	v_mfma_f32_16x16x32_bf16 v[114:117], v[130:133], v[196:199], v[114:117]
	v_mfma_f32_16x16x32_bf16 v[102:105], v[164:167], v[212:215], v[102:105]
	v_mfma_f32_16x16x32_bf16 v[98:101], v[130:133], v[212:215], v[98:101]
	v_mfma_f32_16x16x32_bf16 v[126:129], v[168:171], v[180:183], v[126:129]
	v_mfma_f32_16x16x32_bf16 v[122:125], v[172:175], v[180:183], v[122:125]
	v_mfma_f32_16x16x32_bf16 v[118:121], v[168:171], v[200:203], v[118:121]
	v_mfma_f32_16x16x32_bf16 v[114:117], v[172:175], v[200:203], v[114:117]
	v_mfma_f32_16x16x32_bf16 v[110:113], v[164:167], v[204:207], v[110:113]
	v_mfma_f32_16x16x32_bf16 v[106:109], v[130:133], v[204:207], v[106:109]
	v_mfma_f32_16x16x32_bf16 v[102:105], v[168:171], v[216:219], v[102:105]
	v_mfma_f32_16x16x32_bf16 v[98:101], v[172:175], v[216:219], v[98:101]
	v_mfma_f32_16x16x32_bf16 v[220:223], v[168:171], v[208:211], v[110:113]
	v_mfma_f32_16x16x32_bf16 v[224:227], v[172:175], v[208:211], v[106:109]
	s_barrier
	s_nop 1
	ds_read_b128 v[106:109], v148
	ds_read_b128 v[110:113], v149
	ds_read_b128 v[228:231], v154
	ds_read_b128 v[232:235], v155
	s_barrier
	s_waitcnt lgkmcnt(0)
	s_waitcnt lgkmcnt(0)
	v_mfma_f32_16x16x32_bf16 v[84:87], v[106:109], v[196:199], v[84:87]
	v_mfma_f32_16x16x32_bf16 v[80:83], v[228:231], v[196:199], v[80:83]
	v_mfma_f32_16x16x32_bf16 v[68:71], v[106:109], v[212:215], v[68:71]
	v_mfma_f32_16x16x32_bf16 v[64:67], v[228:231], v[212:215], v[64:67]
	v_mfma_f32_16x16x32_bf16 v[92:95], v[106:109], v[176:179], v[92:95]
	v_mfma_f32_16x16x32_bf16 v[88:91], v[228:231], v[176:179], v[88:91]
	v_mfma_f32_16x16x32_bf16 v[84:87], v[110:113], v[200:203], v[84:87]
	v_mfma_f32_16x16x32_bf16 v[80:83], v[232:235], v[200:203], v[80:83]
	v_mfma_f32_16x16x32_bf16 v[76:79], v[106:109], v[204:207], v[76:79]
	v_mfma_f32_16x16x32_bf16 v[72:75], v[228:231], v[204:207], v[72:75]
	v_mfma_f32_16x16x32_bf16 v[68:71], v[110:113], v[216:219], v[68:71]
	v_mfma_f32_16x16x32_bf16 v[64:67], v[232:235], v[216:219], v[64:67]
	v_mfma_f32_16x16x32_bf16 v[236:239], v[110:113], v[180:183], v[92:95]
	v_mfma_f32_16x16x32_bf16 v[176:179], v[232:235], v[180:183], v[88:91]
	v_mfma_f32_16x16x32_bf16 v[180:183], v[110:113], v[208:211], v[76:79]
	v_mfma_f32_16x16x32_bf16 v[196:199], v[232:235], v[208:211], v[72:75]
	s_barrier
	s_nop 0
	ds_read_b128 v[72:75], v151 offset:16384
	ds_read_b128 v[76:79], v151 offset:17408
	ds_read_b128 v[88:91], v151 offset:18432
	ds_read_b128 v[92:95], v151 offset:19456
	ds_read_b128 v[200:203], v151 offset:20480
	ds_read_b128 v[204:207], v151 offset:21504
	ds_read_b128 v[208:211], v151 offset:22528
	ds_read_b128 v[212:215], v151 offset:23552
	s_waitcnt vmcnt(4)
	s_barrier
	s_waitcnt lgkmcnt(0)
	s_waitcnt lgkmcnt(0)
	v_mfma_f32_16x16x32_bf16 v[60:63], v[164:167], v[72:75], v[60:63]
	v_mfma_f32_16x16x32_bf16 v[56:59], v[130:133], v[72:75], v[56:59]
	v_mfma_f32_16x16x32_bf16 v[52:55], v[164:167], v[88:91], v[52:55]
	v_mfma_f32_16x16x32_bf16 v[48:51], v[130:133], v[88:91], v[48:51]
	v_mfma_f32_16x16x32_bf16 v[36:39], v[164:167], v[208:211], v[36:39]
	v_mfma_f32_16x16x32_bf16 v[32:35], v[130:133], v[208:211], v[32:35]
	v_mfma_f32_16x16x32_bf16 v[60:63], v[168:171], v[76:79], v[60:63]
	v_mfma_f32_16x16x32_bf16 v[56:59], v[172:175], v[76:79], v[56:59]
	v_mfma_f32_16x16x32_bf16 v[52:55], v[168:171], v[92:95], v[52:55]
	v_mfma_f32_16x16x32_bf16 v[48:51], v[172:175], v[92:95], v[48:51]
	v_mfma_f32_16x16x32_bf16 v[44:47], v[164:167], v[200:203], v[44:47]
	v_mfma_f32_16x16x32_bf16 v[40:43], v[130:133], v[200:203], v[40:43]
	v_mfma_f32_16x16x32_bf16 v[36:39], v[168:171], v[212:215], v[36:39]
	v_mfma_f32_16x16x32_bf16 v[32:35], v[172:175], v[212:215], v[32:35]
	v_mfma_f32_16x16x32_bf16 v[216:219], v[168:171], v[204:207], v[44:47]
	v_mfma_f32_16x16x32_bf16 v[240:243], v[172:175], v[204:207], v[40:43]
	v_mfma_f32_16x16x32_bf16 v[20:23], v[106:109], v[88:91], v[20:23]
	v_mfma_f32_16x16x32_bf16 v[16:19], v[228:231], v[88:91], v[16:19]
	v_mfma_f32_16x16x32_bf16 v[4:7], v[106:109], v[208:211], v[4:7]
	v_mfma_f32_16x16x32_bf16 v[0:3], v[228:231], v[208:211], v[0:3]
	v_mfma_f32_16x16x32_bf16 v[28:31], v[106:109], v[72:75], v[28:31]
	v_mfma_f32_16x16x32_bf16 v[24:27], v[228:231], v[72:75], v[24:27]
	v_mfma_f32_16x16x32_bf16 v[20:23], v[110:113], v[92:95], v[20:23]
	v_mfma_f32_16x16x32_bf16 v[16:19], v[232:235], v[92:95], v[16:19]
	v_mfma_f32_16x16x32_bf16 v[12:15], v[106:109], v[200:203], v[12:15]
	v_mfma_f32_16x16x32_bf16 v[8:11], v[228:231], v[200:203], v[8:11]
	v_mfma_f32_16x16x32_bf16 v[4:7], v[110:113], v[212:215], v[4:7]
	v_mfma_f32_16x16x32_bf16 v[0:3], v[232:235], v[212:215], v[0:3]
	v_mfma_f32_16x16x32_bf16 v[130:133], v[110:113], v[76:79], v[28:31]
	v_mfma_f32_16x16x32_bf16 v[164:167], v[232:235], v[76:79], v[24:27]
	v_mfma_f32_16x16x32_bf16 v[168:171], v[110:113], v[204:207], v[12:15]
	v_mfma_f32_16x16x32_bf16 v[172:175], v[232:235], v[204:207], v[8:11]
	s_barrier
; #define WAIT_V(n) asm volatile("s_waitcnt vmcnt(%0)" ::"n"(n) : "memory")
; #define WAIT_L(n) asm volatile("s_waitcnt lgkmcnt(%0)" ::"n"(n) : "memory")
; #define LDA(dst, b, h) _Pragma("unroll") for (int m = 0; m < 4; ++m) _Pragma("unroll") for (int k = 0; k < 2; ++k) \
;       dst[m][k] = *(const bf16x8*)(SA(b, h) + aoff + (m * 2048 + k * 1024))
; #define LDB(dst, b, h) _Pragma("unroll") for (int n = 0; n < 2; ++n) _Pragma("unroll") for (int k = 0; k < 2; ++k) \
;       dst[n][k] = *(const bf16x8*)(SB(b, h) + boff + (n * 256 + k * 1024))
; #define BAR __builtin_amdgcn_s_barrier()
; template <int EPI, int N, int K>
; __device__ __forceinline__ void phase_gemm(const Params& p, const u16* __restrict__ A, const u16* __restrict__ Bt, int nM, char* shm,
;                            u16* __restrict__ outp, float* __restrict__ rowss) {
;     ...
;     { LDB(B0, 1, 0); LDA(At, 1, 0); WAIT_V(2); BAR; WAIT_L(0); MMA(0, 0, At, B0); BAR;
;       LDB(B1, 1, 1); WAIT_V(0); BAR; WAIT_L(0); MMA(0, 1, At, B1); BAR;
;       LDA(At, 1, 1); BAR; WAIT_L(0); MMA(1, 0, At, B0); MMA(1, 1, At, B1); BAR; }
;     if (wr == 0) BAR;
	s_nop 0
	ds_read_b128 v[8:11], v156
	ds_read_b128 v[12:15], v157
	ds_read_b128 v[154:157], v158
	ds_read_b128 v[200:203], v159
	ds_read_b128 v[24:27], v151 offset:32768
	ds_read_b128 v[28:31], v151 offset:33792
	ds_read_b128 v[40:43], v151 offset:34816
	ds_read_b128 v[44:47], v151 offset:35840
	ds_read_b128 v[204:207], v151 offset:36864
	ds_read_b128 v[208:211], v151 offset:37888
	ds_read_b128 v[212:215], v151 offset:38912
	ds_read_b128 v[228:231], v151 offset:39936
	s_waitcnt vmcnt(2)
	s_barrier
	s_waitcnt lgkmcnt(0)
	s_waitcnt lgkmcnt(0)
	v_mfma_f32_16x16x32_bf16 v[72:75], v[8:11], v[24:27], v[126:129]
	v_mfma_f32_16x16x32_bf16 v[126:129], v[12:15], v[28:31], v[72:75]
	v_mfma_f32_16x16x32_bf16 v[72:75], v[154:157], v[24:27], v[122:125]
	v_mfma_f32_16x16x32_bf16 v[122:125], v[200:203], v[28:31], v[72:75]
	v_mfma_f32_16x16x32_bf16 v[72:75], v[8:11], v[40:43], v[118:121]
	v_mfma_f32_16x16x32_bf16 v[110:113], v[12:15], v[44:47], v[72:75]
	v_mfma_f32_16x16x32_bf16 v[72:75], v[154:157], v[40:43], v[114:117]
	v_mfma_f32_16x16x32_bf16 v[106:109], v[200:203], v[44:47], v[72:75]
	v_mfma_f32_16x16x32_bf16 v[72:75], v[8:11], v[204:207], v[220:223]
	v_mfma_f32_16x16x32_bf16 v[92:95], v[12:15], v[208:211], v[72:75]
	v_mfma_f32_16x16x32_bf16 v[72:75], v[154:157], v[204:207], v[224:227]
	v_mfma_f32_16x16x32_bf16 v[88:91], v[200:203], v[208:211], v[72:75]
	v_mfma_f32_16x16x32_bf16 v[72:75], v[8:11], v[212:215], v[102:105]
	v_mfma_f32_16x16x32_bf16 v[76:79], v[12:15], v[228:231], v[72:75]
	v_mfma_f32_16x16x32_bf16 v[72:75], v[154:157], v[212:215], v[98:101]
	v_mfma_f32_16x16x32_bf16 v[72:75], v[200:203], v[228:231], v[72:75]
	s_barrier
	ds_read_b128 v[220:223], v160
	ds_read_b128 v[158:161], v161
	ds_read_b128 v[224:227], v162
	ds_read_b128 v[232:235], v163
	s_waitcnt vmcnt(0)
	s_barrier
	s_waitcnt lgkmcnt(0)
	s_waitcnt lgkmcnt(0)
	v_mfma_f32_16x16x32_bf16 v[98:101], v[220:223], v[24:27], v[236:239]
	v_mfma_f32_16x16x32_bf16 v[24:27], v[224:227], v[24:27], v[176:179]
	v_mfma_f32_16x16x32_bf16 v[114:117], v[232:235], v[28:31], v[24:27]
	v_mfma_f32_16x16x32_bf16 v[24:27], v[220:223], v[40:43], v[84:87]
	v_mfma_f32_16x16x32_bf16 v[102:105], v[158:161], v[44:47], v[24:27]
	v_mfma_f32_16x16x32_bf16 v[24:27], v[224:227], v[40:43], v[80:83]
	v_mfma_f32_16x16x32_bf16 v[118:121], v[158:161], v[28:31], v[98:101]
	v_mfma_f32_16x16x32_bf16 v[98:101], v[232:235], v[44:47], v[24:27]
	v_mfma_f32_16x16x32_bf16 v[24:27], v[220:223], v[204:207], v[180:183]
	v_mfma_f32_16x16x32_bf16 v[84:87], v[158:161], v[208:211], v[24:27]
	v_mfma_f32_16x16x32_bf16 v[24:27], v[224:227], v[204:207], v[196:199]
	v_mfma_f32_16x16x32_bf16 v[80:83], v[232:235], v[208:211], v[24:27]
	v_mfma_f32_16x16x32_bf16 v[24:27], v[220:223], v[212:215], v[68:71]
	v_mfma_f32_16x16x32_bf16 v[68:71], v[158:161], v[228:231], v[24:27]
	v_mfma_f32_16x16x32_bf16 v[24:27], v[224:227], v[212:215], v[64:67]
	v_mfma_f32_16x16x32_bf16 v[64:67], v[232:235], v[228:231], v[24:27]
	s_barrier
	ds_read_b128 v[176:179], v151 offset:49152
	ds_read_b128 v[180:183], v151 offset:50176
	ds_read_b128 v[196:199], v151 offset:51200
	ds_read_b128 v[204:207], v151 offset:52224
	ds_read_b128 v[208:211], v151 offset:53248
	ds_read_b128 v[212:215], v151 offset:54272
	ds_read_b128 v[228:231], v151 offset:55296
	ds_read_b128 v[236:239], v151 offset:56320
	s_barrier
	s_waitcnt lgkmcnt(0)
	s_waitcnt lgkmcnt(0)
	v_mfma_f32_16x16x32_bf16 v[24:27], v[8:11], v[176:179], v[60:63]
	v_mfma_f32_16x16x32_bf16 v[60:63], v[12:15], v[180:183], v[24:27]
	v_mfma_f32_16x16x32_bf16 v[24:27], v[154:157], v[176:179], v[56:59]
	v_mfma_f32_16x16x32_bf16 v[56:59], v[200:203], v[180:183], v[24:27]
	v_mfma_f32_16x16x32_bf16 v[24:27], v[8:11], v[196:199], v[52:55]
	v_mfma_f32_16x16x32_bf16 v[44:47], v[12:15], v[204:207], v[24:27]
	v_mfma_f32_16x16x32_bf16 v[24:27], v[154:157], v[196:199], v[48:51]
	v_mfma_f32_16x16x32_bf16 v[40:43], v[200:203], v[204:207], v[24:27]
	v_mfma_f32_16x16x32_bf16 v[24:27], v[8:11], v[208:211], v[216:219]
	v_mfma_f32_16x16x32_bf16 v[8:11], v[8:11], v[228:231], v[36:39]
	v_mfma_f32_16x16x32_bf16 v[28:31], v[12:15], v[212:215], v[24:27]
	v_mfma_f32_16x16x32_bf16 v[24:27], v[154:157], v[208:211], v[240:243]
	v_mfma_f32_16x16x32_bf16 v[12:15], v[12:15], v[236:239], v[8:11]
	v_mfma_f32_16x16x32_bf16 v[8:11], v[154:157], v[228:231], v[32:35]
	v_mfma_f32_16x16x32_bf16 v[24:27], v[200:203], v[212:215], v[24:27]
	v_mfma_f32_16x16x32_bf16 v[8:11], v[200:203], v[236:239], v[8:11]
	v_mfma_f32_16x16x32_bf16 v[32:35], v[220:223], v[176:179], v[130:133]
	v_mfma_f32_16x16x32_bf16 v[52:55], v[158:161], v[180:183], v[32:35]
	v_mfma_f32_16x16x32_bf16 v[32:35], v[224:227], v[176:179], v[164:167]
	v_mfma_f32_16x16x32_bf16 v[16:19], v[224:227], v[196:199], v[16:19]
	v_mfma_f32_16x16x32_bf16 v[48:51], v[232:235], v[180:183], v[32:35]
	v_mfma_f32_16x16x32_bf16 v[20:23], v[220:223], v[196:199], v[20:23]
	v_mfma_f32_16x16x32_bf16 v[32:35], v[232:235], v[204:207], v[16:19]
	v_mfma_f32_16x16x32_bf16 v[16:19], v[220:223], v[208:211], v[168:171]
	v_mfma_f32_16x16x32_bf16 v[36:39], v[158:161], v[204:207], v[20:23]
	v_mfma_f32_16x16x32_bf16 v[20:23], v[158:161], v[212:215], v[16:19]
	v_mfma_f32_16x16x32_bf16 v[16:19], v[224:227], v[208:211], v[172:175]
	v_mfma_f32_16x16x32_bf16 v[4:7], v[220:223], v[228:231], v[4:7]
	v_mfma_f32_16x16x32_bf16 v[0:3], v[224:227], v[228:231], v[0:3]
	v_mfma_f32_16x16x32_bf16 v[16:19], v[232:235], v[212:215], v[16:19]
	v_mfma_f32_16x16x32_bf16 v[4:7], v[158:161], v[236:239], v[4:7]
	v_mfma_f32_16x16x32_bf16 v[0:3], v[232:235], v[236:239], v[0:3]
	s_andn2_b64 vcc, exec, s[62:63]
	s_barrier
	s_cbranch_vccnz .LBB0_382
	s_barrier

; #define WAIT_V(n) asm volatile("s_waitcnt vmcnt(%0)" ::"n"(n) : "memory")
; #define WAIT_L(n) asm volatile("s_waitcnt lgkmcnt(%0)" ::"n"(n) : "memory")
; #define SBAR() __builtin_amdgcn_sched_barrier(0)
; #define STAGE(P, base, kt) do { _Pragma("unroll") for (int _i = 0; _i < 2; ++_i)                                        \
;       __builtin_amdgcn_global_load_lds((const unsigned*)((base) + (size_t)(sOff[_i] + (unsigned)(kt) * (BK * 2))),        \
;                                        (unsigned*)((P) + wid * 1024 + _i * 8192), 16, 0, 0); } while (0)
; #define LDA(dst, b, h) _Pragma("unroll") for (int m = 0; m < 4; ++m) _Pragma("unroll") for (int k = 0; k < 2; ++k) \
;       dst[m][k] = *(const bf16x8*)(SA(b, h) + aoff + (m * 2048 + k * 1024))
; #define LDB(dst, b, h) _Pragma("unroll") for (int n = 0; n < 2; ++n) _Pragma("unroll") for (int k = 0; k < 2; ++k) \
;       dst[n][k] = *(const bf16x8*)(SB(b, h) + boff + (n * 256 + k * 1024))
; #define BAR __builtin_amdgcn_s_barrier()
; template <int EPI, int N, int K>
; __device__ __forceinline__ void phase_gemm(const Params& p, const u16* __restrict__ A, const u16* __restrict__ Bt, int nM, char* shm,
;                            u16* __restrict__ outp, float* __restrict__ rowss) {
;     ...
;     for (int t = 0; t < nt - 2; t += 2) {
;       LDB(B0, 0, 0); SBAR(); LDA(At, 0, 0); STAGE(SA(1, 1), A1, t + 1);
;       WAIT_L(8); BAR; WAIT_L(0); MMA(0, 0, At, B0); BAR; SBAR();
;       LDB(B1, 0, 1); STAGE(SB(0, 0), B0p, t + 2);
;       BAR; WAIT_L(0); MMA(0, 1, At, B1); BAR;
;       LDA(At, 0, 1); STAGE(SA(0, 0), A0, t + 2);
;       BAR; WAIT_L(0); MMA(1, 0, At, B0); BAR; SBAR();
;       STAGE(SB(0, 1), B1p, t + 2);
;       WAIT_V(6); BAR; MMA(1, 1, At, B1); BAR;
.LBB0_433:
	v_or_b32_e32 v143, 0x10000, v145
	v_add_u32_e32 v150, 0x10100, v145
	v_add_u32_e32 v149, 0x10400, v145
	ds_read_b128 v[156:159], v143
	ds_read_b128 v[160:163], v149
	v_add_u32_e32 v151, 0x10500, v145
	ds_read_b128 v[164:167], v150
	ds_read_b128 v[168:171], v151
	v_add_u32_e32 v204, v144, v96
	s_add_i32 s62, s5, 0xc000
	v_add_u32_e32 v152, 0x80, v204
	s_mov_b32 m0, s62
	v_add_u32_e32 v205, v144, v142
	s_add_i32 s23, s5, 0xe000
	ds_read_b128 v[172:175], v146
	ds_read_b128 v[176:179], v146 offset:1024
	ds_read_b128 v[180:183], v146 offset:2048
	ds_read_b128 v[196:199], v146 offset:3072
	ds_read_b128 v[200:203], v146 offset:4096
	ds_read_b128 v[208:211], v146 offset:5120
	ds_read_b128 v[212:215], v146 offset:6144
	ds_read_b128 v[216:219], v146 offset:7168
	global_load_lds_dwordx4 v152, s[16:17]
	v_add_u32_e32 v152, 0x80, v205
	s_mov_b32 m0, s23
	s_nop 0
	global_load_lds_dwordx4 v152, s[16:17]
	v_or_b32_e32 v152, 0x14000, v145
	v_add_u32_e32 v154, 0x14100, v145
	v_add_u32_e32 v153, 0x14400, v145
	ds_read_b128 v[220:223], v152
	ds_read_b128 v[224:227], v153
	v_add_u32_e32 v155, 0x14500, v145
	ds_read_b128 v[228:231], v154
	ds_read_b128 v[232:235], v155
	s_waitcnt vmcnt(8)
	s_waitcnt lgkmcnt(0)
	s_barrier
	v_mfma_f32_16x16x32_bf16 v[126:129], v[156:159], v[172:175], v[126:129]
	v_mfma_f32_16x16x32_bf16 v[122:125], v[164:167], v[172:175], v[122:125]
	v_mfma_f32_16x16x32_bf16 v[118:121], v[156:159], v[180:183], v[118:121]
	v_mfma_f32_16x16x32_bf16 v[114:117], v[164:167], v[180:183], v[114:117]
	v_mfma_f32_16x16x32_bf16 v[110:113], v[156:159], v[200:203], v[110:113]
	v_mfma_f32_16x16x32_bf16 v[106:109], v[164:167], v[200:203], v[106:109]
	v_mfma_f32_16x16x32_bf16 v[102:105], v[156:159], v[212:215], v[102:105]
	v_mfma_f32_16x16x32_bf16 v[98:101], v[164:167], v[212:215], v[98:101]
	v_mfma_f32_16x16x32_bf16 v[126:129], v[160:163], v[176:179], v[126:129]
	v_mfma_f32_16x16x32_bf16 v[122:125], v[168:171], v[176:179], v[122:125]
	v_mfma_f32_16x16x32_bf16 v[118:121], v[160:163], v[196:199], v[118:121]
	v_mfma_f32_16x16x32_bf16 v[114:117], v[168:171], v[196:199], v[114:117]
	v_mfma_f32_16x16x32_bf16 v[110:113], v[160:163], v[208:211], v[110:113]
	v_mfma_f32_16x16x32_bf16 v[106:109], v[168:171], v[208:211], v[106:109]
	v_mfma_f32_16x16x32_bf16 v[102:105], v[160:163], v[216:219], v[102:105]
	v_mfma_f32_16x16x32_bf16 v[98:101], v[168:171], v[216:219], v[98:101]
	v_mfma_f32_16x16x32_bf16 v[92:95], v[220:223], v[172:175], v[92:95]
	v_mfma_f32_16x16x32_bf16 v[88:91], v[228:231], v[172:175], v[88:91]
	v_mfma_f32_16x16x32_bf16 v[84:87], v[220:223], v[180:183], v[84:87]
	v_mfma_f32_16x16x32_bf16 v[80:83], v[228:231], v[180:183], v[80:83]
	v_mfma_f32_16x16x32_bf16 v[76:79], v[220:223], v[200:203], v[76:79]
	v_mfma_f32_16x16x32_bf16 v[72:75], v[228:231], v[200:203], v[72:75]
	v_mfma_f32_16x16x32_bf16 v[68:71], v[220:223], v[212:215], v[68:71]
	v_mfma_f32_16x16x32_bf16 v[64:67], v[228:231], v[212:215], v[64:67]
	v_mfma_f32_16x16x32_bf16 v[92:95], v[224:227], v[176:179], v[92:95]
	v_mfma_f32_16x16x32_bf16 v[88:91], v[232:235], v[176:179], v[88:91]
	v_mfma_f32_16x16x32_bf16 v[84:87], v[224:227], v[196:199], v[84:87]
	v_mfma_f32_16x16x32_bf16 v[80:83], v[232:235], v[196:199], v[80:83]
	v_mfma_f32_16x16x32_bf16 v[76:79], v[224:227], v[208:211], v[76:79]
	v_mfma_f32_16x16x32_bf16 v[72:75], v[232:235], v[208:211], v[72:75]
	v_mfma_f32_16x16x32_bf16 v[68:71], v[224:227], v[216:219], v[68:71]
	v_mfma_f32_16x16x32_bf16 v[64:67], v[232:235], v[216:219], v[64:67]
	s_barrier
	ds_read_b128 v[172:175], v146 offset:16384
	ds_read_b128 v[176:179], v146 offset:17408
	ds_read_b128 v[180:183], v146 offset:18432
	ds_read_b128 v[196:199], v146 offset:19456
	ds_read_b128 v[200:203], v146 offset:20480
	ds_read_b128 v[208:211], v146 offset:21504
	ds_read_b128 v[212:215], v146 offset:22528
	ds_read_b128 v[216:219], v146 offset:23552
	s_mov_b32 m0, s25
	v_add_u32_e32 v206, 0x100, v204
	global_load_lds_dwordx4 v206, s[8:9]
	v_add_u32_e32 v207, 0x100, v205
	s_mov_b32 m0, s26
	s_nop 0
	global_load_lds_dwordx4 v207, s[8:9]
	s_mov_b32 m0, s5
	s_nop 0
	global_load_lds_dwordx4 v206, s[10:11]
	s_mov_b32 m0, s24
	s_nop 0
	global_load_lds_dwordx4 v207, s[10:11]
	s_mov_b32 m0, s27
	s_nop 0
	global_load_lds_dwordx4 v206, s[18:19]
	s_mov_b32 m0, s28
	s_nop 0
	global_load_lds_dwordx4 v207, s[18:19]
	s_waitcnt vmcnt(8)
	s_waitcnt lgkmcnt(0)
	s_barrier
	v_mfma_f32_16x16x32_bf16 v[60:63], v[156:159], v[172:175], v[60:63]
	v_mfma_f32_16x16x32_bf16 v[56:59], v[164:167], v[172:175], v[56:59]
	v_mfma_f32_16x16x32_bf16 v[52:55], v[156:159], v[180:183], v[52:55]
	v_mfma_f32_16x16x32_bf16 v[48:51], v[164:167], v[180:183], v[48:51]
	v_mfma_f32_16x16x32_bf16 v[44:47], v[156:159], v[200:203], v[44:47]
	v_mfma_f32_16x16x32_bf16 v[40:43], v[164:167], v[200:203], v[40:43]
	v_mfma_f32_16x16x32_bf16 v[36:39], v[156:159], v[212:215], v[36:39]
	v_mfma_f32_16x16x32_bf16 v[32:35], v[164:167], v[212:215], v[32:35]
	v_mfma_f32_16x16x32_bf16 v[60:63], v[160:163], v[176:179], v[60:63]
	v_mfma_f32_16x16x32_bf16 v[56:59], v[168:171], v[176:179], v[56:59]
	v_mfma_f32_16x16x32_bf16 v[52:55], v[160:163], v[196:199], v[52:55]
	v_mfma_f32_16x16x32_bf16 v[48:51], v[168:171], v[196:199], v[48:51]
	v_mfma_f32_16x16x32_bf16 v[44:47], v[160:163], v[208:211], v[44:47]
	v_mfma_f32_16x16x32_bf16 v[40:43], v[168:171], v[208:211], v[40:43]
	v_mfma_f32_16x16x32_bf16 v[36:39], v[160:163], v[216:219], v[36:39]
	v_mfma_f32_16x16x32_bf16 v[32:35], v[168:171], v[216:219], v[32:35]
	v_mfma_f32_16x16x32_bf16 v[28:31], v[220:223], v[172:175], v[28:31]
	v_mfma_f32_16x16x32_bf16 v[24:27], v[228:231], v[172:175], v[24:27]
	v_mfma_f32_16x16x32_bf16 v[20:23], v[220:223], v[180:183], v[20:23]
	v_mfma_f32_16x16x32_bf16 v[16:19], v[228:231], v[180:183], v[16:19]
	v_mfma_f32_16x16x32_bf16 v[12:15], v[220:223], v[200:203], v[12:15]
	v_mfma_f32_16x16x32_bf16 v[8:11], v[228:231], v[200:203], v[8:11]
	v_mfma_f32_16x16x32_bf16 v[4:7], v[220:223], v[212:215], v[4:7]
	v_mfma_f32_16x16x32_bf16 v[0:3], v[228:231], v[212:215], v[0:3]
	v_mfma_f32_16x16x32_bf16 v[28:31], v[224:227], v[176:179], v[28:31]
	v_mfma_f32_16x16x32_bf16 v[24:27], v[232:235], v[176:179], v[24:27]
	v_mfma_f32_16x16x32_bf16 v[20:23], v[224:227], v[196:199], v[20:23]
	v_mfma_f32_16x16x32_bf16 v[16:19], v[232:235], v[196:199], v[16:19]
	v_mfma_f32_16x16x32_bf16 v[12:15], v[224:227], v[208:211], v[12:15]
	v_mfma_f32_16x16x32_bf16 v[8:11], v[232:235], v[208:211], v[8:11]
	v_mfma_f32_16x16x32_bf16 v[4:7], v[224:227], v[216:219], v[4:7]
	v_mfma_f32_16x16x32_bf16 v[0:3], v[232:235], v[216:219], v[0:3]
	v_or_b32_e32 v156, 0x18000, v145
	v_add_u32_e32 v158, 0x18100, v145
	s_barrier
; #define WAIT_V(n) asm volatile("s_waitcnt vmcnt(%0)" ::"n"(n) : "memory")
; #define WAIT_L(n) asm volatile("s_waitcnt lgkmcnt(%0)" ::"n"(n) : "memory")
; #define SBAR() __builtin_amdgcn_sched_barrier(0)
; #define STAGE(P, base, kt) do { _Pragma("unroll") for (int _i = 0; _i < 2; ++_i)                                        \
;       __builtin_amdgcn_global_load_lds((const unsigned*)((base) + (size_t)(sOff[_i] + (unsigned)(kt) * (BK * 2))),        \
;                                        (unsigned*)((P) + wid * 1024 + _i * 8192), 16, 0, 0); } while (0)
; #define LDA(dst, b, h) _Pragma("unroll") for (int m = 0; m < 4; ++m) _Pragma("unroll") for (int k = 0; k < 2; ++k) \
;       dst[m][k] = *(const bf16x8*)(SA(b, h) + aoff + (m * 2048 + k * 1024))
; #define LDB(dst, b, h) _Pragma("unroll") for (int n = 0; n < 2; ++n) _Pragma("unroll") for (int k = 0; k < 2; ++k) \
;       dst[n][k] = *(const bf16x8*)(SB(b, h) + boff + (n * 256 + k * 1024))
; #define BAR __builtin_amdgcn_s_barrier()
; template <int EPI, int N, int K>
; __device__ __forceinline__ void phase_gemm(const Params& p, const u16* __restrict__ A, const u16* __restrict__ Bt, int nM, char* shm,
;                            u16* __restrict__ outp, float* __restrict__ rowss) {
;     ...
;       LDB(B0, 1, 0); SBAR(); LDA(At, 1, 0); STAGE(SA(0, 1), A1, t + 2);
;       WAIT_L(8); BAR; WAIT_L(0); MMA(0, 0, At, B0); BAR; SBAR();
;       LDB(B1, 1, 1); STAGE(SB(1, 0), B0p, t + 3);
;       BAR; WAIT_L(0); MMA(0, 1, At, B1); BAR;
;       LDA(At, 1, 1); STAGE(SA(1, 0), A0, t + 3);
;       BAR; WAIT_L(0); MMA(1, 0, At, B0); BAR; SBAR();
;       STAGE(SB(1, 1), B1p, t + 3);
;       WAIT_V(6); BAR; MMA(1, 1, At, B1); BAR;
;     }
	v_add_u32_e32 v157, 0x18400, v145
	ds_read_b128 v[164:167], v156
	ds_read_b128 v[168:171], v157
	v_add_u32_e32 v159, 0x18500, v145
	ds_read_b128 v[172:175], v158
	ds_read_b128 v[176:179], v159
	s_mov_b32 m0, s29
	ds_read_b128 v[180:183], v146 offset:32768
	ds_read_b128 v[196:199], v146 offset:33792
	ds_read_b128 v[200:203], v146 offset:34816
	ds_read_b128 v[208:211], v146 offset:35840
	ds_read_b128 v[212:215], v146 offset:36864
	ds_read_b128 v[216:219], v146 offset:37888
	ds_read_b128 v[220:223], v146 offset:38912
	ds_read_b128 v[224:227], v146 offset:39936
	global_load_lds_dwordx4 v206, s[16:17]
	s_mov_b32 m0, s30
	s_nop 0
	global_load_lds_dwordx4 v207, s[16:17]
	v_or_b32_e32 v160, 0x1c000, v145
	v_add_u32_e32 v162, 0x1c100, v145
	v_add_u32_e32 v161, 0x1c400, v145
	ds_read_b128 v[228:231], v160
	ds_read_b128 v[232:235], v161
	v_add_u32_e32 v163, 0x1c500, v145
	ds_read_b128 v[236:239], v162
	ds_read_b128 v[240:243], v163
	s_waitcnt vmcnt(8)
	s_waitcnt lgkmcnt(0)
	s_barrier
	v_mfma_f32_16x16x32_bf16 v[126:129], v[164:167], v[180:183], v[126:129]
	v_mfma_f32_16x16x32_bf16 v[122:125], v[172:175], v[180:183], v[122:125]
	v_mfma_f32_16x16x32_bf16 v[118:121], v[164:167], v[200:203], v[118:121]
	v_mfma_f32_16x16x32_bf16 v[114:117], v[172:175], v[200:203], v[114:117]
	v_mfma_f32_16x16x32_bf16 v[110:113], v[164:167], v[212:215], v[110:113]
	v_mfma_f32_16x16x32_bf16 v[106:109], v[172:175], v[212:215], v[106:109]
	v_mfma_f32_16x16x32_bf16 v[102:105], v[164:167], v[220:223], v[102:105]
	v_mfma_f32_16x16x32_bf16 v[98:101], v[172:175], v[220:223], v[98:101]
	v_mfma_f32_16x16x32_bf16 v[126:129], v[168:171], v[196:199], v[126:129]
	v_mfma_f32_16x16x32_bf16 v[122:125], v[176:179], v[196:199], v[122:125]
	v_mfma_f32_16x16x32_bf16 v[118:121], v[168:171], v[208:211], v[118:121]
	v_mfma_f32_16x16x32_bf16 v[114:117], v[176:179], v[208:211], v[114:117]
	v_mfma_f32_16x16x32_bf16 v[110:113], v[168:171], v[216:219], v[110:113]
	v_mfma_f32_16x16x32_bf16 v[106:109], v[176:179], v[216:219], v[106:109]
	v_mfma_f32_16x16x32_bf16 v[102:105], v[168:171], v[224:227], v[102:105]
	v_mfma_f32_16x16x32_bf16 v[98:101], v[176:179], v[224:227], v[98:101]
	v_mfma_f32_16x16x32_bf16 v[92:95], v[228:231], v[180:183], v[92:95]
	v_mfma_f32_16x16x32_bf16 v[88:91], v[236:239], v[180:183], v[88:91]
	v_mfma_f32_16x16x32_bf16 v[84:87], v[228:231], v[200:203], v[84:87]
	v_mfma_f32_16x16x32_bf16 v[80:83], v[236:239], v[200:203], v[80:83]
	v_mfma_f32_16x16x32_bf16 v[76:79], v[228:231], v[212:215], v[76:79]
	v_mfma_f32_16x16x32_bf16 v[72:75], v[236:239], v[212:215], v[72:75]
	v_mfma_f32_16x16x32_bf16 v[68:71], v[228:231], v[220:223], v[68:71]
	v_mfma_f32_16x16x32_bf16 v[64:67], v[236:239], v[220:223], v[64:67]
	v_mfma_f32_16x16x32_bf16 v[92:95], v[232:235], v[196:199], v[92:95]
	v_mfma_f32_16x16x32_bf16 v[88:91], v[240:243], v[196:199], v[88:91]
	v_mfma_f32_16x16x32_bf16 v[84:87], v[232:235], v[208:211], v[84:87]
	v_mfma_f32_16x16x32_bf16 v[80:83], v[240:243], v[208:211], v[80:83]
	v_mfma_f32_16x16x32_bf16 v[76:79], v[232:235], v[216:219], v[76:79]
	v_mfma_f32_16x16x32_bf16 v[72:75], v[240:243], v[216:219], v[72:75]
	v_mfma_f32_16x16x32_bf16 v[68:71], v[232:235], v[224:227], v[68:71]
	v_mfma_f32_16x16x32_bf16 v[64:67], v[240:243], v[224:227], v[64:67]
	s_barrier
	ds_read_b128 v[180:183], v146 offset:49152
	ds_read_b128 v[196:199], v146 offset:50176
	ds_read_b128 v[200:203], v146 offset:51200
	ds_read_b128 v[208:211], v146 offset:52224
	ds_read_b128 v[212:215], v146 offset:53248
	ds_read_b128 v[216:219], v146 offset:54272
	ds_read_b128 v[220:223], v146 offset:55296
	ds_read_b128 v[224:227], v146 offset:56320
	s_mov_b32 m0, s31
	v_add_u32_e32 v204, 0x180, v204
	global_load_lds_dwordx4 v204, s[8:9]
	v_add_u32_e32 v205, 0x180, v205
	s_mov_b32 m0, s33
	s_nop 0
	global_load_lds_dwordx4 v205, s[8:9]
	s_mov_b32 m0, s35
	s_nop 0
	global_load_lds_dwordx4 v204, s[10:11]
	s_mov_b32 m0, s52
	s_nop 0
	global_load_lds_dwordx4 v205, s[10:11]
	s_mov_b32 m0, s53
	s_nop 0
	global_load_lds_dwordx4 v204, s[18:19]
	s_mov_b32 m0, s54
	s_nop 0
	global_load_lds_dwordx4 v205, s[18:19]
	s_waitcnt vmcnt(8)
	s_waitcnt lgkmcnt(0)
	s_barrier
	v_mfma_f32_16x16x32_bf16 v[60:63], v[164:167], v[180:183], v[60:63]
	v_mfma_f32_16x16x32_bf16 v[56:59], v[172:175], v[180:183], v[56:59]
	v_mfma_f32_16x16x32_bf16 v[52:55], v[164:167], v[200:203], v[52:55]
	v_mfma_f32_16x16x32_bf16 v[48:51], v[172:175], v[200:203], v[48:51]
	v_mfma_f32_16x16x32_bf16 v[44:47], v[164:167], v[212:215], v[44:47]
	v_mfma_f32_16x16x32_bf16 v[40:43], v[172:175], v[212:215], v[40:43]
	v_mfma_f32_16x16x32_bf16 v[36:39], v[164:167], v[220:223], v[36:39]
	v_mfma_f32_16x16x32_bf16 v[32:35], v[172:175], v[220:223], v[32:35]
	v_mfma_f32_16x16x32_bf16 v[60:63], v[168:171], v[196:199], v[60:63]
	v_mfma_f32_16x16x32_bf16 v[56:59], v[176:179], v[196:199], v[56:59]
	v_mfma_f32_16x16x32_bf16 v[52:55], v[168:171], v[208:211], v[52:55]
	v_mfma_f32_16x16x32_bf16 v[48:51], v[176:179], v[208:211], v[48:51]
	v_mfma_f32_16x16x32_bf16 v[44:47], v[168:171], v[216:219], v[44:47]
	v_mfma_f32_16x16x32_bf16 v[40:43], v[176:179], v[216:219], v[40:43]
	v_mfma_f32_16x16x32_bf16 v[36:39], v[168:171], v[224:227], v[36:39]
	v_mfma_f32_16x16x32_bf16 v[32:35], v[176:179], v[224:227], v[32:35]
	v_mfma_f32_16x16x32_bf16 v[28:31], v[228:231], v[180:183], v[28:31]
	v_mfma_f32_16x16x32_bf16 v[24:27], v[236:239], v[180:183], v[24:27]
	v_mfma_f32_16x16x32_bf16 v[20:23], v[228:231], v[200:203], v[20:23]
	v_mfma_f32_16x16x32_bf16 v[16:19], v[236:239], v[200:203], v[16:19]
	v_mfma_f32_16x16x32_bf16 v[12:15], v[228:231], v[212:215], v[12:15]
	v_mfma_f32_16x16x32_bf16 v[8:11], v[236:239], v[212:215], v[8:11]
	v_mfma_f32_16x16x32_bf16 v[4:7], v[228:231], v[220:223], v[4:7]
	v_mfma_f32_16x16x32_bf16 v[0:3], v[236:239], v[220:223], v[0:3]
	v_mfma_f32_16x16x32_bf16 v[28:31], v[232:235], v[196:199], v[28:31]
	v_mfma_f32_16x16x32_bf16 v[24:27], v[240:243], v[196:199], v[24:27]
	v_mfma_f32_16x16x32_bf16 v[20:23], v[232:235], v[208:211], v[20:23]
	v_mfma_f32_16x16x32_bf16 v[16:19], v[240:243], v[208:211], v[16:19]
	v_mfma_f32_16x16x32_bf16 v[12:15], v[232:235], v[216:219], v[12:15]
	v_mfma_f32_16x16x32_bf16 v[8:11], v[240:243], v[216:219], v[8:11]
	v_mfma_f32_16x16x32_bf16 v[4:7], v[232:235], v[224:227], v[4:7]
	v_mfma_f32_16x16x32_bf16 v[0:3], v[240:243], v[224:227], v[0:3]
	s_add_i32 s22, s22, 2
	v_add_u32_e32 v142, 0x100, v142
	s_cmp_lt_u32 s22, 12
	v_add_u32_e32 v96, 0x100, v96
	s_barrier
; #define WAIT_V(n) asm volatile("s_waitcnt vmcnt(%0)" ::"n"(n) : "memory")
; #define WAIT_L(n) asm volatile("s_waitcnt lgkmcnt(%0)" ::"n"(n) : "memory")
; #define STAGE(P, base, kt) do { _Pragma("unroll") for (int _i = 0; _i < 2; ++_i)                                        \
;       __builtin_amdgcn_global_load_lds((const unsigned*)((base) + (size_t)(sOff[_i] + (unsigned)(kt) * (BK * 2))),        \
;                                        (unsigned*)((P) + wid * 1024 + _i * 8192), 16, 0, 0); } while (0)
; #define LDA(dst, b, h) _Pragma("unroll") for (int m = 0; m < 4; ++m) _Pragma("unroll") for (int k = 0; k < 2; ++k) \
;       dst[m][k] = *(const bf16x8*)(SA(b, h) + aoff + (m * 2048 + k * 1024))
; #define LDB(dst, b, h) _Pragma("unroll") for (int n = 0; n < 2; ++n) _Pragma("unroll") for (int k = 0; k < 2; ++k) \
;       dst[n][k] = *(const bf16x8*)(SB(b, h) + boff + (n * 256 + k * 1024))
; #define BAR __builtin_amdgcn_s_barrier()
; template <int EPI, int N, int K>
; __device__ __forceinline__ void phase_gemm(const Params& p, const u16* __restrict__ A, const u16* __restrict__ Bt, int nM, char* shm,
;                            u16* __restrict__ outp, float* __restrict__ rowss) {
;     ...
;     { LDB(B0, 0, 0); LDA(At, 0, 0); STAGE(SA(1, 1), A1, nt - 1);
;       BAR; WAIT_L(0); MMA(0, 0, At, B0); BAR;
;       LDB(B1, 0, 1); BAR; WAIT_L(0); MMA(0, 1, At, B1); BAR;
;       LDA(At, 0, 1); WAIT_V(4); BAR; WAIT_L(0); MMA(1, 0, At, B0); MMA(1, 1, At, B1); BAR; }
	s_cbranch_scc1 .LBB0_433
	s_waitcnt vmcnt(6)
	s_mov_b32 m0, s62
	ds_read_b128 v[164:167], v143
	ds_read_b128 v[168:171], v149
	ds_read_b128 v[172:175], v150
	ds_read_b128 v[176:179], v151
	ds_read_b128 v[180:183], v146
	ds_read_b128 v[196:199], v146 offset:1024
	ds_read_b128 v[200:203], v146 offset:2048
	ds_read_b128 v[208:211], v146 offset:3072
	ds_read_b128 v[212:215], v146 offset:4096
	ds_read_b128 v[216:219], v146 offset:5120
	ds_read_b128 v[220:223], v146 offset:6144
	ds_read_b128 v[224:227], v146 offset:7168
	v_lshl_add_u64 v[142:143], s[16:17], 0, v[138:139]
	global_load_lds_dwordx4 v[142:143], off
	v_lshl_add_u64 v[142:143], s[16:17], 0, v[140:141]
	s_mov_b32 m0, s23
	s_nop 0
	global_load_lds_dwordx4 v[142:143], off
	s_barrier
	s_waitcnt lgkmcnt(0)
	s_waitcnt lgkmcnt(0)
	v_mfma_f32_16x16x32_bf16 v[126:129], v[164:167], v[180:183], v[126:129]
	v_mfma_f32_16x16x32_bf16 v[122:125], v[172:175], v[180:183], v[122:125]
	v_mfma_f32_16x16x32_bf16 v[110:113], v[164:167], v[212:215], v[110:113]
	v_mfma_f32_16x16x32_bf16 v[106:109], v[172:175], v[212:215], v[106:109]
	v_mfma_f32_16x16x32_bf16 v[126:129], v[168:171], v[196:199], v[126:129]
	v_mfma_f32_16x16x32_bf16 v[122:125], v[176:179], v[196:199], v[122:125]
	v_mfma_f32_16x16x32_bf16 v[118:121], v[164:167], v[200:203], v[118:121]
	v_mfma_f32_16x16x32_bf16 v[114:117], v[172:175], v[200:203], v[114:117]
	v_mfma_f32_16x16x32_bf16 v[110:113], v[168:171], v[216:219], v[110:113]
	v_mfma_f32_16x16x32_bf16 v[106:109], v[176:179], v[216:219], v[106:109]
	v_mfma_f32_16x16x32_bf16 v[102:105], v[164:167], v[220:223], v[102:105]
	v_mfma_f32_16x16x32_bf16 v[98:101], v[172:175], v[220:223], v[98:101]
	v_mfma_f32_16x16x32_bf16 v[228:231], v[168:171], v[208:211], v[118:121]
	v_mfma_f32_16x16x32_bf16 v[232:235], v[176:179], v[208:211], v[114:117]
	v_mfma_f32_16x16x32_bf16 v[236:239], v[168:171], v[224:227], v[102:105]
	v_mfma_f32_16x16x32_bf16 v[240:243], v[176:179], v[224:227], v[98:101]
	s_barrier
	s_nop 1
	ds_read_b128 v[98:101], v152
	ds_read_b128 v[102:105], v153
	ds_read_b128 v[114:117], v154
	ds_read_b128 v[118:121], v155
	s_barrier
	s_waitcnt lgkmcnt(0)
	s_waitcnt lgkmcnt(0)
	v_mfma_f32_16x16x32_bf16 v[92:95], v[98:101], v[180:183], v[92:95]
	v_mfma_f32_16x16x32_bf16 v[88:91], v[114:117], v[180:183], v[88:91]
	v_mfma_f32_16x16x32_bf16 v[76:79], v[98:101], v[212:215], v[76:79]
	v_mfma_f32_16x16x32_bf16 v[72:75], v[114:117], v[212:215], v[72:75]
	v_mfma_f32_16x16x32_bf16 v[68:71], v[98:101], v[220:223], v[68:71]
	v_mfma_f32_16x16x32_bf16 v[64:67], v[114:117], v[220:223], v[64:67]
	v_mfma_f32_16x16x32_bf16 v[92:95], v[102:105], v[196:199], v[92:95]
	v_mfma_f32_16x16x32_bf16 v[88:91], v[118:121], v[196:199], v[88:91]
	v_mfma_f32_16x16x32_bf16 v[84:87], v[98:101], v[200:203], v[84:87]
	v_mfma_f32_16x16x32_bf16 v[80:83], v[114:117], v[200:203], v[80:83]
	v_mfma_f32_16x16x32_bf16 v[76:79], v[102:105], v[216:219], v[76:79]
	v_mfma_f32_16x16x32_bf16 v[72:75], v[118:121], v[216:219], v[72:75]
	v_mfma_f32_16x16x32_bf16 v[68:71], v[102:105], v[224:227], v[68:71]
	v_mfma_f32_16x16x32_bf16 v[64:67], v[118:121], v[224:227], v[64:67]
	v_mfma_f32_16x16x32_bf16 v[150:153], v[102:105], v[208:211], v[84:87]
	v_mfma_f32_16x16x32_bf16 v[180:183], v[118:121], v[208:211], v[80:83]
	s_barrier
	s_nop 0
	ds_read_b128 v[80:83], v146 offset:16384
	ds_read_b128 v[84:87], v146 offset:17408
	ds_read_b128 v[196:199], v146 offset:18432
	ds_read_b128 v[200:203], v146 offset:19456
	ds_read_b128 v[208:211], v146 offset:20480
	ds_read_b128 v[212:215], v146 offset:21504
	ds_read_b128 v[216:219], v146 offset:22528
	ds_read_b128 v[220:223], v146 offset:23552
	s_waitcnt vmcnt(4)
	s_barrier
	s_waitcnt lgkmcnt(0)
	s_waitcnt lgkmcnt(0)
	v_mfma_f32_16x16x32_bf16 v[56:59], v[172:175], v[80:83], v[56:59]
	v_mfma_f32_16x16x32_bf16 v[52:55], v[164:167], v[196:199], v[52:55]
	v_mfma_f32_16x16x32_bf16 v[40:43], v[172:175], v[208:211], v[40:43]
	v_mfma_f32_16x16x32_bf16 v[32:35], v[172:175], v[216:219], v[32:35]
	v_mfma_f32_16x16x32_bf16 v[60:63], v[164:167], v[80:83], v[60:63]
	v_mfma_f32_16x16x32_bf16 v[56:59], v[176:179], v[84:87], v[56:59]
	v_mfma_f32_16x16x32_bf16 v[52:55], v[168:171], v[200:203], v[52:55]
	v_mfma_f32_16x16x32_bf16 v[48:51], v[172:175], v[196:199], v[48:51]
	v_mfma_f32_16x16x32_bf16 v[44:47], v[164:167], v[208:211], v[44:47]
	v_mfma_f32_16x16x32_bf16 v[40:43], v[176:179], v[212:215], v[40:43]
	v_mfma_f32_16x16x32_bf16 v[36:39], v[164:167], v[216:219], v[36:39]
	v_mfma_f32_16x16x32_bf16 v[32:35], v[176:179], v[220:223], v[32:35]
	v_mfma_f32_16x16x32_bf16 v[224:227], v[168:171], v[84:87], v[60:63]
	v_mfma_f32_16x16x32_bf16 v[244:247], v[176:179], v[200:203], v[48:51]
	v_mfma_f32_16x16x32_bf16 v[248:251], v[168:171], v[212:215], v[44:47]
	v_mfma_f32_16x16x32_bf16 v[164:167], v[168:171], v[220:223], v[36:39]
	v_mfma_f32_16x16x32_bf16 v[24:27], v[114:117], v[80:83], v[24:27]
	v_mfma_f32_16x16x32_bf16 v[16:19], v[114:117], v[196:199], v[16:19]
	v_mfma_f32_16x16x32_bf16 v[8:11], v[114:117], v[208:211], v[8:11]
	v_mfma_f32_16x16x32_bf16 v[0:3], v[114:117], v[216:219], v[0:3]
	v_mfma_f32_16x16x32_bf16 v[28:31], v[98:101], v[80:83], v[28:31]
	v_mfma_f32_16x16x32_bf16 v[24:27], v[118:121], v[84:87], v[24:27]
	v_mfma_f32_16x16x32_bf16 v[20:23], v[98:101], v[196:199], v[20:23]
	v_mfma_f32_16x16x32_bf16 v[16:19], v[118:121], v[200:203], v[16:19]
	v_mfma_f32_16x16x32_bf16 v[12:15], v[98:101], v[208:211], v[12:15]
	v_mfma_f32_16x16x32_bf16 v[8:11], v[118:121], v[212:215], v[8:11]
	v_mfma_f32_16x16x32_bf16 v[4:7], v[98:101], v[216:219], v[4:7]
	v_mfma_f32_16x16x32_bf16 v[0:3], v[118:121], v[220:223], v[0:3]
	v_mfma_f32_16x16x32_bf16 v[168:171], v[102:105], v[84:87], v[28:31]
	v_mfma_f32_16x16x32_bf16 v[172:175], v[102:105], v[200:203], v[20:23]
	v_mfma_f32_16x16x32_bf16 v[176:179], v[102:105], v[212:215], v[12:15]
	v_mfma_f32_16x16x32_bf16 v[196:199], v[102:105], v[220:223], v[4:7]
	s_barrier
; #define WAIT_V(n) asm volatile("s_waitcnt vmcnt(%0)" ::"n"(n) : "memory")
; #define WAIT_L(n) asm volatile("s_waitcnt lgkmcnt(%0)" ::"n"(n) : "memory")
; #define LDA(dst, b, h) _Pragma("unroll") for (int m = 0; m < 4; ++m) _Pragma("unroll") for (int k = 0; k < 2; ++k) \
;       dst[m][k] = *(const bf16x8*)(SA(b, h) + aoff + (m * 2048 + k * 1024))
; #define LDB(dst, b, h) _Pragma("unroll") for (int n = 0; n < 2; ++n) _Pragma("unroll") for (int k = 0; k < 2; ++k) \
;       dst[n][k] = *(const bf16x8*)(SB(b, h) + boff + (n * 256 + k * 1024))
; #define BAR __builtin_amdgcn_s_barrier()
; template <int EPI, int N, int K>
; __device__ __forceinline__ void phase_gemm(const Params& p, const u16* __restrict__ A, const u16* __restrict__ Bt, int nM, char* shm,
;                            u16* __restrict__ outp, float* __restrict__ rowss) {
;     ...
;     { LDB(B0, 1, 0); LDA(At, 1, 0); WAIT_V(2); BAR; WAIT_L(0); MMA(0, 0, At, B0); BAR;
;       LDB(B1, 1, 1); WAIT_V(0); BAR; WAIT_L(0); MMA(0, 1, At, B1); BAR;
;       LDA(At, 1, 1); BAR; WAIT_L(0); MMA(1, 0, At, B0); MMA(1, 1, At, B1); BAR; }
;     if (wr == 0) BAR;
	s_nop 0
	ds_read_b128 v[4:7], v156
	ds_read_b128 v[12:15], v157
	ds_read_b128 v[154:157], v158
	ds_read_b128 v[200:203], v159
	ds_read_b128 v[20:23], v146 offset:32768
	ds_read_b128 v[28:31], v146 offset:33792
	ds_read_b128 v[36:39], v146 offset:34816
	ds_read_b128 v[44:47], v146 offset:35840
	ds_read_b128 v[208:211], v146 offset:36864
	ds_read_b128 v[212:215], v146 offset:37888
	ds_read_b128 v[216:219], v146 offset:38912
	ds_read_b128 v[220:223], v146 offset:39936
	s_waitcnt vmcnt(2)
	s_barrier
	s_waitcnt lgkmcnt(0)
	s_waitcnt lgkmcnt(0)
	v_mfma_f32_16x16x32_bf16 v[48:51], v[4:7], v[20:23], v[126:129]
	v_mfma_f32_16x16x32_bf16 v[118:121], v[12:15], v[28:31], v[48:51]
	v_mfma_f32_16x16x32_bf16 v[48:51], v[154:157], v[20:23], v[122:125]
	v_mfma_f32_16x16x32_bf16 v[114:117], v[200:203], v[28:31], v[48:51]
	v_mfma_f32_16x16x32_bf16 v[48:51], v[4:7], v[36:39], v[228:231]
	v_mfma_f32_16x16x32_bf16 v[102:105], v[12:15], v[44:47], v[48:51]
	v_mfma_f32_16x16x32_bf16 v[48:51], v[154:157], v[36:39], v[232:235]
	v_mfma_f32_16x16x32_bf16 v[98:101], v[200:203], v[44:47], v[48:51]
	v_mfma_f32_16x16x32_bf16 v[48:51], v[4:7], v[208:211], v[110:113]
	v_mfma_f32_16x16x32_bf16 v[84:87], v[12:15], v[212:215], v[48:51]
	v_mfma_f32_16x16x32_bf16 v[48:51], v[154:157], v[208:211], v[106:109]
	v_mfma_f32_16x16x32_bf16 v[80:83], v[200:203], v[212:215], v[48:51]
	v_mfma_f32_16x16x32_bf16 v[48:51], v[4:7], v[216:219], v[236:239]
	v_mfma_f32_16x16x32_bf16 v[60:63], v[12:15], v[220:223], v[48:51]
	v_mfma_f32_16x16x32_bf16 v[48:51], v[154:157], v[216:219], v[240:243]
	v_mfma_f32_16x16x32_bf16 v[48:51], v[200:203], v[220:223], v[48:51]
	s_barrier
	ds_read_b128 v[228:231], v160
	ds_read_b128 v[158:161], v161
	ds_read_b128 v[232:235], v162
	ds_read_b128 v[236:239], v163
	s_waitcnt vmcnt(0)
	s_barrier
	s_waitcnt lgkmcnt(0)
	s_waitcnt lgkmcnt(0)
	v_mfma_f32_16x16x32_bf16 v[92:95], v[228:231], v[20:23], v[92:95]
	v_mfma_f32_16x16x32_bf16 v[20:23], v[232:235], v[20:23], v[88:91]
	v_mfma_f32_16x16x32_bf16 v[122:125], v[236:239], v[28:31], v[20:23]
	v_mfma_f32_16x16x32_bf16 v[20:23], v[228:231], v[36:39], v[150:153]
	v_mfma_f32_16x16x32_bf16 v[110:113], v[158:161], v[44:47], v[20:23]
	v_mfma_f32_16x16x32_bf16 v[20:23], v[232:235], v[36:39], v[180:183]
	v_mfma_f32_16x16x32_bf16 v[106:109], v[236:239], v[44:47], v[20:23]
	v_mfma_f32_16x16x32_bf16 v[20:23], v[228:231], v[208:211], v[76:79]
	v_mfma_f32_16x16x32_bf16 v[126:129], v[158:161], v[28:31], v[92:95]
	v_mfma_f32_16x16x32_bf16 v[92:95], v[158:161], v[212:215], v[20:23]
	v_mfma_f32_16x16x32_bf16 v[20:23], v[232:235], v[208:211], v[72:75]
	v_mfma_f32_16x16x32_bf16 v[88:91], v[236:239], v[212:215], v[20:23]
	v_mfma_f32_16x16x32_bf16 v[20:23], v[228:231], v[216:219], v[68:71]
	v_mfma_f32_16x16x32_bf16 v[76:79], v[158:161], v[220:223], v[20:23]
	v_mfma_f32_16x16x32_bf16 v[20:23], v[232:235], v[216:219], v[64:67]
	v_mfma_f32_16x16x32_bf16 v[64:67], v[236:239], v[220:223], v[20:23]
	s_barrier
	ds_read_b128 v[150:153], v146 offset:49152
	ds_read_b128 v[180:183], v146 offset:50176
	ds_read_b128 v[208:211], v146 offset:51200
	ds_read_b128 v[212:215], v146 offset:52224
	ds_read_b128 v[216:219], v146 offset:53248
	ds_read_b128 v[220:223], v146 offset:54272
	ds_read_b128 v[240:243], v146 offset:55296
	ds_read_b128 v[204:207], v146 offset:56320
	s_barrier
	s_waitcnt lgkmcnt(0)
	s_waitcnt lgkmcnt(0)
	v_mfma_f32_16x16x32_bf16 v[20:23], v[4:7], v[150:153], v[224:227]
	v_mfma_f32_16x16x32_bf16 v[72:75], v[12:15], v[180:183], v[20:23]
	v_mfma_f32_16x16x32_bf16 v[20:23], v[154:157], v[150:153], v[56:59]
	v_mfma_f32_16x16x32_bf16 v[56:59], v[200:203], v[180:183], v[20:23]
	v_mfma_f32_16x16x32_bf16 v[20:23], v[4:7], v[208:211], v[52:55]
	v_mfma_f32_16x16x32_bf16 v[44:47], v[12:15], v[212:215], v[20:23]
	v_mfma_f32_16x16x32_bf16 v[20:23], v[154:157], v[208:211], v[244:247]
	v_mfma_f32_16x16x32_bf16 v[36:39], v[200:203], v[212:215], v[20:23]
	v_mfma_f32_16x16x32_bf16 v[20:23], v[4:7], v[216:219], v[248:251]
	v_mfma_f32_16x16x32_bf16 v[4:7], v[4:7], v[240:243], v[164:167]
	v_mfma_f32_16x16x32_bf16 v[28:31], v[12:15], v[220:223], v[20:23]
	v_mfma_f32_16x16x32_bf16 v[20:23], v[154:157], v[216:219], v[40:43]
	v_mfma_f32_16x16x32_bf16 v[12:15], v[12:15], v[204:207], v[4:7]
	v_mfma_f32_16x16x32_bf16 v[4:7], v[154:157], v[240:243], v[32:35]
	v_mfma_f32_16x16x32_bf16 v[20:23], v[200:203], v[220:223], v[20:23]
	v_mfma_f32_16x16x32_bf16 v[4:7], v[200:203], v[204:207], v[4:7]
	v_mfma_f32_16x16x32_bf16 v[32:35], v[228:231], v[150:153], v[168:171]
	v_mfma_f32_16x16x32_bf16 v[24:27], v[232:235], v[150:153], v[24:27]
	v_mfma_f32_16x16x32_bf16 v[16:19], v[232:235], v[208:211], v[16:19]
	v_mfma_f32_16x16x32_bf16 v[68:71], v[158:161], v[180:183], v[32:35]
	v_mfma_f32_16x16x32_bf16 v[52:55], v[236:239], v[180:183], v[24:27]
	v_mfma_f32_16x16x32_bf16 v[24:27], v[228:231], v[208:211], v[172:175]
	v_mfma_f32_16x16x32_bf16 v[32:35], v[236:239], v[212:215], v[16:19]
	v_mfma_f32_16x16x32_bf16 v[16:19], v[228:231], v[216:219], v[176:179]
	v_mfma_f32_16x16x32_bf16 v[8:11], v[232:235], v[216:219], v[8:11]
	v_mfma_f32_16x16x32_bf16 v[40:43], v[158:161], v[212:215], v[24:27]
	v_mfma_f32_16x16x32_bf16 v[24:27], v[158:161], v[220:223], v[16:19]
	v_mfma_f32_16x16x32_bf16 v[16:19], v[236:239], v[220:223], v[8:11]
	v_mfma_f32_16x16x32_bf16 v[8:11], v[228:231], v[240:243], v[196:199]
	v_mfma_f32_16x16x32_bf16 v[0:3], v[232:235], v[240:243], v[0:3]
	v_mfma_f32_16x16x32_bf16 v[8:11], v[158:161], v[204:207], v[8:11]
	v_mfma_f32_16x16x32_bf16 v[0:3], v[236:239], v[204:207], v[0:3]
	s_andn2_b64 vcc, exec, s[56:57]
	s_barrier
	s_cbranch_vccnz .LBB0_436
	s_barrier

; #define WAIT_V(n) asm volatile("s_waitcnt vmcnt(%0)" ::"n"(n) : "memory")
; #define WAIT_L(n) asm volatile("s_waitcnt lgkmcnt(%0)" ::"n"(n) : "memory")
; #define SBAR() __builtin_amdgcn_sched_barrier(0)
; #define STAGE(P, base, kt) do { _Pragma("unroll") for (int _i = 0; _i < 2; ++_i)                                        \
;       __builtin_amdgcn_global_load_lds((const unsigned*)((base) + (size_t)(sOff[_i] + (unsigned)(kt) * (BK * 2))),        \
;                                        (unsigned*)((P) + wid * 1024 + _i * 8192), 16, 0, 0); } while (0)
; #define LDA(dst, b, h) _Pragma("unroll") for (int m = 0; m < 4; ++m) _Pragma("unroll") for (int k = 0; k < 2; ++k) \
;       dst[m][k] = *(const bf16x8*)(SA(b, h) + aoff + (m * 2048 + k * 1024))
; #define LDB(dst, b, h) _Pragma("unroll") for (int n = 0; n < 2; ++n) _Pragma("unroll") for (int k = 0; k < 2; ++k) \
;       dst[n][k] = *(const bf16x8*)(SB(b, h) + boff + (n * 256 + k * 1024))
; #define BAR __builtin_amdgcn_s_barrier()
; template <int EPI, int N, int K>
; __device__ __forceinline__ void phase_gemm(const Params& p, const u16* __restrict__ A, const u16* __restrict__ Bt, int nM, char* shm,
;                            u16* __restrict__ outp, float* __restrict__ rowss) {
;     ...
;   for (;;) {
;     const char* A1 = A0 + (size_t)128 * K * 2;
;     const char* B1p = B0p + (size_t)128 * K * 2;
;     f32x4 acc[2][2][4][2] = {};
;     bf16x8 At[4][2], B0[2][2], B1[2][2];
;     if (wr == 1) BAR;
;     WAIT_V(0); BAR;
;     BAR;
;     for (int t = 0; t < nt - 2; t += 2) {
;       LDB(B0, 0, 0); SBAR(); LDA(At, 0, 0); STAGE(SA(1, 1), A1, t + 1);
;       WAIT_L(8); BAR; WAIT_L(0); MMA(0, 0, At, B0); BAR; SBAR();
;       LDB(B1, 0, 1); STAGE(SB(0, 0), B0p, t + 2);
;       BAR; WAIT_L(0); MMA(0, 1, At, B1); BAR;
;       LDA(At, 0, 1); STAGE(SA(0, 0), A0, t + 2);
;       BAR; WAIT_L(0); MMA(1, 0, At, B0); BAR; SBAR();
;       STAGE(SB(0, 1), B1p, t + 2);
;       WAIT_V(6); BAR; MMA(1, 1, At, B1); BAR;
.LBB0_517:
	v_or_b32_e32 v143, 0x10000, v146
	v_add_u32_e32 v145, 0x10100, v146
	v_add_u32_e32 v144, 0x10400, v146
	ds_read_b128 v[156:159], v143
	ds_read_b128 v[160:163], v144
	v_add_u32_e32 v151, 0x10500, v146
	ds_read_b128 v[164:167], v145
	ds_read_b128 v[168:171], v151
	v_add_u32_e32 v204, v148, v96
	s_add_i32 s60, s25, 0xc000
	v_add_u32_e32 v152, 0x80, v204
	s_mov_b32 m0, s60
	v_add_u32_e32 v205, v148, v142
	s_add_i32 s59, s25, 0xe000
	ds_read_b128 v[172:175], v147
	ds_read_b128 v[176:179], v147 offset:1024
	ds_read_b128 v[180:183], v147 offset:2048
	ds_read_b128 v[196:199], v147 offset:3072
	ds_read_b128 v[200:203], v147 offset:4096
	ds_read_b128 v[208:211], v147 offset:5120
	ds_read_b128 v[212:215], v147 offset:6144
	ds_read_b128 v[216:219], v147 offset:7168
	global_load_lds_dwordx4 v152, s[4:5]
	v_add_u32_e32 v152, 0x80, v205
	s_mov_b32 m0, s59
	s_nop 0
	global_load_lds_dwordx4 v152, s[4:5]
	v_or_b32_e32 v152, 0x14000, v146
	v_add_u32_e32 v154, 0x14100, v146
	v_add_u32_e32 v153, 0x14400, v146
	ds_read_b128 v[220:223], v152
	ds_read_b128 v[224:227], v153
	v_add_u32_e32 v155, 0x14500, v146
	ds_read_b128 v[228:231], v154
	ds_read_b128 v[232:235], v155
	s_waitcnt vmcnt(8)
	s_waitcnt lgkmcnt(0)
	s_barrier
	v_mfma_f32_16x16x32_bf16 v[126:129], v[156:159], v[172:175], v[126:129]
	v_mfma_f32_16x16x32_bf16 v[122:125], v[164:167], v[172:175], v[122:125]
	v_mfma_f32_16x16x32_bf16 v[118:121], v[156:159], v[180:183], v[118:121]
	v_mfma_f32_16x16x32_bf16 v[114:117], v[164:167], v[180:183], v[114:117]
	v_mfma_f32_16x16x32_bf16 v[110:113], v[156:159], v[200:203], v[110:113]
	v_mfma_f32_16x16x32_bf16 v[106:109], v[164:167], v[200:203], v[106:109]
	v_mfma_f32_16x16x32_bf16 v[102:105], v[156:159], v[212:215], v[102:105]
	v_mfma_f32_16x16x32_bf16 v[98:101], v[164:167], v[212:215], v[98:101]
	v_mfma_f32_16x16x32_bf16 v[126:129], v[160:163], v[176:179], v[126:129]
	v_mfma_f32_16x16x32_bf16 v[122:125], v[168:171], v[176:179], v[122:125]
	v_mfma_f32_16x16x32_bf16 v[118:121], v[160:163], v[196:199], v[118:121]
	v_mfma_f32_16x16x32_bf16 v[114:117], v[168:171], v[196:199], v[114:117]
	v_mfma_f32_16x16x32_bf16 v[110:113], v[160:163], v[208:211], v[110:113]
	v_mfma_f32_16x16x32_bf16 v[106:109], v[168:171], v[208:211], v[106:109]
	v_mfma_f32_16x16x32_bf16 v[102:105], v[160:163], v[216:219], v[102:105]
	v_mfma_f32_16x16x32_bf16 v[98:101], v[168:171], v[216:219], v[98:101]
	v_mfma_f32_16x16x32_bf16 v[92:95], v[220:223], v[172:175], v[92:95]
	v_mfma_f32_16x16x32_bf16 v[88:91], v[228:231], v[172:175], v[88:91]
	v_mfma_f32_16x16x32_bf16 v[84:87], v[220:223], v[180:183], v[84:87]
	v_mfma_f32_16x16x32_bf16 v[80:83], v[228:231], v[180:183], v[80:83]
	v_mfma_f32_16x16x32_bf16 v[76:79], v[220:223], v[200:203], v[76:79]
	v_mfma_f32_16x16x32_bf16 v[72:75], v[228:231], v[200:203], v[72:75]
	v_mfma_f32_16x16x32_bf16 v[68:71], v[220:223], v[212:215], v[68:71]
	v_mfma_f32_16x16x32_bf16 v[64:67], v[228:231], v[212:215], v[64:67]
	v_mfma_f32_16x16x32_bf16 v[92:95], v[224:227], v[176:179], v[92:95]
	v_mfma_f32_16x16x32_bf16 v[88:91], v[232:235], v[176:179], v[88:91]
	v_mfma_f32_16x16x32_bf16 v[84:87], v[224:227], v[196:199], v[84:87]
	v_mfma_f32_16x16x32_bf16 v[80:83], v[232:235], v[196:199], v[80:83]
	v_mfma_f32_16x16x32_bf16 v[76:79], v[224:227], v[208:211], v[76:79]
	v_mfma_f32_16x16x32_bf16 v[72:75], v[232:235], v[208:211], v[72:75]
	v_mfma_f32_16x16x32_bf16 v[68:71], v[224:227], v[216:219], v[68:71]
	v_mfma_f32_16x16x32_bf16 v[64:67], v[232:235], v[216:219], v[64:67]
	s_barrier
	ds_read_b128 v[172:175], v147 offset:16384
	ds_read_b128 v[176:179], v147 offset:17408
	ds_read_b128 v[180:183], v147 offset:18432
	ds_read_b128 v[196:199], v147 offset:19456
	ds_read_b128 v[200:203], v147 offset:20480
	ds_read_b128 v[208:211], v147 offset:21504
	ds_read_b128 v[212:215], v147 offset:22528
	ds_read_b128 v[216:219], v147 offset:23552
	s_mov_b32 m0, s28
	v_add_u32_e32 v206, 0x100, v204
	global_load_lds_dwordx4 v206, s[10:11]
	v_add_u32_e32 v207, 0x100, v205
	s_mov_b32 m0, s29
	s_nop 0
	global_load_lds_dwordx4 v207, s[10:11]
	s_mov_b32 m0, s25
	s_nop 0
	global_load_lds_dwordx4 v206, s[12:13]
	s_mov_b32 m0, s26
	s_nop 0
	global_load_lds_dwordx4 v207, s[12:13]
	s_mov_b32 m0, s30
	s_nop 0
	global_load_lds_dwordx4 v206, s[18:19]
	s_mov_b32 m0, s31
	s_nop 0
	global_load_lds_dwordx4 v207, s[18:19]
	s_waitcnt vmcnt(8)
	s_waitcnt lgkmcnt(0)
	s_barrier
	v_mfma_f32_16x16x32_bf16 v[60:63], v[156:159], v[172:175], v[60:63]
	v_mfma_f32_16x16x32_bf16 v[56:59], v[164:167], v[172:175], v[56:59]
	v_mfma_f32_16x16x32_bf16 v[52:55], v[156:159], v[180:183], v[52:55]
	v_mfma_f32_16x16x32_bf16 v[48:51], v[164:167], v[180:183], v[48:51]
	v_mfma_f32_16x16x32_bf16 v[44:47], v[156:159], v[200:203], v[44:47]
	v_mfma_f32_16x16x32_bf16 v[40:43], v[164:167], v[200:203], v[40:43]
	v_mfma_f32_16x16x32_bf16 v[36:39], v[156:159], v[212:215], v[36:39]
	v_mfma_f32_16x16x32_bf16 v[32:35], v[164:167], v[212:215], v[32:35]
	v_mfma_f32_16x16x32_bf16 v[60:63], v[160:163], v[176:179], v[60:63]
	v_mfma_f32_16x16x32_bf16 v[56:59], v[168:171], v[176:179], v[56:59]
	v_mfma_f32_16x16x32_bf16 v[52:55], v[160:163], v[196:199], v[52:55]
	v_mfma_f32_16x16x32_bf16 v[48:51], v[168:171], v[196:199], v[48:51]
	v_mfma_f32_16x16x32_bf16 v[44:47], v[160:163], v[208:211], v[44:47]
	v_mfma_f32_16x16x32_bf16 v[40:43], v[168:171], v[208:211], v[40:43]
	v_mfma_f32_16x16x32_bf16 v[36:39], v[160:163], v[216:219], v[36:39]
	v_mfma_f32_16x16x32_bf16 v[32:35], v[168:171], v[216:219], v[32:35]
	v_mfma_f32_16x16x32_bf16 v[28:31], v[220:223], v[172:175], v[28:31]
	v_mfma_f32_16x16x32_bf16 v[24:27], v[228:231], v[172:175], v[24:27]
	v_mfma_f32_16x16x32_bf16 v[20:23], v[220:223], v[180:183], v[20:23]
	v_mfma_f32_16x16x32_bf16 v[16:19], v[228:231], v[180:183], v[16:19]
	v_mfma_f32_16x16x32_bf16 v[12:15], v[220:223], v[200:203], v[12:15]
	v_mfma_f32_16x16x32_bf16 v[8:11], v[228:231], v[200:203], v[8:11]
	v_mfma_f32_16x16x32_bf16 v[4:7], v[220:223], v[212:215], v[4:7]
	v_mfma_f32_16x16x32_bf16 v[0:3], v[228:231], v[212:215], v[0:3]
	v_mfma_f32_16x16x32_bf16 v[28:31], v[224:227], v[176:179], v[28:31]
	v_mfma_f32_16x16x32_bf16 v[24:27], v[232:235], v[176:179], v[24:27]
	v_mfma_f32_16x16x32_bf16 v[20:23], v[224:227], v[196:199], v[20:23]
	v_mfma_f32_16x16x32_bf16 v[16:19], v[232:235], v[196:199], v[16:19]
	v_mfma_f32_16x16x32_bf16 v[12:15], v[224:227], v[208:211], v[12:15]
	v_mfma_f32_16x16x32_bf16 v[8:11], v[232:235], v[208:211], v[8:11]
	v_mfma_f32_16x16x32_bf16 v[4:7], v[224:227], v[216:219], v[4:7]
	v_mfma_f32_16x16x32_bf16 v[0:3], v[232:235], v[216:219], v[0:3]
	v_or_b32_e32 v156, 0x18000, v146
	v_add_u32_e32 v158, 0x18100, v146
	s_barrier
; #define WAIT_V(n) asm volatile("s_waitcnt vmcnt(%0)" ::"n"(n) : "memory")
; #define WAIT_L(n) asm volatile("s_waitcnt lgkmcnt(%0)" ::"n"(n) : "memory")
; #define SBAR() __builtin_amdgcn_sched_barrier(0)
; #define STAGE(P, base, kt) do { _Pragma("unroll") for (int _i = 0; _i < 2; ++_i)                                        \
;       __builtin_amdgcn_global_load_lds((const unsigned*)((base) + (size_t)(sOff[_i] + (unsigned)(kt) * (BK * 2))),        \
;                                        (unsigned*)((P) + wid * 1024 + _i * 8192), 16, 0, 0); } while (0)
; #define LDA(dst, b, h) _Pragma("unroll") for (int m = 0; m < 4; ++m) _Pragma("unroll") for (int k = 0; k < 2; ++k) \
;       dst[m][k] = *(const bf16x8*)(SA(b, h) + aoff + (m * 2048 + k * 1024))
; #define LDB(dst, b, h) _Pragma("unroll") for (int n = 0; n < 2; ++n) _Pragma("unroll") for (int k = 0; k < 2; ++k) \
;       dst[n][k] = *(const bf16x8*)(SB(b, h) + boff + (n * 256 + k * 1024))
; #define BAR __builtin_amdgcn_s_barrier()
; template <int EPI, int N, int K>
; __device__ __forceinline__ void phase_gemm(const Params& p, const u16* __restrict__ A, const u16* __restrict__ Bt, int nM, char* shm,
;                            u16* __restrict__ outp, float* __restrict__ rowss) {
;     ...
;       LDB(B0, 1, 0); SBAR(); LDA(At, 1, 0); STAGE(SA(0, 1), A1, t + 2);
;       WAIT_L(8); BAR; WAIT_L(0); MMA(0, 0, At, B0); BAR; SBAR();
;       LDB(B1, 1, 1); STAGE(SB(1, 0), B0p, t + 3);
;       BAR; WAIT_L(0); MMA(0, 1, At, B1); BAR;
;       LDA(At, 1, 1); STAGE(SA(1, 0), A0, t + 3);
;       BAR; WAIT_L(0); MMA(1, 0, At, B0); BAR; SBAR();
;       STAGE(SB(1, 1), B1p, t + 3);
;       WAIT_V(6); BAR; MMA(1, 1, At, B1); BAR;
	v_add_u32_e32 v157, 0x18400, v146
	ds_read_b128 v[164:167], v156
	ds_read_b128 v[168:171], v157
	v_add_u32_e32 v159, 0x18500, v146
	ds_read_b128 v[172:175], v158
	ds_read_b128 v[176:179], v159
	s_mov_b32 m0, s33
	ds_read_b128 v[180:183], v147 offset:32768
	ds_read_b128 v[196:199], v147 offset:33792
	ds_read_b128 v[200:203], v147 offset:34816
	ds_read_b128 v[208:211], v147 offset:35840
	ds_read_b128 v[212:215], v147 offset:36864
	ds_read_b128 v[216:219], v147 offset:37888
	ds_read_b128 v[220:223], v147 offset:38912
	ds_read_b128 v[224:227], v147 offset:39936
	global_load_lds_dwordx4 v206, s[4:5]
	s_mov_b32 m0, s35
	s_nop 0
	global_load_lds_dwordx4 v207, s[4:5]
	v_or_b32_e32 v160, 0x1c000, v146
	v_add_u32_e32 v162, 0x1c100, v146
	v_add_u32_e32 v161, 0x1c400, v146
	ds_read_b128 v[228:231], v160
	ds_read_b128 v[232:235], v161
	v_add_u32_e32 v163, 0x1c500, v146
	ds_read_b128 v[236:239], v162
	ds_read_b128 v[240:243], v163
	s_waitcnt vmcnt(8)
	s_waitcnt lgkmcnt(0)
	s_barrier
	v_mfma_f32_16x16x32_bf16 v[126:129], v[164:167], v[180:183], v[126:129]
	v_mfma_f32_16x16x32_bf16 v[122:125], v[172:175], v[180:183], v[122:125]
	v_mfma_f32_16x16x32_bf16 v[118:121], v[164:167], v[200:203], v[118:121]
	v_mfma_f32_16x16x32_bf16 v[114:117], v[172:175], v[200:203], v[114:117]
	v_mfma_f32_16x16x32_bf16 v[110:113], v[164:167], v[212:215], v[110:113]
	v_mfma_f32_16x16x32_bf16 v[106:109], v[172:175], v[212:215], v[106:109]
	v_mfma_f32_16x16x32_bf16 v[102:105], v[164:167], v[220:223], v[102:105]
	v_mfma_f32_16x16x32_bf16 v[98:101], v[172:175], v[220:223], v[98:101]
	v_mfma_f32_16x16x32_bf16 v[126:129], v[168:171], v[196:199], v[126:129]
	v_mfma_f32_16x16x32_bf16 v[122:125], v[176:179], v[196:199], v[122:125]
	v_mfma_f32_16x16x32_bf16 v[118:121], v[168:171], v[208:211], v[118:121]
	v_mfma_f32_16x16x32_bf16 v[114:117], v[176:179], v[208:211], v[114:117]
	v_mfma_f32_16x16x32_bf16 v[110:113], v[168:171], v[216:219], v[110:113]
	v_mfma_f32_16x16x32_bf16 v[106:109], v[176:179], v[216:219], v[106:109]
	v_mfma_f32_16x16x32_bf16 v[102:105], v[168:171], v[224:227], v[102:105]
	v_mfma_f32_16x16x32_bf16 v[98:101], v[176:179], v[224:227], v[98:101]
	v_mfma_f32_16x16x32_bf16 v[92:95], v[228:231], v[180:183], v[92:95]
	v_mfma_f32_16x16x32_bf16 v[88:91], v[236:239], v[180:183], v[88:91]
	v_mfma_f32_16x16x32_bf16 v[84:87], v[228:231], v[200:203], v[84:87]
	v_mfma_f32_16x16x32_bf16 v[80:83], v[236:239], v[200:203], v[80:83]
	v_mfma_f32_16x16x32_bf16 v[76:79], v[228:231], v[212:215], v[76:79]
	v_mfma_f32_16x16x32_bf16 v[72:75], v[236:239], v[212:215], v[72:75]
	v_mfma_f32_16x16x32_bf16 v[68:71], v[228:231], v[220:223], v[68:71]
	v_mfma_f32_16x16x32_bf16 v[64:67], v[236:239], v[220:223], v[64:67]
	v_mfma_f32_16x16x32_bf16 v[92:95], v[232:235], v[196:199], v[92:95]
	v_mfma_f32_16x16x32_bf16 v[88:91], v[240:243], v[196:199], v[88:91]
	v_mfma_f32_16x16x32_bf16 v[84:87], v[232:235], v[208:211], v[84:87]
	v_mfma_f32_16x16x32_bf16 v[80:83], v[240:243], v[208:211], v[80:83]
	v_mfma_f32_16x16x32_bf16 v[76:79], v[232:235], v[216:219], v[76:79]
	v_mfma_f32_16x16x32_bf16 v[72:75], v[240:243], v[216:219], v[72:75]
	v_mfma_f32_16x16x32_bf16 v[68:71], v[232:235], v[224:227], v[68:71]
	v_mfma_f32_16x16x32_bf16 v[64:67], v[240:243], v[224:227], v[64:67]
	s_barrier
	ds_read_b128 v[180:183], v147 offset:49152
	ds_read_b128 v[196:199], v147 offset:50176
	ds_read_b128 v[200:203], v147 offset:51200
	ds_read_b128 v[208:211], v147 offset:52224
	ds_read_b128 v[212:215], v147 offset:53248
	ds_read_b128 v[216:219], v147 offset:54272
	ds_read_b128 v[220:223], v147 offset:55296
	ds_read_b128 v[224:227], v147 offset:56320
	s_mov_b32 m0, s92
	v_add_u32_e32 v204, 0x180, v204
	global_load_lds_dwordx4 v204, s[10:11]
	v_add_u32_e32 v205, 0x180, v205
	s_mov_b32 m0, s93
	s_nop 0
	global_load_lds_dwordx4 v205, s[10:11]
	s_mov_b32 m0, s94
	s_nop 0
	global_load_lds_dwordx4 v204, s[12:13]
	s_mov_b32 m0, s52
	s_nop 0
	global_load_lds_dwordx4 v205, s[12:13]
	s_mov_b32 m0, s53
	s_nop 0
	global_load_lds_dwordx4 v204, s[18:19]
	s_mov_b32 m0, s54
	s_nop 0
	global_load_lds_dwordx4 v205, s[18:19]
	s_waitcnt vmcnt(8)
	s_waitcnt lgkmcnt(0)
	s_barrier
	v_mfma_f32_16x16x32_bf16 v[60:63], v[164:167], v[180:183], v[60:63]
	v_mfma_f32_16x16x32_bf16 v[56:59], v[172:175], v[180:183], v[56:59]
	v_mfma_f32_16x16x32_bf16 v[52:55], v[164:167], v[200:203], v[52:55]
	v_mfma_f32_16x16x32_bf16 v[48:51], v[172:175], v[200:203], v[48:51]
	v_mfma_f32_16x16x32_bf16 v[44:47], v[164:167], v[212:215], v[44:47]
	v_mfma_f32_16x16x32_bf16 v[40:43], v[172:175], v[212:215], v[40:43]
	v_mfma_f32_16x16x32_bf16 v[36:39], v[164:167], v[220:223], v[36:39]
	v_mfma_f32_16x16x32_bf16 v[32:35], v[172:175], v[220:223], v[32:35]
	v_mfma_f32_16x16x32_bf16 v[60:63], v[168:171], v[196:199], v[60:63]
	v_mfma_f32_16x16x32_bf16 v[56:59], v[176:179], v[196:199], v[56:59]
	v_mfma_f32_16x16x32_bf16 v[52:55], v[168:171], v[208:211], v[52:55]
	v_mfma_f32_16x16x32_bf16 v[48:51], v[176:179], v[208:211], v[48:51]
	v_mfma_f32_16x16x32_bf16 v[44:47], v[168:171], v[216:219], v[44:47]
	v_mfma_f32_16x16x32_bf16 v[40:43], v[176:179], v[216:219], v[40:43]
	v_mfma_f32_16x16x32_bf16 v[36:39], v[168:171], v[224:227], v[36:39]
	v_mfma_f32_16x16x32_bf16 v[32:35], v[176:179], v[224:227], v[32:35]
	v_mfma_f32_16x16x32_bf16 v[28:31], v[228:231], v[180:183], v[28:31]
	v_mfma_f32_16x16x32_bf16 v[24:27], v[236:239], v[180:183], v[24:27]
	v_mfma_f32_16x16x32_bf16 v[20:23], v[228:231], v[200:203], v[20:23]
	v_mfma_f32_16x16x32_bf16 v[16:19], v[236:239], v[200:203], v[16:19]
	v_mfma_f32_16x16x32_bf16 v[12:15], v[228:231], v[212:215], v[12:15]
	v_mfma_f32_16x16x32_bf16 v[8:11], v[236:239], v[212:215], v[8:11]
	v_mfma_f32_16x16x32_bf16 v[4:7], v[228:231], v[220:223], v[4:7]
	v_mfma_f32_16x16x32_bf16 v[0:3], v[236:239], v[220:223], v[0:3]
	v_mfma_f32_16x16x32_bf16 v[28:31], v[232:235], v[196:199], v[28:31]
	v_mfma_f32_16x16x32_bf16 v[24:27], v[240:243], v[196:199], v[24:27]
	v_mfma_f32_16x16x32_bf16 v[20:23], v[232:235], v[208:211], v[20:23]
	v_mfma_f32_16x16x32_bf16 v[16:19], v[240:243], v[208:211], v[16:19]
	v_mfma_f32_16x16x32_bf16 v[12:15], v[232:235], v[216:219], v[12:15]
	v_mfma_f32_16x16x32_bf16 v[8:11], v[240:243], v[216:219], v[8:11]
	v_mfma_f32_16x16x32_bf16 v[4:7], v[232:235], v[224:227], v[4:7]
	v_mfma_f32_16x16x32_bf16 v[0:3], v[240:243], v[224:227], v[0:3]
	s_add_i32 s58, s58, 2
	v_add_u32_e32 v142, 0x100, v142
	s_cmp_lt_u32 s58, 40
	v_add_u32_e32 v96, 0x100, v96
	s_barrier
; #define WAIT_V(n) asm volatile("s_waitcnt vmcnt(%0)" ::"n"(n) : "memory")
; #define WAIT_L(n) asm volatile("s_waitcnt lgkmcnt(%0)" ::"n"(n) : "memory")
; #define STAGE(P, base, kt) do { _Pragma("unroll") for (int _i = 0; _i < 2; ++_i)                                        \
;       __builtin_amdgcn_global_load_lds((const unsigned*)((base) + (size_t)(sOff[_i] + (unsigned)(kt) * (BK * 2))),        \
;                                        (unsigned*)((P) + wid * 1024 + _i * 8192), 16, 0, 0); } while (0)
; #define LDA(dst, b, h) _Pragma("unroll") for (int m = 0; m < 4; ++m) _Pragma("unroll") for (int k = 0; k < 2; ++k) \
;       dst[m][k] = *(const bf16x8*)(SA(b, h) + aoff + (m * 2048 + k * 1024))
; #define LDB(dst, b, h) _Pragma("unroll") for (int n = 0; n < 2; ++n) _Pragma("unroll") for (int k = 0; k < 2; ++k) \
;       dst[n][k] = *(const bf16x8*)(SB(b, h) + boff + (n * 256 + k * 1024))
; #define BAR __builtin_amdgcn_s_barrier()
; template <int EPI, int N, int K>
; __device__ __forceinline__ void phase_gemm(const Params& p, const u16* __restrict__ A, const u16* __restrict__ Bt, int nM, char* shm,
;                            u16* __restrict__ outp, float* __restrict__ rowss) {
;     ...
;     { LDB(B0, 0, 0); LDA(At, 0, 0); STAGE(SA(1, 1), A1, nt - 1);
;       BAR; WAIT_L(0); MMA(0, 0, At, B0); BAR;
;       LDB(B1, 0, 1); BAR; WAIT_L(0); MMA(0, 1, At, B1); BAR;
;       LDA(At, 0, 1); WAIT_V(4); BAR; WAIT_L(0); MMA(1, 0, At, B0); MMA(1, 1, At, B1); BAR; }
;     { LDB(B0, 1, 0); LDA(At, 1, 0); WAIT_V(2); BAR; WAIT_L(0); MMA(0, 0, At, B0); BAR;
;       LDB(B1, 1, 1); WAIT_V(0); BAR; WAIT_L(0); MMA(0, 1, At, B1); BAR;
;       LDA(At, 1, 1); BAR; WAIT_L(0); MMA(1, 0, At, B0); MMA(1, 1, At, B1); BAR; }
	s_cbranch_scc1 .LBB0_517
	s_waitcnt vmcnt(6)
	s_mov_b32 m0, s60
	v_lshl_add_u64 v[204:205], s[4:5], 0, v[138:139]
	ds_read_b128 v[164:167], v143
	ds_read_b128 v[168:171], v144
	ds_read_b128 v[142:145], v145
	ds_read_b128 v[172:175], v151
	ds_read_b128 v[176:179], v147
	ds_read_b128 v[180:183], v147 offset:1024
	ds_read_b128 v[196:199], v147 offset:2048
	ds_read_b128 v[200:203], v147 offset:3072
	ds_read_b128 v[208:211], v147 offset:4096
	ds_read_b128 v[212:215], v147 offset:5120
	ds_read_b128 v[216:219], v147 offset:6144
	ds_read_b128 v[220:223], v147 offset:7168
	global_load_lds_dwordx4 v[204:205], off
	v_lshl_add_u64 v[204:205], s[4:5], 0, v[140:141]
	s_mov_b32 m0, s59
	s_nop 0
	global_load_lds_dwordx4 v[204:205], off
	s_barrier
	s_waitcnt lgkmcnt(0)
	s_waitcnt lgkmcnt(0)
	v_mfma_f32_16x16x32_bf16 v[126:129], v[164:167], v[176:179], v[126:129]
	v_mfma_f32_16x16x32_bf16 v[122:125], v[142:145], v[176:179], v[122:125]
	v_mfma_f32_16x16x32_bf16 v[118:121], v[164:167], v[196:199], v[118:121]
	v_mfma_f32_16x16x32_bf16 v[102:105], v[164:167], v[216:219], v[102:105]
	v_mfma_f32_16x16x32_bf16 v[98:101], v[142:145], v[216:219], v[98:101]
	v_mfma_f32_16x16x32_bf16 v[126:129], v[168:171], v[180:183], v[126:129]
	v_mfma_f32_16x16x32_bf16 v[122:125], v[172:175], v[180:183], v[122:125]
	v_mfma_f32_16x16x32_bf16 v[118:121], v[168:171], v[200:203], v[118:121]
	v_mfma_f32_16x16x32_bf16 v[114:117], v[142:145], v[196:199], v[114:117]
	v_mfma_f32_16x16x32_bf16 v[110:113], v[164:167], v[208:211], v[110:113]
	v_mfma_f32_16x16x32_bf16 v[106:109], v[142:145], v[208:211], v[106:109]
	v_mfma_f32_16x16x32_bf16 v[102:105], v[168:171], v[220:223], v[102:105]
	v_mfma_f32_16x16x32_bf16 v[98:101], v[172:175], v[220:223], v[98:101]
	v_mfma_f32_16x16x32_bf16 v[224:227], v[172:175], v[200:203], v[114:117]
	v_mfma_f32_16x16x32_bf16 v[228:231], v[168:171], v[212:215], v[110:113]
	v_mfma_f32_16x16x32_bf16 v[232:235], v[172:175], v[212:215], v[106:109]
	s_barrier
	s_nop 0
	ds_read_b128 v[106:109], v152
	ds_read_b128 v[110:113], v153
	ds_read_b128 v[114:117], v154
	ds_read_b128 v[152:155], v155
	s_barrier
	s_waitcnt lgkmcnt(0)
	s_waitcnt lgkmcnt(0)
	v_mfma_f32_16x16x32_bf16 v[84:87], v[106:109], v[196:199], v[84:87]
	v_mfma_f32_16x16x32_bf16 v[80:83], v[114:117], v[196:199], v[80:83]
	v_mfma_f32_16x16x32_bf16 v[68:71], v[106:109], v[216:219], v[68:71]
	v_mfma_f32_16x16x32_bf16 v[92:95], v[106:109], v[176:179], v[92:95]
	v_mfma_f32_16x16x32_bf16 v[88:91], v[114:117], v[176:179], v[88:91]
	v_mfma_f32_16x16x32_bf16 v[84:87], v[110:113], v[200:203], v[84:87]
	v_mfma_f32_16x16x32_bf16 v[80:83], v[152:155], v[200:203], v[80:83]
	v_mfma_f32_16x16x32_bf16 v[76:79], v[106:109], v[208:211], v[76:79]
	v_mfma_f32_16x16x32_bf16 v[72:75], v[114:117], v[208:211], v[72:75]
	v_mfma_f32_16x16x32_bf16 v[68:71], v[110:113], v[220:223], v[68:71]
	v_mfma_f32_16x16x32_bf16 v[64:67], v[114:117], v[216:219], v[64:67]
	v_mfma_f32_16x16x32_bf16 v[236:239], v[110:113], v[180:183], v[92:95]
	v_mfma_f32_16x16x32_bf16 v[176:179], v[152:155], v[180:183], v[88:91]
	v_mfma_f32_16x16x32_bf16 v[180:183], v[110:113], v[212:215], v[76:79]
	v_mfma_f32_16x16x32_bf16 v[196:199], v[152:155], v[212:215], v[72:75]
	v_mfma_f32_16x16x32_bf16 v[200:203], v[152:155], v[220:223], v[64:67]
	s_barrier
	s_nop 0
	ds_read_b128 v[64:67], v147 offset:16384
	ds_read_b128 v[72:75], v147 offset:17408
	ds_read_b128 v[76:79], v147 offset:18432
	ds_read_b128 v[88:91], v147 offset:19456
	ds_read_b128 v[92:95], v147 offset:20480
	ds_read_b128 v[208:211], v147 offset:21504
	ds_read_b128 v[212:215], v147 offset:22528
	ds_read_b128 v[216:219], v147 offset:23552
	s_waitcnt vmcnt(4)
	s_barrier
	s_waitcnt lgkmcnt(0)
	s_waitcnt lgkmcnt(0)
	v_mfma_f32_16x16x32_bf16 v[60:63], v[164:167], v[64:67], v[60:63]
	v_mfma_f32_16x16x32_bf16 v[52:55], v[164:167], v[76:79], v[52:55]
	v_mfma_f32_16x16x32_bf16 v[48:51], v[142:145], v[76:79], v[48:51]
	v_mfma_f32_16x16x32_bf16 v[36:39], v[164:167], v[212:215], v[36:39]
	v_mfma_f32_16x16x32_bf16 v[32:35], v[142:145], v[212:215], v[32:35]
	v_mfma_f32_16x16x32_bf16 v[60:63], v[168:171], v[72:75], v[60:63]
	v_mfma_f32_16x16x32_bf16 v[56:59], v[142:145], v[64:67], v[56:59]
	v_mfma_f32_16x16x32_bf16 v[52:55], v[168:171], v[88:91], v[52:55]
	v_mfma_f32_16x16x32_bf16 v[48:51], v[172:175], v[88:91], v[48:51]
	v_mfma_f32_16x16x32_bf16 v[44:47], v[164:167], v[92:95], v[44:47]
	v_mfma_f32_16x16x32_bf16 v[40:43], v[142:145], v[92:95], v[40:43]
	v_mfma_f32_16x16x32_bf16 v[36:39], v[168:171], v[216:219], v[36:39]
	v_mfma_f32_16x16x32_bf16 v[32:35], v[172:175], v[216:219], v[32:35]
	v_mfma_f32_16x16x32_bf16 v[220:223], v[172:175], v[72:75], v[56:59]
	v_mfma_f32_16x16x32_bf16 v[240:243], v[168:171], v[208:211], v[44:47]
	v_mfma_f32_16x16x32_bf16 v[244:247], v[172:175], v[208:211], v[40:43]
	v_mfma_f32_16x16x32_bf16 v[20:23], v[106:109], v[76:79], v[20:23]
	v_mfma_f32_16x16x32_bf16 v[16:19], v[114:117], v[76:79], v[16:19]
	v_mfma_f32_16x16x32_bf16 v[4:7], v[106:109], v[212:215], v[4:7]
	v_mfma_f32_16x16x32_bf16 v[28:31], v[106:109], v[64:67], v[28:31]
	v_mfma_f32_16x16x32_bf16 v[24:27], v[114:117], v[64:67], v[24:27]
	v_mfma_f32_16x16x32_bf16 v[20:23], v[110:113], v[88:91], v[20:23]
	v_mfma_f32_16x16x32_bf16 v[16:19], v[152:155], v[88:91], v[16:19]
	v_mfma_f32_16x16x32_bf16 v[12:15], v[106:109], v[92:95], v[12:15]
	v_mfma_f32_16x16x32_bf16 v[8:11], v[114:117], v[92:95], v[8:11]
	v_mfma_f32_16x16x32_bf16 v[4:7], v[110:113], v[216:219], v[4:7]
	v_mfma_f32_16x16x32_bf16 v[0:3], v[114:117], v[212:215], v[0:3]
	v_mfma_f32_16x16x32_bf16 v[142:145], v[110:113], v[72:75], v[28:31]
	v_mfma_f32_16x16x32_bf16 v[164:167], v[152:155], v[72:75], v[24:27]
	v_mfma_f32_16x16x32_bf16 v[168:171], v[110:113], v[208:211], v[12:15]
	v_mfma_f32_16x16x32_bf16 v[172:175], v[152:155], v[208:211], v[8:11]
	v_mfma_f32_16x16x32_bf16 v[152:155], v[152:155], v[216:219], v[0:3]
	s_barrier
; #define WAIT_V(n) asm volatile("s_waitcnt vmcnt(%0)" ::"n"(n) : "memory")
; #define WAIT_L(n) asm volatile("s_waitcnt lgkmcnt(%0)" ::"n"(n) : "memory")
; #define LDA(dst, b, h) _Pragma("unroll") for (int m = 0; m < 4; ++m) _Pragma("unroll") for (int k = 0; k < 2; ++k) \
;       dst[m][k] = *(const bf16x8*)(SA(b, h) + aoff + (m * 2048 + k * 1024))
; #define LDB(dst, b, h) _Pragma("unroll") for (int n = 0; n < 2; ++n) _Pragma("unroll") for (int k = 0; k < 2; ++k) \
;       dst[n][k] = *(const bf16x8*)(SB(b, h) + boff + (n * 256 + k * 1024))
; #define BAR __builtin_amdgcn_s_barrier()
; template <int EPI, int N, int K>
; __device__ __forceinline__ void phase_gemm(const Params& p, const u16* __restrict__ A, const u16* __restrict__ Bt, int nM, char* shm,
;                            u16* __restrict__ outp, float* __restrict__ rowss) {
;     ...
;     { LDB(B0, 1, 0); LDA(At, 1, 0); WAIT_V(2); BAR; WAIT_L(0); MMA(0, 0, At, B0); BAR;
;       LDB(B1, 1, 1); WAIT_V(0); BAR; WAIT_L(0); MMA(0, 1, At, B1); BAR;
;       LDA(At, 1, 1); BAR; WAIT_L(0); MMA(1, 0, At, B0); MMA(1, 1, At, B1); BAR; }
;     if (wr == 0) BAR;
	s_nop 0
	ds_read_b128 v[0:3], v156
	ds_read_b128 v[8:11], v157
	ds_read_b128 v[12:15], v158
	ds_read_b128 v[156:159], v159
	ds_read_b128 v[24:27], v147 offset:32768
	ds_read_b128 v[28:31], v147 offset:33792
	ds_read_b128 v[40:43], v147 offset:34816
	ds_read_b128 v[44:47], v147 offset:35840
	ds_read_b128 v[56:59], v147 offset:36864
	ds_read_b128 v[64:67], v147 offset:37888
	ds_read_b128 v[208:211], v147 offset:38912
	ds_read_b128 v[212:215], v147 offset:39936
	s_waitcnt vmcnt(2)
	s_barrier
	s_waitcnt lgkmcnt(0)
	s_waitcnt lgkmcnt(0)
	v_mfma_f32_16x16x32_bf16 v[72:75], v[0:3], v[24:27], v[126:129]
	v_mfma_f32_16x16x32_bf16 v[126:129], v[8:11], v[28:31], v[72:75]
	v_mfma_f32_16x16x32_bf16 v[72:75], v[12:15], v[24:27], v[122:125]
	v_mfma_f32_16x16x32_bf16 v[114:117], v[156:159], v[28:31], v[72:75]
	v_mfma_f32_16x16x32_bf16 v[72:75], v[0:3], v[40:43], v[118:121]
	v_mfma_f32_16x16x32_bf16 v[106:109], v[8:11], v[44:47], v[72:75]
	v_mfma_f32_16x16x32_bf16 v[72:75], v[12:15], v[40:43], v[224:227]
	v_mfma_f32_16x16x32_bf16 v[110:113], v[156:159], v[44:47], v[72:75]
	v_mfma_f32_16x16x32_bf16 v[72:75], v[0:3], v[56:59], v[228:231]
	v_mfma_f32_16x16x32_bf16 v[88:91], v[8:11], v[64:67], v[72:75]
	v_mfma_f32_16x16x32_bf16 v[72:75], v[12:15], v[56:59], v[232:235]
	v_mfma_f32_16x16x32_bf16 v[92:95], v[156:159], v[64:67], v[72:75]
	v_mfma_f32_16x16x32_bf16 v[72:75], v[0:3], v[208:211], v[102:105]
	v_mfma_f32_16x16x32_bf16 v[76:79], v[12:15], v[208:211], v[98:101]
	v_mfma_f32_16x16x32_bf16 v[72:75], v[8:11], v[212:215], v[72:75]
	v_mfma_f32_16x16x32_bf16 v[76:79], v[156:159], v[212:215], v[76:79]
	s_barrier
	ds_read_b128 v[216:219], v160
	ds_read_b128 v[224:227], v161
	ds_read_b128 v[228:231], v162
	ds_read_b128 v[160:163], v163
	s_waitcnt vmcnt(0)
	s_barrier
	s_waitcnt lgkmcnt(0)
	s_waitcnt lgkmcnt(0)
	v_mfma_f32_16x16x32_bf16 v[98:101], v[216:219], v[24:27], v[236:239]
	v_mfma_f32_16x16x32_bf16 v[24:27], v[228:231], v[24:27], v[176:179]
	v_mfma_f32_16x16x32_bf16 v[122:125], v[160:163], v[28:31], v[24:27]
	v_mfma_f32_16x16x32_bf16 v[24:27], v[216:219], v[40:43], v[84:87]
	v_mfma_f32_16x16x32_bf16 v[118:121], v[224:227], v[28:31], v[98:101]
	v_mfma_f32_16x16x32_bf16 v[98:101], v[224:227], v[44:47], v[24:27]
	v_mfma_f32_16x16x32_bf16 v[24:27], v[228:231], v[40:43], v[80:83]
	v_mfma_f32_16x16x32_bf16 v[102:105], v[160:163], v[44:47], v[24:27]
	v_mfma_f32_16x16x32_bf16 v[24:27], v[216:219], v[56:59], v[180:183]
	v_mfma_f32_16x16x32_bf16 v[80:83], v[224:227], v[64:67], v[24:27]
	v_mfma_f32_16x16x32_bf16 v[24:27], v[228:231], v[56:59], v[196:199]
	v_mfma_f32_16x16x32_bf16 v[84:87], v[160:163], v[64:67], v[24:27]
	v_mfma_f32_16x16x32_bf16 v[24:27], v[216:219], v[208:211], v[68:71]
	v_mfma_f32_16x16x32_bf16 v[64:67], v[224:227], v[212:215], v[24:27]
	v_mfma_f32_16x16x32_bf16 v[24:27], v[228:231], v[208:211], v[200:203]
	v_mfma_f32_16x16x32_bf16 v[68:71], v[160:163], v[212:215], v[24:27]
	s_barrier
	ds_read_b128 v[176:179], v147 offset:49152
	ds_read_b128 v[180:183], v147 offset:50176
	ds_read_b128 v[196:199], v147 offset:51200
	ds_read_b128 v[200:203], v147 offset:52224
	ds_read_b128 v[208:211], v147 offset:53248
	ds_read_b128 v[212:215], v147 offset:54272
	ds_read_b128 v[232:235], v147 offset:55296
	ds_read_b128 v[236:239], v147 offset:56320
	s_barrier
	s_waitcnt lgkmcnt(0)
	s_waitcnt lgkmcnt(0)
	v_mfma_f32_16x16x32_bf16 v[24:27], v[0:3], v[176:179], v[60:63]
	v_mfma_f32_16x16x32_bf16 v[56:59], v[8:11], v[180:183], v[24:27]
	v_mfma_f32_16x16x32_bf16 v[24:27], v[12:15], v[176:179], v[220:223]
	v_mfma_f32_16x16x32_bf16 v[60:63], v[156:159], v[180:183], v[24:27]
	v_mfma_f32_16x16x32_bf16 v[24:27], v[0:3], v[196:199], v[52:55]
	v_mfma_f32_16x16x32_bf16 v[40:43], v[8:11], v[200:203], v[24:27]
	v_mfma_f32_16x16x32_bf16 v[24:27], v[12:15], v[196:199], v[48:51]
	v_mfma_f32_16x16x32_bf16 v[44:47], v[156:159], v[200:203], v[24:27]
	v_mfma_f32_16x16x32_bf16 v[24:27], v[0:3], v[208:211], v[240:243]
	v_mfma_f32_16x16x32_bf16 v[0:3], v[0:3], v[232:235], v[36:39]
	v_mfma_f32_16x16x32_bf16 v[24:27], v[8:11], v[212:215], v[24:27]
	v_mfma_f32_16x16x32_bf16 v[28:31], v[12:15], v[208:211], v[244:247]
	v_mfma_f32_16x16x32_bf16 v[8:11], v[8:11], v[236:239], v[0:3]
	v_mfma_f32_16x16x32_bf16 v[0:3], v[12:15], v[232:235], v[32:35]
	v_mfma_f32_16x16x32_bf16 v[28:31], v[156:159], v[212:215], v[28:31]
	v_mfma_f32_16x16x32_bf16 v[12:15], v[156:159], v[236:239], v[0:3]
	v_mfma_f32_16x16x32_bf16 v[0:3], v[216:219], v[176:179], v[142:145]
	v_mfma_f32_16x16x32_bf16 v[48:51], v[224:227], v[180:183], v[0:3]
	v_mfma_f32_16x16x32_bf16 v[0:3], v[228:231], v[176:179], v[164:167]
	v_mfma_f32_16x16x32_bf16 v[52:55], v[160:163], v[180:183], v[0:3]
	v_mfma_f32_16x16x32_bf16 v[0:3], v[216:219], v[196:199], v[20:23]
	v_mfma_f32_16x16x32_bf16 v[32:35], v[224:227], v[200:203], v[0:3]
	v_mfma_f32_16x16x32_bf16 v[0:3], v[228:231], v[196:199], v[16:19]
	v_mfma_f32_16x16x32_bf16 v[36:39], v[160:163], v[200:203], v[0:3]
	v_mfma_f32_16x16x32_bf16 v[0:3], v[216:219], v[208:211], v[168:171]
	v_mfma_f32_16x16x32_bf16 v[16:19], v[224:227], v[212:215], v[0:3]
	v_mfma_f32_16x16x32_bf16 v[0:3], v[228:231], v[208:211], v[172:175]
	v_mfma_f32_16x16x32_bf16 v[20:23], v[160:163], v[212:215], v[0:3]
	v_mfma_f32_16x16x32_bf16 v[0:3], v[216:219], v[232:235], v[4:7]
	v_mfma_f32_16x16x32_bf16 v[4:7], v[228:231], v[232:235], v[152:155]
	v_mfma_f32_16x16x32_bf16 v[0:3], v[224:227], v[236:239], v[0:3]
	v_mfma_f32_16x16x32_bf16 v[4:7], v[160:163], v[236:239], v[4:7]
	s_andn2_b64 vcc, exec, s[16:17]
	s_barrier
	s_cbranch_vccnz .LBB0_520
	s_barrier

; #define WAIT_V(n) asm volatile("s_waitcnt vmcnt(%0)" ::"n"(n) : "memory")
; #define WAIT_L(n) asm volatile("s_waitcnt lgkmcnt(%0)" ::"n"(n) : "memory")
; #define SBAR() __builtin_amdgcn_sched_barrier(0)
; #define STAGE(P, base, kt) do { _Pragma("unroll") for (int _i = 0; _i < 2; ++_i)                                        \
;       __builtin_amdgcn_global_load_lds((const unsigned*)((base) + (size_t)(sOff[_i] + (unsigned)(kt) * (BK * 2))),        \
;                                        (unsigned*)((P) + wid * 1024 + _i * 8192), 16, 0, 0); } while (0)
; #define LDA(dst, b, h) _Pragma("unroll") for (int m = 0; m < 4; ++m) _Pragma("unroll") for (int k = 0; k < 2; ++k) \
;       dst[m][k] = *(const bf16x8*)(SA(b, h) + aoff + (m * 2048 + k * 1024))
; #define LDB(dst, b, h) _Pragma("unroll") for (int n = 0; n < 2; ++n) _Pragma("unroll") for (int k = 0; k < 2; ++k) \
;       dst[n][k] = *(const bf16x8*)(SB(b, h) + boff + (n * 256 + k * 1024))
; #define BAR __builtin_amdgcn_s_barrier()
; template <int EPI, int N, int K>
; __device__ __forceinline__ void phase_gemm(const Params& p, const u16* __restrict__ A, const u16* __restrict__ Bt, int nM, char* shm,
;                            u16* __restrict__ outp, float* __restrict__ rowss) {
;     ...
;   for (;;) {
;     const char* A1 = A0 + (size_t)128 * K * 2;
;     const char* B1p = B0p + (size_t)128 * K * 2;
;     f32x4 acc[2][2][4][2] = {};
;     bf16x8 At[4][2], B0[2][2], B1[2][2];
;     if (wr == 1) BAR;
;     WAIT_V(0); BAR;
;     BAR;
;     for (int t = 0; t < nt - 2; t += 2) {
;       LDB(B0, 0, 0); SBAR(); LDA(At, 0, 0); STAGE(SA(1, 1), A1, t + 1);
;       WAIT_L(8); BAR; WAIT_L(0); MMA(0, 0, At, B0); BAR; SBAR();
;       LDB(B1, 0, 1); STAGE(SB(0, 0), B0p, t + 2);
;       BAR; WAIT_L(0); MMA(0, 1, At, B1); BAR;
;       LDA(At, 0, 1); STAGE(SA(0, 0), A0, t + 2);
;       BAR; WAIT_L(0); MMA(1, 0, At, B0); BAR; SBAR();
;       STAGE(SB(0, 1), B1p, t + 2);
;       WAIT_V(6); BAR; MMA(1, 1, At, B1); BAR;
.LBB0_553:
	v_or_b32_e32 v147, 0x10000, v143
	v_add_u32_e32 v149, 0x10100, v143
	v_add_u32_e32 v148, 0x10400, v143
	ds_read_b128 v[156:159], v147
	ds_read_b128 v[160:163], v148
	v_add_u32_e32 v150, 0x10500, v143
	ds_read_b128 v[164:167], v149
	ds_read_b128 v[168:171], v150
	v_add_u32_e32 v196, v142, v140
	s_add_i32 s55, s19, 0xc000
	v_add_u32_e32 v151, 0x80, v196
	s_mov_b32 m0, s55
	v_add_u32_e32 v197, v142, v141
	s_add_i32 s54, s19, 0xe000
	ds_read_b128 v[172:175], v144
	ds_read_b128 v[176:179], v144 offset:1024
	ds_read_b128 v[180:183], v144 offset:2048
	ds_read_b128 v[208:211], v144 offset:3072
	ds_read_b128 v[212:215], v144 offset:4096
	ds_read_b128 v[216:219], v144 offset:5120
	ds_read_b128 v[220:223], v144 offset:6144
	ds_read_b128 v[224:227], v144 offset:7168
	global_load_lds_dwordx4 v151, s[14:15]
	v_add_u32_e32 v151, 0x80, v197
	s_mov_b32 m0, s54
	s_nop 0
	global_load_lds_dwordx4 v151, s[14:15]
	v_or_b32_e32 v151, 0x14000, v143
	v_add_u32_e32 v153, 0x14100, v143
	v_add_u32_e32 v152, 0x14400, v143
	ds_read_b128 v[228:231], v151
	ds_read_b128 v[232:235], v152
	v_add_u32_e32 v154, 0x14500, v143
	ds_read_b128 v[236:239], v153
	ds_read_b128 v[240:243], v154
	s_waitcnt vmcnt(8)
	s_waitcnt lgkmcnt(0)
	s_barrier
	v_mfma_f32_16x16x32_bf16 v[126:129], v[156:159], v[172:175], v[126:129]
	v_mfma_f32_16x16x32_bf16 v[122:125], v[164:167], v[172:175], v[122:125]
	v_mfma_f32_16x16x32_bf16 v[118:121], v[156:159], v[180:183], v[118:121]
	v_mfma_f32_16x16x32_bf16 v[114:117], v[164:167], v[180:183], v[114:117]
	v_mfma_f32_16x16x32_bf16 v[110:113], v[156:159], v[212:215], v[110:113]
	v_mfma_f32_16x16x32_bf16 v[106:109], v[164:167], v[212:215], v[106:109]
	v_mfma_f32_16x16x32_bf16 v[102:105], v[156:159], v[220:223], v[102:105]
	v_mfma_f32_16x16x32_bf16 v[98:101], v[164:167], v[220:223], v[98:101]
	v_mfma_f32_16x16x32_bf16 v[126:129], v[160:163], v[176:179], v[126:129]
	v_mfma_f32_16x16x32_bf16 v[122:125], v[168:171], v[176:179], v[122:125]
	v_mfma_f32_16x16x32_bf16 v[118:121], v[160:163], v[208:211], v[118:121]
	v_mfma_f32_16x16x32_bf16 v[114:117], v[168:171], v[208:211], v[114:117]
	v_mfma_f32_16x16x32_bf16 v[110:113], v[160:163], v[216:219], v[110:113]
	v_mfma_f32_16x16x32_bf16 v[106:109], v[168:171], v[216:219], v[106:109]
	v_mfma_f32_16x16x32_bf16 v[102:105], v[160:163], v[224:227], v[102:105]
	v_mfma_f32_16x16x32_bf16 v[98:101], v[168:171], v[224:227], v[98:101]
	v_mfma_f32_16x16x32_bf16 v[92:95], v[228:231], v[172:175], v[92:95]
	v_mfma_f32_16x16x32_bf16 v[88:91], v[236:239], v[172:175], v[88:91]
	v_mfma_f32_16x16x32_bf16 v[84:87], v[228:231], v[180:183], v[84:87]
	v_mfma_f32_16x16x32_bf16 v[80:83], v[236:239], v[180:183], v[80:83]
	v_mfma_f32_16x16x32_bf16 v[76:79], v[228:231], v[212:215], v[76:79]
	v_mfma_f32_16x16x32_bf16 v[72:75], v[236:239], v[212:215], v[72:75]
	v_mfma_f32_16x16x32_bf16 v[68:71], v[228:231], v[220:223], v[68:71]
	v_mfma_f32_16x16x32_bf16 v[64:67], v[236:239], v[220:223], v[64:67]
	v_mfma_f32_16x16x32_bf16 v[92:95], v[232:235], v[176:179], v[92:95]
	v_mfma_f32_16x16x32_bf16 v[88:91], v[240:243], v[176:179], v[88:91]
	v_mfma_f32_16x16x32_bf16 v[84:87], v[232:235], v[208:211], v[84:87]
	v_mfma_f32_16x16x32_bf16 v[80:83], v[240:243], v[208:211], v[80:83]
	v_mfma_f32_16x16x32_bf16 v[76:79], v[232:235], v[216:219], v[76:79]
	v_mfma_f32_16x16x32_bf16 v[72:75], v[240:243], v[216:219], v[72:75]
	v_mfma_f32_16x16x32_bf16 v[68:71], v[232:235], v[224:227], v[68:71]
	v_mfma_f32_16x16x32_bf16 v[64:67], v[240:243], v[224:227], v[64:67]
	s_barrier
	ds_read_b128 v[172:175], v144 offset:16384
	ds_read_b128 v[176:179], v144 offset:17408
	ds_read_b128 v[180:183], v144 offset:18432
	ds_read_b128 v[208:211], v144 offset:19456
	ds_read_b128 v[212:215], v144 offset:20480
	ds_read_b128 v[216:219], v144 offset:21504
	ds_read_b128 v[220:223], v144 offset:22528
	ds_read_b128 v[224:227], v144 offset:23552
	s_mov_b32 m0, s23
	v_add_u32_e32 v198, 0x100, v196
	global_load_lds_dwordx4 v198, s[6:7]
	v_add_u32_e32 v199, 0x100, v197
	s_mov_b32 m0, s92
	s_nop 0
	global_load_lds_dwordx4 v199, s[6:7]
	s_mov_b32 m0, s19
	s_nop 0
	global_load_lds_dwordx4 v198, s[8:9]
	s_mov_b32 m0, s22
	s_nop 0
	global_load_lds_dwordx4 v199, s[8:9]
	s_mov_b32 m0, s94
	s_nop 0
	global_load_lds_dwordx4 v198, s[16:17]
	s_mov_b32 m0, s95
	s_nop 0
	global_load_lds_dwordx4 v199, s[16:17]
	s_waitcnt vmcnt(8)
	s_waitcnt lgkmcnt(0)
	s_barrier
	v_mfma_f32_16x16x32_bf16 v[60:63], v[156:159], v[172:175], v[60:63]
	v_mfma_f32_16x16x32_bf16 v[56:59], v[164:167], v[172:175], v[56:59]
	v_mfma_f32_16x16x32_bf16 v[52:55], v[156:159], v[180:183], v[52:55]
	v_mfma_f32_16x16x32_bf16 v[48:51], v[164:167], v[180:183], v[48:51]
	v_mfma_f32_16x16x32_bf16 v[44:47], v[156:159], v[212:215], v[44:47]
	v_mfma_f32_16x16x32_bf16 v[40:43], v[164:167], v[212:215], v[40:43]
	v_mfma_f32_16x16x32_bf16 v[36:39], v[156:159], v[220:223], v[36:39]
	v_mfma_f32_16x16x32_bf16 v[32:35], v[164:167], v[220:223], v[32:35]
	v_mfma_f32_16x16x32_bf16 v[60:63], v[160:163], v[176:179], v[60:63]
	v_mfma_f32_16x16x32_bf16 v[56:59], v[168:171], v[176:179], v[56:59]
	v_mfma_f32_16x16x32_bf16 v[52:55], v[160:163], v[208:211], v[52:55]
	v_mfma_f32_16x16x32_bf16 v[48:51], v[168:171], v[208:211], v[48:51]
	v_mfma_f32_16x16x32_bf16 v[44:47], v[160:163], v[216:219], v[44:47]
	v_mfma_f32_16x16x32_bf16 v[40:43], v[168:171], v[216:219], v[40:43]
	v_mfma_f32_16x16x32_bf16 v[36:39], v[160:163], v[224:227], v[36:39]
	v_mfma_f32_16x16x32_bf16 v[32:35], v[168:171], v[224:227], v[32:35]
	v_mfma_f32_16x16x32_bf16 v[28:31], v[228:231], v[172:175], v[28:31]
	v_mfma_f32_16x16x32_bf16 v[24:27], v[236:239], v[172:175], v[24:27]
	v_mfma_f32_16x16x32_bf16 v[20:23], v[228:231], v[180:183], v[20:23]
	v_mfma_f32_16x16x32_bf16 v[16:19], v[236:239], v[180:183], v[16:19]
	v_mfma_f32_16x16x32_bf16 v[12:15], v[228:231], v[212:215], v[12:15]
	v_mfma_f32_16x16x32_bf16 v[8:11], v[236:239], v[212:215], v[8:11]
	v_mfma_f32_16x16x32_bf16 v[4:7], v[228:231], v[220:223], v[4:7]
	v_mfma_f32_16x16x32_bf16 v[0:3], v[236:239], v[220:223], v[0:3]
	v_mfma_f32_16x16x32_bf16 v[28:31], v[232:235], v[176:179], v[28:31]
	v_mfma_f32_16x16x32_bf16 v[24:27], v[240:243], v[176:179], v[24:27]
	v_mfma_f32_16x16x32_bf16 v[20:23], v[232:235], v[208:211], v[20:23]
	v_mfma_f32_16x16x32_bf16 v[16:19], v[240:243], v[208:211], v[16:19]
	v_mfma_f32_16x16x32_bf16 v[12:15], v[232:235], v[216:219], v[12:15]
	v_mfma_f32_16x16x32_bf16 v[8:11], v[240:243], v[216:219], v[8:11]
	v_mfma_f32_16x16x32_bf16 v[4:7], v[232:235], v[224:227], v[4:7]
	v_mfma_f32_16x16x32_bf16 v[0:3], v[240:243], v[224:227], v[0:3]
	v_or_b32_e32 v155, 0x18000, v143
	v_add_u32_e32 v157, 0x18100, v143
	s_barrier
; #define WAIT_V(n) asm volatile("s_waitcnt vmcnt(%0)" ::"n"(n) : "memory")
; #define WAIT_L(n) asm volatile("s_waitcnt lgkmcnt(%0)" ::"n"(n) : "memory")
; #define SBAR() __builtin_amdgcn_sched_barrier(0)
; #define STAGE(P, base, kt) do { _Pragma("unroll") for (int _i = 0; _i < 2; ++_i)                                        \
;       __builtin_amdgcn_global_load_lds((const unsigned*)((base) + (size_t)(sOff[_i] + (unsigned)(kt) * (BK * 2))),        \
;                                        (unsigned*)((P) + wid * 1024 + _i * 8192), 16, 0, 0); } while (0)
; #define LDA(dst, b, h) _Pragma("unroll") for (int m = 0; m < 4; ++m) _Pragma("unroll") for (int k = 0; k < 2; ++k) \
;       dst[m][k] = *(const bf16x8*)(SA(b, h) + aoff + (m * 2048 + k * 1024))
; #define LDB(dst, b, h) _Pragma("unroll") for (int n = 0; n < 2; ++n) _Pragma("unroll") for (int k = 0; k < 2; ++k) \
;       dst[n][k] = *(const bf16x8*)(SB(b, h) + boff + (n * 256 + k * 1024))
; #define BAR __builtin_amdgcn_s_barrier()
; template <int EPI, int N, int K>
; __device__ __forceinline__ void phase_gemm(const Params& p, const u16* __restrict__ A, const u16* __restrict__ Bt, int nM, char* shm,
;                            u16* __restrict__ outp, float* __restrict__ rowss) {
;     ...
;       LDB(B0, 1, 0); SBAR(); LDA(At, 1, 0); STAGE(SA(0, 1), A1, t + 2);
;       WAIT_L(8); BAR; WAIT_L(0); MMA(0, 0, At, B0); BAR; SBAR();
;       LDB(B1, 1, 1); STAGE(SB(1, 0), B0p, t + 3);
;       BAR; WAIT_L(0); MMA(0, 1, At, B1); BAR;
;       LDA(At, 1, 1); STAGE(SA(1, 0), A0, t + 3);
;       BAR; WAIT_L(0); MMA(1, 0, At, B0); BAR; SBAR();
;       STAGE(SB(1, 1), B1p, t + 3);
;       WAIT_V(6); BAR; MMA(1, 1, At, B1); BAR;
	v_add_u32_e32 v156, 0x18400, v143
	ds_read_b128 v[164:167], v155
	ds_read_b128 v[168:171], v156
	v_add_u32_e32 v158, 0x18500, v143
	ds_read_b128 v[172:175], v157
	ds_read_b128 v[176:179], v158
	s_mov_b32 m0, s96
	ds_read_b128 v[180:183], v144 offset:32768
	ds_read_b128 v[208:211], v144 offset:33792
	ds_read_b128 v[212:215], v144 offset:34816
	ds_read_b128 v[216:219], v144 offset:35840
	ds_read_b128 v[220:223], v144 offset:36864
	ds_read_b128 v[224:227], v144 offset:37888
	ds_read_b128 v[228:231], v144 offset:38912
	ds_read_b128 v[232:235], v144 offset:39936
	global_load_lds_dwordx4 v198, s[14:15]
	s_mov_b32 m0, s33
	s_nop 0
	global_load_lds_dwordx4 v199, s[14:15]
	v_or_b32_e32 v159, 0x1c000, v143
	v_add_u32_e32 v161, 0x1c100, v143
	v_add_u32_e32 v160, 0x1c400, v143
	ds_read_b128 v[236:239], v159
	ds_read_b128 v[240:243], v160
	v_add_u32_e32 v162, 0x1c500, v143
	ds_read_b128 v[244:247], v161
	ds_read_b128 v[248:251], v162
	s_waitcnt vmcnt(8)
	s_waitcnt lgkmcnt(0)
	s_barrier
	v_mfma_f32_16x16x32_bf16 v[126:129], v[164:167], v[180:183], v[126:129]
	v_mfma_f32_16x16x32_bf16 v[122:125], v[172:175], v[180:183], v[122:125]
	v_mfma_f32_16x16x32_bf16 v[118:121], v[164:167], v[212:215], v[118:121]
	v_mfma_f32_16x16x32_bf16 v[114:117], v[172:175], v[212:215], v[114:117]
	v_mfma_f32_16x16x32_bf16 v[110:113], v[164:167], v[220:223], v[110:113]
	v_mfma_f32_16x16x32_bf16 v[106:109], v[172:175], v[220:223], v[106:109]
	v_mfma_f32_16x16x32_bf16 v[102:105], v[164:167], v[228:231], v[102:105]
	v_mfma_f32_16x16x32_bf16 v[98:101], v[172:175], v[228:231], v[98:101]
	v_mfma_f32_16x16x32_bf16 v[126:129], v[168:171], v[208:211], v[126:129]
	v_mfma_f32_16x16x32_bf16 v[122:125], v[176:179], v[208:211], v[122:125]
	v_mfma_f32_16x16x32_bf16 v[118:121], v[168:171], v[216:219], v[118:121]
	v_mfma_f32_16x16x32_bf16 v[114:117], v[176:179], v[216:219], v[114:117]
	v_mfma_f32_16x16x32_bf16 v[110:113], v[168:171], v[224:227], v[110:113]
	v_mfma_f32_16x16x32_bf16 v[106:109], v[176:179], v[224:227], v[106:109]
	v_mfma_f32_16x16x32_bf16 v[102:105], v[168:171], v[232:235], v[102:105]
	v_mfma_f32_16x16x32_bf16 v[98:101], v[176:179], v[232:235], v[98:101]
	v_mfma_f32_16x16x32_bf16 v[92:95], v[236:239], v[180:183], v[92:95]
	v_mfma_f32_16x16x32_bf16 v[88:91], v[244:247], v[180:183], v[88:91]
	v_mfma_f32_16x16x32_bf16 v[84:87], v[236:239], v[212:215], v[84:87]
	v_mfma_f32_16x16x32_bf16 v[80:83], v[244:247], v[212:215], v[80:83]
	v_mfma_f32_16x16x32_bf16 v[76:79], v[236:239], v[220:223], v[76:79]
	v_mfma_f32_16x16x32_bf16 v[72:75], v[244:247], v[220:223], v[72:75]
	v_mfma_f32_16x16x32_bf16 v[68:71], v[236:239], v[228:231], v[68:71]
	v_mfma_f32_16x16x32_bf16 v[64:67], v[244:247], v[228:231], v[64:67]
	v_mfma_f32_16x16x32_bf16 v[92:95], v[240:243], v[208:211], v[92:95]
	v_mfma_f32_16x16x32_bf16 v[88:91], v[248:251], v[208:211], v[88:91]
	v_mfma_f32_16x16x32_bf16 v[84:87], v[240:243], v[216:219], v[84:87]
	v_mfma_f32_16x16x32_bf16 v[80:83], v[248:251], v[216:219], v[80:83]
	v_mfma_f32_16x16x32_bf16 v[76:79], v[240:243], v[224:227], v[76:79]
	v_mfma_f32_16x16x32_bf16 v[72:75], v[248:251], v[224:227], v[72:75]
	v_mfma_f32_16x16x32_bf16 v[68:71], v[240:243], v[232:235], v[68:71]
	v_mfma_f32_16x16x32_bf16 v[64:67], v[248:251], v[232:235], v[64:67]
	s_barrier
	ds_read_b128 v[180:183], v144 offset:49152
	ds_read_b128 v[208:211], v144 offset:50176
	ds_read_b128 v[212:215], v144 offset:51200
	ds_read_b128 v[216:219], v144 offset:52224
	ds_read_b128 v[220:223], v144 offset:53248
	ds_read_b128 v[224:227], v144 offset:54272
	ds_read_b128 v[228:231], v144 offset:55296
	ds_read_b128 v[232:235], v144 offset:56320
	s_mov_b32 m0, s35
	v_add_u32_e32 v163, 0x180, v196
	global_load_lds_dwordx4 v163, s[6:7]
	v_add_u32_e32 v196, 0x180, v197
	s_mov_b32 m0, s93
	s_nop 0
	global_load_lds_dwordx4 v196, s[6:7]
	s_mov_b32 m0, s24
	s_nop 0
	global_load_lds_dwordx4 v163, s[8:9]
	s_mov_b32 m0, s25
	s_nop 0
	global_load_lds_dwordx4 v196, s[8:9]
	s_mov_b32 m0, s26
	s_nop 0
	global_load_lds_dwordx4 v163, s[16:17]
	s_mov_b32 m0, s27
	s_nop 0
	global_load_lds_dwordx4 v196, s[16:17]
	s_waitcnt vmcnt(8)
	s_waitcnt lgkmcnt(0)
	s_barrier
	v_mfma_f32_16x16x32_bf16 v[60:63], v[164:167], v[180:183], v[60:63]
	v_mfma_f32_16x16x32_bf16 v[56:59], v[172:175], v[180:183], v[56:59]
	v_mfma_f32_16x16x32_bf16 v[52:55], v[164:167], v[212:215], v[52:55]
	v_mfma_f32_16x16x32_bf16 v[48:51], v[172:175], v[212:215], v[48:51]
	v_mfma_f32_16x16x32_bf16 v[44:47], v[164:167], v[220:223], v[44:47]
	v_mfma_f32_16x16x32_bf16 v[40:43], v[172:175], v[220:223], v[40:43]
	v_mfma_f32_16x16x32_bf16 v[36:39], v[164:167], v[228:231], v[36:39]
	v_mfma_f32_16x16x32_bf16 v[32:35], v[172:175], v[228:231], v[32:35]
	v_mfma_f32_16x16x32_bf16 v[60:63], v[168:171], v[208:211], v[60:63]
	v_mfma_f32_16x16x32_bf16 v[56:59], v[176:179], v[208:211], v[56:59]
	v_mfma_f32_16x16x32_bf16 v[52:55], v[168:171], v[216:219], v[52:55]
	v_mfma_f32_16x16x32_bf16 v[48:51], v[176:179], v[216:219], v[48:51]
	v_mfma_f32_16x16x32_bf16 v[44:47], v[168:171], v[224:227], v[44:47]
	v_mfma_f32_16x16x32_bf16 v[40:43], v[176:179], v[224:227], v[40:43]
	v_mfma_f32_16x16x32_bf16 v[36:39], v[168:171], v[232:235], v[36:39]
	v_mfma_f32_16x16x32_bf16 v[32:35], v[176:179], v[232:235], v[32:35]
	v_mfma_f32_16x16x32_bf16 v[28:31], v[236:239], v[180:183], v[28:31]
	v_mfma_f32_16x16x32_bf16 v[24:27], v[244:247], v[180:183], v[24:27]
	v_mfma_f32_16x16x32_bf16 v[20:23], v[236:239], v[212:215], v[20:23]
	v_mfma_f32_16x16x32_bf16 v[16:19], v[244:247], v[212:215], v[16:19]
	v_mfma_f32_16x16x32_bf16 v[12:15], v[236:239], v[220:223], v[12:15]
	v_mfma_f32_16x16x32_bf16 v[8:11], v[244:247], v[220:223], v[8:11]
	v_mfma_f32_16x16x32_bf16 v[4:7], v[236:239], v[228:231], v[4:7]
	v_mfma_f32_16x16x32_bf16 v[0:3], v[244:247], v[228:231], v[0:3]
	v_mfma_f32_16x16x32_bf16 v[28:31], v[240:243], v[208:211], v[28:31]
	v_mfma_f32_16x16x32_bf16 v[24:27], v[248:251], v[208:211], v[24:27]
	v_mfma_f32_16x16x32_bf16 v[20:23], v[240:243], v[216:219], v[20:23]
	v_mfma_f32_16x16x32_bf16 v[16:19], v[248:251], v[216:219], v[16:19]
	v_mfma_f32_16x16x32_bf16 v[12:15], v[240:243], v[224:227], v[12:15]
	v_mfma_f32_16x16x32_bf16 v[8:11], v[248:251], v[224:227], v[8:11]
	v_mfma_f32_16x16x32_bf16 v[4:7], v[240:243], v[232:235], v[4:7]
	v_mfma_f32_16x16x32_bf16 v[0:3], v[248:251], v[232:235], v[0:3]
	s_add_i32 s53, s53, 2
	v_add_u32_e32 v141, 0x100, v141
	s_cmp_lt_u32 s53, 12
	v_add_u32_e32 v140, 0x100, v140
	s_barrier
; #define WAIT_V(n) asm volatile("s_waitcnt vmcnt(%0)" ::"n"(n) : "memory")
; #define WAIT_L(n) asm volatile("s_waitcnt lgkmcnt(%0)" ::"n"(n) : "memory")
; #define STAGE(P, base, kt) do { _Pragma("unroll") for (int _i = 0; _i < 2; ++_i)                                        \
;       __builtin_amdgcn_global_load_lds((const unsigned*)((base) + (size_t)(sOff[_i] + (unsigned)(kt) * (BK * 2))),        \
;                                        (unsigned*)((P) + wid * 1024 + _i * 8192), 16, 0, 0); } while (0)
; #define LDA(dst, b, h) _Pragma("unroll") for (int m = 0; m < 4; ++m) _Pragma("unroll") for (int k = 0; k < 2; ++k) \
;       dst[m][k] = *(const bf16x8*)(SA(b, h) + aoff + (m * 2048 + k * 1024))
; #define LDB(dst, b, h) _Pragma("unroll") for (int n = 0; n < 2; ++n) _Pragma("unroll") for (int k = 0; k < 2; ++k) \
;       dst[n][k] = *(const bf16x8*)(SB(b, h) + boff + (n * 256 + k * 1024))
; #define BAR __builtin_amdgcn_s_barrier()
; template <int EPI, int N, int K>
; __device__ __forceinline__ void phase_gemm(const Params& p, const u16* __restrict__ A, const u16* __restrict__ Bt, int nM, char* shm,
;                            u16* __restrict__ outp, float* __restrict__ rowss) {
;     ...
;     { LDB(B0, 0, 0); LDA(At, 0, 0); STAGE(SA(1, 1), A1, nt - 1);
;       BAR; WAIT_L(0); MMA(0, 0, At, B0); BAR;
;       LDB(B1, 0, 1); BAR; WAIT_L(0); MMA(0, 1, At, B1); BAR;
;       LDA(At, 0, 1); WAIT_V(4); BAR; WAIT_L(0); MMA(1, 0, At, B0); MMA(1, 1, At, B1); BAR; }
;     { LDB(B0, 1, 0); LDA(At, 1, 0); WAIT_V(2); BAR; WAIT_L(0); MMA(0, 0, At, B0); BAR;
;       LDB(B1, 1, 1); WAIT_V(0); BAR; WAIT_L(0); MMA(0, 1, At, B1); BAR;
;       LDA(At, 1, 1); BAR; WAIT_L(0); MMA(1, 0, At, B0); MMA(1, 1, At, B1); BAR; }
	s_cbranch_scc1 .LBB0_553
	s_waitcnt vmcnt(6)
	s_mov_b32 m0, s55
	v_lshl_add_u64 v[140:141], s[14:15], 0, v[136:137]
	ds_read_b128 v[164:167], v147
	ds_read_b128 v[168:171], v148
	ds_read_b128 v[172:175], v149
	ds_read_b128 v[176:179], v150
	ds_read_b128 v[180:183], v144
	ds_read_b128 v[208:211], v144 offset:1024
	ds_read_b128 v[212:215], v144 offset:2048
	ds_read_b128 v[216:219], v144 offset:3072
	ds_read_b128 v[220:223], v144 offset:4096
	ds_read_b128 v[224:227], v144 offset:5120
	ds_read_b128 v[228:231], v144 offset:6144
	ds_read_b128 v[232:235], v144 offset:7168
	global_load_lds_dwordx4 v[140:141], off
	v_lshl_add_u64 v[140:141], s[14:15], 0, v[138:139]
	s_mov_b32 m0, s54
	s_nop 0
	global_load_lds_dwordx4 v[140:141], off
	s_barrier
	s_waitcnt lgkmcnt(0)
	s_waitcnt lgkmcnt(0)
	v_mfma_f32_16x16x32_bf16 v[126:129], v[164:167], v[180:183], v[126:129]
	v_mfma_f32_16x16x32_bf16 v[118:121], v[164:167], v[212:215], v[118:121]
	v_mfma_f32_16x16x32_bf16 v[110:113], v[164:167], v[220:223], v[110:113]
	v_mfma_f32_16x16x32_bf16 v[102:105], v[164:167], v[228:231], v[102:105]
	v_mfma_f32_16x16x32_bf16 v[126:129], v[168:171], v[208:211], v[126:129]
	v_mfma_f32_16x16x32_bf16 v[122:125], v[172:175], v[180:183], v[122:125]
	v_mfma_f32_16x16x32_bf16 v[118:121], v[168:171], v[216:219], v[118:121]
	v_mfma_f32_16x16x32_bf16 v[114:117], v[172:175], v[212:215], v[114:117]
	v_mfma_f32_16x16x32_bf16 v[110:113], v[168:171], v[224:227], v[110:113]
	v_mfma_f32_16x16x32_bf16 v[106:109], v[172:175], v[220:223], v[106:109]
	v_mfma_f32_16x16x32_bf16 v[102:105], v[168:171], v[232:235], v[102:105]
	v_mfma_f32_16x16x32_bf16 v[98:101], v[172:175], v[228:231], v[98:101]
	v_mfma_f32_16x16x32_bf16 v[236:239], v[176:179], v[208:211], v[122:125]
	v_mfma_f32_16x16x32_bf16 v[240:243], v[176:179], v[216:219], v[114:117]
	v_mfma_f32_16x16x32_bf16 v[244:247], v[176:179], v[224:227], v[106:109]
	v_mfma_f32_16x16x32_bf16 v[248:251], v[176:179], v[232:235], v[98:101]
	s_barrier
	s_nop 1
	ds_read_b128 v[98:101], v151
	ds_read_b128 v[106:109], v152
	ds_read_b128 v[114:117], v153
	ds_read_b128 v[122:125], v154
	s_barrier
	s_waitcnt lgkmcnt(0)
	s_waitcnt lgkmcnt(0)
	v_mfma_f32_16x16x32_bf16 v[92:95], v[98:101], v[180:183], v[92:95]
	v_mfma_f32_16x16x32_bf16 v[84:87], v[98:101], v[212:215], v[84:87]
	v_mfma_f32_16x16x32_bf16 v[76:79], v[98:101], v[220:223], v[76:79]
	v_mfma_f32_16x16x32_bf16 v[68:71], v[98:101], v[228:231], v[68:71]
	v_mfma_f32_16x16x32_bf16 v[92:95], v[106:109], v[208:211], v[92:95]
	v_mfma_f32_16x16x32_bf16 v[88:91], v[114:117], v[180:183], v[88:91]
	v_mfma_f32_16x16x32_bf16 v[84:87], v[106:109], v[216:219], v[84:87]
	v_mfma_f32_16x16x32_bf16 v[80:83], v[114:117], v[212:215], v[80:83]
	v_mfma_f32_16x16x32_bf16 v[76:79], v[106:109], v[224:227], v[76:79]
	v_mfma_f32_16x16x32_bf16 v[72:75], v[114:117], v[220:223], v[72:75]
	v_mfma_f32_16x16x32_bf16 v[68:71], v[106:109], v[232:235], v[68:71]
	v_mfma_f32_16x16x32_bf16 v[64:67], v[114:117], v[228:231], v[64:67]
	v_mfma_f32_16x16x32_bf16 v[148:151], v[122:125], v[208:211], v[88:91]
	v_mfma_f32_16x16x32_bf16 v[180:183], v[122:125], v[216:219], v[80:83]
	v_mfma_f32_16x16x32_bf16 v[208:211], v[122:125], v[224:227], v[72:75]
	v_mfma_f32_16x16x32_bf16 v[212:215], v[122:125], v[232:235], v[64:67]
	s_barrier
	s_nop 1
	ds_read_b128 v[64:67], v144 offset:16384
	ds_read_b128 v[72:75], v144 offset:17408
	ds_read_b128 v[80:83], v144 offset:18432
	ds_read_b128 v[88:91], v144 offset:19456
	ds_read_b128 v[216:219], v144 offset:20480
	ds_read_b128 v[220:223], v144 offset:21504
	ds_read_b128 v[224:227], v144 offset:22528
	ds_read_b128 v[228:231], v144 offset:23552
	s_waitcnt vmcnt(4)
	s_barrier
	s_waitcnt lgkmcnt(0)
	s_waitcnt lgkmcnt(0)
	v_mfma_f32_16x16x32_bf16 v[60:63], v[164:167], v[64:67], v[60:63]
	v_mfma_f32_16x16x32_bf16 v[52:55], v[164:167], v[80:83], v[52:55]
	v_mfma_f32_16x16x32_bf16 v[44:47], v[164:167], v[216:219], v[44:47]
	v_mfma_f32_16x16x32_bf16 v[36:39], v[164:167], v[224:227], v[36:39]
	v_mfma_f32_16x16x32_bf16 v[60:63], v[168:171], v[72:75], v[60:63]
	v_mfma_f32_16x16x32_bf16 v[56:59], v[172:175], v[64:67], v[56:59]
	v_mfma_f32_16x16x32_bf16 v[52:55], v[168:171], v[88:91], v[52:55]
	v_mfma_f32_16x16x32_bf16 v[48:51], v[172:175], v[80:83], v[48:51]
	v_mfma_f32_16x16x32_bf16 v[44:47], v[168:171], v[220:223], v[44:47]
	v_mfma_f32_16x16x32_bf16 v[40:43], v[172:175], v[216:219], v[40:43]
	v_mfma_f32_16x16x32_bf16 v[36:39], v[168:171], v[228:231], v[36:39]
	v_mfma_f32_16x16x32_bf16 v[32:35], v[172:175], v[224:227], v[32:35]
	v_mfma_f32_16x16x32_bf16 v[232:235], v[176:179], v[72:75], v[56:59]
	v_mfma_f32_16x16x32_bf16 v[196:199], v[176:179], v[88:91], v[48:51]
	v_mfma_f32_16x16x32_bf16 v[200:203], v[176:179], v[220:223], v[40:43]
	v_mfma_f32_16x16x32_bf16 v[164:167], v[176:179], v[228:231], v[32:35]
	v_mfma_f32_16x16x32_bf16 v[28:31], v[98:101], v[64:67], v[28:31]
	v_mfma_f32_16x16x32_bf16 v[20:23], v[98:101], v[80:83], v[20:23]
	v_mfma_f32_16x16x32_bf16 v[12:15], v[98:101], v[216:219], v[12:15]
	v_mfma_f32_16x16x32_bf16 v[4:7], v[98:101], v[224:227], v[4:7]
	v_mfma_f32_16x16x32_bf16 v[28:31], v[106:109], v[72:75], v[28:31]
	v_mfma_f32_16x16x32_bf16 v[24:27], v[114:117], v[64:67], v[24:27]
	v_mfma_f32_16x16x32_bf16 v[20:23], v[106:109], v[88:91], v[20:23]
	v_mfma_f32_16x16x32_bf16 v[16:19], v[114:117], v[80:83], v[16:19]
	v_mfma_f32_16x16x32_bf16 v[12:15], v[106:109], v[220:223], v[12:15]
	v_mfma_f32_16x16x32_bf16 v[8:11], v[114:117], v[216:219], v[8:11]
	v_mfma_f32_16x16x32_bf16 v[4:7], v[106:109], v[228:231], v[4:7]
	v_mfma_f32_16x16x32_bf16 v[0:3], v[114:117], v[224:227], v[0:3]
	v_mfma_f32_16x16x32_bf16 v[168:171], v[122:125], v[72:75], v[24:27]
	v_mfma_f32_16x16x32_bf16 v[172:175], v[122:125], v[88:91], v[16:19]
	v_mfma_f32_16x16x32_bf16 v[176:179], v[122:125], v[220:223], v[8:11]
	v_mfma_f32_16x16x32_bf16 v[216:219], v[122:125], v[228:231], v[0:3]
	s_barrier
; #define WAIT_V(n) asm volatile("s_waitcnt vmcnt(%0)" ::"n"(n) : "memory")
; #define WAIT_L(n) asm volatile("s_waitcnt lgkmcnt(%0)" ::"n"(n) : "memory")
; #define LDA(dst, b, h) _Pragma("unroll") for (int m = 0; m < 4; ++m) _Pragma("unroll") for (int k = 0; k < 2; ++k) \
;       dst[m][k] = *(const bf16x8*)(SA(b, h) + aoff + (m * 2048 + k * 1024))
; #define LDB(dst, b, h) _Pragma("unroll") for (int n = 0; n < 2; ++n) _Pragma("unroll") for (int k = 0; k < 2; ++k) \
;       dst[n][k] = *(const bf16x8*)(SB(b, h) + boff + (n * 256 + k * 1024))
; #define BAR __builtin_amdgcn_s_barrier()
; template <int EPI, int N, int K>
; __device__ __forceinline__ void phase_gemm(const Params& p, const u16* __restrict__ A, const u16* __restrict__ Bt, int nM, char* shm,
;                            u16* __restrict__ outp, float* __restrict__ rowss) {
;     ...
;     { LDB(B0, 1, 0); LDA(At, 1, 0); WAIT_V(2); BAR; WAIT_L(0); MMA(0, 0, At, B0); BAR;
;       LDB(B1, 1, 1); WAIT_V(0); BAR; WAIT_L(0); MMA(0, 1, At, B1); BAR;
;       LDA(At, 1, 1); BAR; WAIT_L(0); MMA(1, 0, At, B0); MMA(1, 1, At, B1); BAR; }
;     if (wr == 0) BAR;
	s_nop 1
	ds_read_b128 v[0:3], v155
	ds_read_b128 v[8:11], v156
	ds_read_b128 v[152:155], v157
	ds_read_b128 v[220:223], v158
	ds_read_b128 v[16:19], v144 offset:32768
	ds_read_b128 v[24:27], v144 offset:33792
	ds_read_b128 v[32:35], v144 offset:34816
	ds_read_b128 v[40:43], v144 offset:35840
	ds_read_b128 v[48:51], v144 offset:36864
	ds_read_b128 v[56:59], v144 offset:37888
	ds_read_b128 v[224:227], v144 offset:38912
	ds_read_b128 v[228:231], v144 offset:39936
	s_waitcnt vmcnt(2)
	s_barrier
	s_waitcnt lgkmcnt(0)
	s_waitcnt lgkmcnt(0)
	v_mfma_f32_16x16x32_bf16 v[64:67], v[0:3], v[16:19], v[126:129]
	v_mfma_f32_16x16x32_bf16 v[122:125], v[8:11], v[24:27], v[64:67]
	v_mfma_f32_16x16x32_bf16 v[64:67], v[152:155], v[16:19], v[236:239]
	v_mfma_f32_16x16x32_bf16 v[114:117], v[220:223], v[24:27], v[64:67]
	v_mfma_f32_16x16x32_bf16 v[64:67], v[0:3], v[32:35], v[118:121]
	v_mfma_f32_16x16x32_bf16 v[106:109], v[8:11], v[40:43], v[64:67]
	v_mfma_f32_16x16x32_bf16 v[64:67], v[152:155], v[32:35], v[240:243]
	v_mfma_f32_16x16x32_bf16 v[98:101], v[220:223], v[40:43], v[64:67]
	v_mfma_f32_16x16x32_bf16 v[64:67], v[0:3], v[48:51], v[110:113]
	v_mfma_f32_16x16x32_bf16 v[88:91], v[8:11], v[56:59], v[64:67]
	v_mfma_f32_16x16x32_bf16 v[64:67], v[152:155], v[48:51], v[244:247]
	v_mfma_f32_16x16x32_bf16 v[80:83], v[220:223], v[56:59], v[64:67]
	v_mfma_f32_16x16x32_bf16 v[64:67], v[0:3], v[224:227], v[102:105]
	v_mfma_f32_16x16x32_bf16 v[72:75], v[8:11], v[228:231], v[64:67]
	v_mfma_f32_16x16x32_bf16 v[64:67], v[152:155], v[224:227], v[248:251]
	v_mfma_f32_16x16x32_bf16 v[64:67], v[220:223], v[228:231], v[64:67]
	s_barrier
	ds_read_b128 v[156:159], v159
	ds_read_b128 v[236:239], v160
	ds_read_b128 v[240:243], v161
	ds_read_b128 v[160:163], v162
	s_waitcnt vmcnt(0)
	s_barrier
	s_waitcnt lgkmcnt(0)
	s_waitcnt lgkmcnt(0)
	v_mfma_f32_16x16x32_bf16 v[92:95], v[156:159], v[16:19], v[92:95]
	v_mfma_f32_16x16x32_bf16 v[16:19], v[240:243], v[16:19], v[148:151]
	v_mfma_f32_16x16x32_bf16 v[118:121], v[160:163], v[24:27], v[16:19]
	v_mfma_f32_16x16x32_bf16 v[16:19], v[156:159], v[32:35], v[84:87]
	v_mfma_f32_16x16x32_bf16 v[110:113], v[236:239], v[40:43], v[16:19]
	v_mfma_f32_16x16x32_bf16 v[16:19], v[240:243], v[32:35], v[180:183]
	v_mfma_f32_16x16x32_bf16 v[102:105], v[160:163], v[40:43], v[16:19]
	v_mfma_f32_16x16x32_bf16 v[16:19], v[156:159], v[48:51], v[76:79]
	v_mfma_f32_16x16x32_bf16 v[126:129], v[236:239], v[24:27], v[92:95]
	v_mfma_f32_16x16x32_bf16 v[92:95], v[236:239], v[56:59], v[16:19]
	v_mfma_f32_16x16x32_bf16 v[16:19], v[240:243], v[48:51], v[208:211]
	v_mfma_f32_16x16x32_bf16 v[84:87], v[160:163], v[56:59], v[16:19]
	v_mfma_f32_16x16x32_bf16 v[16:19], v[156:159], v[224:227], v[68:71]
	v_mfma_f32_16x16x32_bf16 v[76:79], v[236:239], v[228:231], v[16:19]
	v_mfma_f32_16x16x32_bf16 v[16:19], v[240:243], v[224:227], v[212:215]
	v_mfma_f32_16x16x32_bf16 v[68:71], v[160:163], v[228:231], v[16:19]
	s_barrier
	ds_read_b128 v[148:151], v144 offset:49152
	ds_read_b128 v[180:183], v144 offset:50176
	ds_read_b128 v[208:211], v144 offset:51200
	ds_read_b128 v[212:215], v144 offset:52224
	ds_read_b128 v[224:227], v144 offset:53248
	ds_read_b128 v[228:231], v144 offset:54272
	ds_read_b128 v[244:247], v144 offset:55296
	ds_read_b128 v[248:251], v144 offset:56320
	s_barrier
	s_waitcnt lgkmcnt(0)
	s_waitcnt lgkmcnt(0)
	v_mfma_f32_16x16x32_bf16 v[16:19], v[0:3], v[148:151], v[60:63]
	v_mfma_f32_16x16x32_bf16 v[56:59], v[8:11], v[180:183], v[16:19]
	v_mfma_f32_16x16x32_bf16 v[16:19], v[152:155], v[148:151], v[232:235]
	v_mfma_f32_16x16x32_bf16 v[48:51], v[220:223], v[180:183], v[16:19]
	v_mfma_f32_16x16x32_bf16 v[16:19], v[0:3], v[208:211], v[52:55]
	v_mfma_f32_16x16x32_bf16 v[40:43], v[8:11], v[212:215], v[16:19]
	v_mfma_f32_16x16x32_bf16 v[16:19], v[152:155], v[208:211], v[196:199]
	v_mfma_f32_16x16x32_bf16 v[32:35], v[220:223], v[212:215], v[16:19]
	v_mfma_f32_16x16x32_bf16 v[16:19], v[0:3], v[224:227], v[44:47]
	v_mfma_f32_16x16x32_bf16 v[0:3], v[0:3], v[244:247], v[36:39]
	v_mfma_f32_16x16x32_bf16 v[24:27], v[8:11], v[228:231], v[16:19]
	v_mfma_f32_16x16x32_bf16 v[16:19], v[152:155], v[224:227], v[200:203]
	v_mfma_f32_16x16x32_bf16 v[8:11], v[8:11], v[248:251], v[0:3]
	v_mfma_f32_16x16x32_bf16 v[0:3], v[152:155], v[244:247], v[164:167]
	v_mfma_f32_16x16x32_bf16 v[16:19], v[220:223], v[228:231], v[16:19]
	v_mfma_f32_16x16x32_bf16 v[0:3], v[220:223], v[248:251], v[0:3]
	v_mfma_f32_16x16x32_bf16 v[28:31], v[156:159], v[148:151], v[28:31]
	v_mfma_f32_16x16x32_bf16 v[60:63], v[236:239], v[180:183], v[28:31]
	v_mfma_f32_16x16x32_bf16 v[28:31], v[240:243], v[148:151], v[168:171]
	v_mfma_f32_16x16x32_bf16 v[20:23], v[156:159], v[208:211], v[20:23]
	v_mfma_f32_16x16x32_bf16 v[12:15], v[156:159], v[224:227], v[12:15]
	v_mfma_f32_16x16x32_bf16 v[52:55], v[160:163], v[180:183], v[28:31]
	v_mfma_f32_16x16x32_bf16 v[44:47], v[236:239], v[212:215], v[20:23]
	v_mfma_f32_16x16x32_bf16 v[20:23], v[240:243], v[208:211], v[172:175]
	v_mfma_f32_16x16x32_bf16 v[28:31], v[236:239], v[228:231], v[12:15]
	v_mfma_f32_16x16x32_bf16 v[12:15], v[240:243], v[224:227], v[176:179]
	v_mfma_f32_16x16x32_bf16 v[4:7], v[156:159], v[244:247], v[4:7]
	v_mfma_f32_16x16x32_bf16 v[36:39], v[160:163], v[212:215], v[20:23]
	v_mfma_f32_16x16x32_bf16 v[20:23], v[160:163], v[228:231], v[12:15]
	v_mfma_f32_16x16x32_bf16 v[12:15], v[236:239], v[248:251], v[4:7]
	v_mfma_f32_16x16x32_bf16 v[4:7], v[240:243], v[244:247], v[216:219]
	v_mfma_f32_16x16x32_bf16 v[4:7], v[160:163], v[248:251], v[4:7]
	s_andn2_b64 vcc, exec, s[12:13]
	s_barrier
	s_cbranch_vccnz .LBB0_556
	s_barrier
